# trailing barrier of every GEMM MFMA segment one MFMA early, tail MFMA at s_setprio 3 (cannot be starved by the other half)
# speedup vs baseline: 1.0166x; 1.0024x over previous
; #define PG8_STAGE(bufoff, gbase, voff) do { _Pragma("unroll") for (int _i = 0; _i < 2; ++_i) \
;         __builtin_amdgcn_global_load_lds((const unsigned*)((const char*)(gbase) + (voff)[_i]), (PG8_LAS unsigned*)(lds + (bufoff) + ldsw + _i * 8192), 16, 0, 0); } while (0)
; #define PG8_LDA(dst, b, h) do { _Pragma("unroll") for (int m = 0; m < 4; ++m) _Pragma("unroll") for (int k = 0; k < 2; ++k) dst[m][k] = *(const PG8_LAS bf16x8*)(lds + PG8_SA(b, h) + aoff + m * 2048 + k * 1024); } while (0)
; #define PG8_LDB(dst, b, h) do { _Pragma("unroll") for (int n = 0; n < 2; ++n) _Pragma("unroll") for (int k = 0; k < 2; ++k) dst[n][k] = *(const PG8_LAS bf16x8*)(lds + PG8_SB(b, h) + boff + n * 2048 + k * 1024); } while (0)
; #define PG8_MMA(ai, bj, At, Bt) do { __builtin_amdgcn_s_setprio(1); _Pragma("unroll") for (int m = 0; m < 4; ++m) _Pragma("unroll") for (int n = 0; n < 2; ++n) _Pragma("unroll") for (int k = 0; k < 2; ++k) \
;         acc[ai][bj][m][n] = __builtin_amdgcn_mfma_f32_16x16x32_bf16(Bt[n][k], At[m][k], acc[ai][bj][m][n], 0, 0, 0); __builtin_amdgcn_s_setprio(0); } while (0)
; #define PG8_WAIT_V(n) asm volatile("s_waitcnt vmcnt(" #n ")" ::: "memory")
; template <class Epi, class Sched, bool ALIGN_EPI = false, bool SP2 = false>
; __device__ __forceinline__ void gemm_phase(PG8_LAS unsigned char* lds, const Gemm g, const Sched& S, const Epi& E) {
;     ...
;             PG8_LDB(B0, 0, 0); PG8_LDB(B1, 0, 1); PG8_SCHED; PG8_LDA(At, 0, 0); PG8_STAGE(PG8_SA(1, 1), a1 + hstep, voffA);
;             PG8_WAIT_V(8); PG8_WAIT_L(0); PG8_BAR; PG8_MMA(0, 0, At, B0); PG8_MMA(0, 1, At, B1); PG8_BAR; PG8_SCHED;
;             PG8_LDA(At, 0, 1); PG8_STAGE(PG8_SB(0, 0), b2, voffB); PG8_STAGE(PG8_SB(0, 1), b2 + hstep, voffB); PG8_STAGE(PG8_SA(0, 0), a2, voffA);
;             PG8_WAIT_V(8); PG8_WAIT_L(0); PG8_BAR; PG8_MMA(1, 0, At, B0); PG8_MMA(1, 1, At, B1); PG8_BAR; PG8_SCHED;
;             PG8_LDB(B0, 1, 0); PG8_LDB(B1, 1, 1); PG8_SCHED; PG8_LDA(At, 1, 0); PG8_STAGE(PG8_SA(0, 1), a2 + hstep, voffA);
;             PG8_WAIT_V(8); PG8_WAIT_L(0); PG8_BAR; PG8_MMA(0, 0, At, B0); PG8_MMA(0, 1, At, B1); PG8_BAR; PG8_SCHED;
;             PG8_LDA(At, 1, 1); PG8_STAGE(PG8_SB(1, 0), b3, voffB); PG8_STAGE(PG8_SB(1, 1), b3 + hstep, voffB); PG8_STAGE(PG8_SA(1, 0), a3, voffA);
;             PG8_WAIT_V(8); PG8_WAIT_L(0); PG8_BAR; PG8_MMA(1, 0, At, B0); PG8_MMA(1, 1, At, B1); PG8_BAR; PG8_SCHED;
.LBB0_141:
	ds_read_b128 v[130:133], v196
	ds_read_b128 v[134:137], v196 offset:1024
	ds_read_b128 v[138:141], v196 offset:2048
	ds_read_b128 v[142:145], v196 offset:3072
	s_waitcnt lgkmcnt(0)
	ds_read_b128 v[170:173], v197
	ds_read_b128 v[174:177], v197 offset:1024
	ds_read_b128 v[178:181], v197 offset:2048
	ds_read_b128 v[182:185], v197 offset:3072
	s_add_u32 s18, s84, 0xfffc0080
	s_addc_u32 s19, s85, -1
	s_cmp_eq_u32 vcc_lo, 12
	s_cselect_b32 s87, s7, s19
	s_cselect_b32 s86, s9, s18
	s_cselect_b32 s31, s10, s75
	s_cselect_b32 s30, s69, s73
	v_lshl_add_u64 v[190:191], s[84:85], 0, v[162:163]
	s_add_i32 m0, s91, 0xc000
	ds_read_b128 v[186:189], v198
	ds_read_b128 v[202:205], v198 offset:1024
	ds_read_b128 v[208:211], v198 offset:2048
	ds_read_b128 v[212:215], v198 offset:3072
	ds_read_b128 v[216:219], v198 offset:4096
	ds_read_b128 v[220:223], v198 offset:5120
	ds_read_b128 v[224:227], v198 offset:6144
	ds_read_b128 v[228:231], v198 offset:7168
	global_load_lds_dwordx4 v[190:191], off
	v_lshl_add_u64 v[190:191], s[84:85], 0, v[164:165]
	s_add_i32 m0, s91, 0xe000
	s_nop 0
	global_load_lds_dwordx4 v[190:191], off
	s_waitcnt vmcnt(8)
	s_waitcnt lgkmcnt(0)
	s_barrier
	s_setprio 1
	s_waitcnt lgkmcnt(0)
	v_mfma_f32_16x16x32_bf16 v[126:129], v[130:133], v[186:189], v[126:129]
	v_mfma_f32_16x16x32_bf16 v[122:125], v[138:141], v[186:189], v[122:125]
	v_mfma_f32_16x16x32_bf16 v[110:113], v[130:133], v[208:211], v[110:113]
	v_mfma_f32_16x16x32_bf16 v[106:109], v[138:141], v[208:211], v[106:109]
	v_mfma_f32_16x16x32_bf16 v[94:97], v[130:133], v[216:219], v[94:97]
	v_mfma_f32_16x16x32_bf16 v[90:93], v[138:141], v[216:219], v[90:93]
	v_mfma_f32_16x16x32_bf16 v[78:81], v[130:133], v[224:227], v[78:81]
	v_mfma_f32_16x16x32_bf16 v[74:77], v[138:141], v[224:227], v[74:77]
	v_mfma_f32_16x16x32_bf16 v[126:129], v[134:137], v[202:205], v[126:129]
	v_mfma_f32_16x16x32_bf16 v[122:125], v[142:145], v[202:205], v[122:125]
	v_mfma_f32_16x16x32_bf16 v[110:113], v[134:137], v[212:215], v[110:113]
	v_mfma_f32_16x16x32_bf16 v[106:109], v[142:145], v[212:215], v[106:109]
	v_mfma_f32_16x16x32_bf16 v[94:97], v[134:137], v[220:223], v[94:97]
	v_mfma_f32_16x16x32_bf16 v[90:93], v[142:145], v[220:223], v[90:93]
	v_mfma_f32_16x16x32_bf16 v[78:81], v[134:137], v[228:231], v[78:81]
	v_mfma_f32_16x16x32_bf16 v[74:77], v[142:145], v[228:231], v[74:77]
	s_setprio 0
	s_setprio 1
	v_mfma_f32_16x16x32_bf16 v[118:121], v[170:173], v[186:189], v[118:121]
	v_mfma_f32_16x16x32_bf16 v[114:117], v[178:181], v[186:189], v[114:117]
	v_mfma_f32_16x16x32_bf16 v[102:105], v[170:173], v[208:211], v[102:105]
	v_mfma_f32_16x16x32_bf16 v[98:101], v[178:181], v[208:211], v[98:101]
	v_mfma_f32_16x16x32_bf16 v[86:89], v[170:173], v[216:219], v[86:89]
	v_mfma_f32_16x16x32_bf16 v[82:85], v[178:181], v[216:219], v[82:85]
	v_mfma_f32_16x16x32_bf16 v[70:73], v[170:173], v[224:227], v[70:73]
	v_mfma_f32_16x16x32_bf16 v[66:69], v[178:181], v[224:227], v[66:69]
	v_mfma_f32_16x16x32_bf16 v[118:121], v[174:177], v[202:205], v[118:121]
	v_mfma_f32_16x16x32_bf16 v[114:117], v[182:185], v[202:205], v[114:117]
	v_mfma_f32_16x16x32_bf16 v[102:105], v[174:177], v[212:215], v[102:105]
	v_mfma_f32_16x16x32_bf16 v[98:101], v[182:185], v[212:215], v[98:101]
	v_mfma_f32_16x16x32_bf16 v[86:89], v[174:177], v[220:223], v[86:89]
	v_mfma_f32_16x16x32_bf16 v[82:85], v[182:185], v[220:223], v[82:85]
	v_mfma_f32_16x16x32_bf16 v[70:73], v[174:177], v[228:231], v[70:73]
	s_setprio 3
	s_barrier
	v_mfma_f32_16x16x32_bf16 v[66:69], v[182:185], v[228:231], v[66:69]
	s_setprio 0
	s_add_i32 s18, s58, s88
	v_lshl_add_u64 v[190:191], s[30:31], 0, v[148:149]
	s_mov_b32 m0, s18
	ds_read_b128 v[186:189], v198 offset:16384
	ds_read_b128 v[202:205], v198 offset:17408
	ds_read_b128 v[208:211], v198 offset:18432
	ds_read_b128 v[212:215], v198 offset:19456
	ds_read_b128 v[216:219], v198 offset:20480
	ds_read_b128 v[220:223], v198 offset:21504
	ds_read_b128 v[224:227], v198 offset:22528
	ds_read_b128 v[228:231], v198 offset:23552
	global_load_lds_dwordx4 v[190:191], off
	s_add_i32 m0, s18, 0x2000
	s_add_u32 s18, s30, 0x40000
	v_lshl_add_u64 v[232:233], s[30:31], 0, v[152:153]
	s_addc_u32 s19, s31, 0
	s_add_i32 vcc_hi, s59, s88
	global_load_lds_dwordx4 v[232:233], off
	v_lshl_add_u64 v[234:235], s[18:19], 0, v[148:149]
	s_mov_b32 m0, vcc_hi
	v_lshl_add_u64 v[238:239], s[86:87], 0, v[150:151]
	global_load_lds_dwordx4 v[234:235], off
	v_lshl_add_u64 v[234:235], s[18:19], 0, v[152:153]
	s_add_i32 m0, vcc_hi, 0x2000
	s_nop 0
	global_load_lds_dwordx4 v[234:235], off
	v_lshl_add_u64 v[234:235], s[86:87], 0, v[146:147]
	s_mov_b32 m0, s91
	s_nop 0
	global_load_lds_dwordx4 v[234:235], off
	s_mov_b32 m0, s92
	s_nop 0
	global_load_lds_dwordx4 v[238:239], off
	s_waitcnt vmcnt(8)
	s_waitcnt lgkmcnt(0)
	s_barrier
; #define PG8_STAGE(bufoff, gbase, voff) do { _Pragma("unroll") for (int _i = 0; _i < 2; ++_i) \
;         __builtin_amdgcn_global_load_lds((const unsigned*)((const char*)(gbase) + (voff)[_i]), (PG8_LAS unsigned*)(lds + (bufoff) + ldsw + _i * 8192), 16, 0, 0); } while (0)
; #define PG8_LDA(dst, b, h) do { _Pragma("unroll") for (int m = 0; m < 4; ++m) _Pragma("unroll") for (int k = 0; k < 2; ++k) dst[m][k] = *(const PG8_LAS bf16x8*)(lds + PG8_SA(b, h) + aoff + m * 2048 + k * 1024); } while (0)
; #define PG8_LDB(dst, b, h) do { _Pragma("unroll") for (int n = 0; n < 2; ++n) _Pragma("unroll") for (int k = 0; k < 2; ++k) dst[n][k] = *(const PG8_LAS bf16x8*)(lds + PG8_SB(b, h) + boff + n * 2048 + k * 1024); } while (0)
; #define PG8_MMA(ai, bj, At, Bt) do { __builtin_amdgcn_s_setprio(1); _Pragma("unroll") for (int m = 0; m < 4; ++m) _Pragma("unroll") for (int n = 0; n < 2; ++n) _Pragma("unroll") for (int k = 0; k < 2; ++k) \
;         acc[ai][bj][m][n] = __builtin_amdgcn_mfma_f32_16x16x32_bf16(Bt[n][k], At[m][k], acc[ai][bj][m][n], 0, 0, 0); __builtin_amdgcn_s_setprio(0); } while (0)
; #define PG8_WAIT_V(n) asm volatile("s_waitcnt vmcnt(" #n ")" ::: "memory")
; template <class Epi, class Sched, bool ALIGN_EPI = false, bool SP2 = false>
; __device__ __forceinline__ void gemm_phase(PG8_LAS unsigned char* lds, const Gemm g, const Sched& S, const Epi& E) {
;     ...
;             PG8_LDB(B0, 0, 0); PG8_LDB(B1, 0, 1); PG8_SCHED; PG8_LDA(At, 0, 0); PG8_STAGE(PG8_SA(1, 1), a1 + hstep, voffA);
;             PG8_WAIT_V(8); PG8_WAIT_L(0); PG8_BAR; PG8_MMA(0, 0, At, B0); PG8_MMA(0, 1, At, B1); PG8_BAR; PG8_SCHED;
;             PG8_LDA(At, 0, 1); PG8_STAGE(PG8_SB(0, 0), b2, voffB); PG8_STAGE(PG8_SB(0, 1), b2 + hstep, voffB); PG8_STAGE(PG8_SA(0, 0), a2, voffA);
;             PG8_WAIT_V(8); PG8_WAIT_L(0); PG8_BAR; PG8_MMA(1, 0, At, B0); PG8_MMA(1, 1, At, B1); PG8_BAR; PG8_SCHED;
;             PG8_LDB(B0, 1, 0); PG8_LDB(B1, 1, 1); PG8_SCHED; PG8_LDA(At, 1, 0); PG8_STAGE(PG8_SA(0, 1), a2 + hstep, voffA);
;             PG8_WAIT_V(8); PG8_WAIT_L(0); PG8_BAR; PG8_MMA(0, 0, At, B0); PG8_MMA(0, 1, At, B1); PG8_BAR; PG8_SCHED;
;             PG8_LDA(At, 1, 1); PG8_STAGE(PG8_SB(1, 0), b3, voffB); PG8_STAGE(PG8_SB(1, 1), b3 + hstep, voffB); PG8_STAGE(PG8_SA(1, 0), a3, voffA);
;             PG8_WAIT_V(8); PG8_WAIT_L(0); PG8_BAR; PG8_MMA(1, 0, At, B0); PG8_MMA(1, 1, At, B1); PG8_BAR; PG8_SCHED;
	s_setprio 1
	s_waitcnt lgkmcnt(0)
	v_mfma_f32_16x16x32_bf16 v[62:65], v[130:133], v[186:189], v[62:65]
	v_mfma_f32_16x16x32_bf16 v[58:61], v[138:141], v[186:189], v[58:61]
	v_mfma_f32_16x16x32_bf16 v[46:49], v[130:133], v[208:211], v[46:49]
	v_mfma_f32_16x16x32_bf16 v[42:45], v[138:141], v[208:211], v[42:45]
	v_mfma_f32_16x16x32_bf16 v[30:33], v[130:133], v[216:219], v[30:33]
	v_mfma_f32_16x16x32_bf16 v[26:29], v[138:141], v[216:219], v[26:29]
	v_mfma_f32_16x16x32_bf16 v[14:17], v[130:133], v[224:227], v[14:17]
	v_mfma_f32_16x16x32_bf16 v[10:13], v[138:141], v[224:227], v[10:13]
	v_mfma_f32_16x16x32_bf16 v[62:65], v[134:137], v[202:205], v[62:65]
	v_mfma_f32_16x16x32_bf16 v[58:61], v[142:145], v[202:205], v[58:61]
	v_mfma_f32_16x16x32_bf16 v[46:49], v[134:137], v[212:215], v[46:49]
	v_mfma_f32_16x16x32_bf16 v[42:45], v[142:145], v[212:215], v[42:45]
	v_mfma_f32_16x16x32_bf16 v[30:33], v[134:137], v[220:223], v[30:33]
	v_mfma_f32_16x16x32_bf16 v[26:29], v[142:145], v[220:223], v[26:29]
	v_mfma_f32_16x16x32_bf16 v[14:17], v[134:137], v[228:231], v[14:17]
	v_mfma_f32_16x16x32_bf16 v[10:13], v[142:145], v[228:231], v[10:13]
	s_setprio 0
	s_setprio 1
	v_mfma_f32_16x16x32_bf16 v[54:57], v[170:173], v[186:189], v[54:57]
	v_mfma_f32_16x16x32_bf16 v[50:53], v[178:181], v[186:189], v[50:53]
	v_mfma_f32_16x16x32_bf16 v[38:41], v[170:173], v[208:211], v[38:41]
	v_mfma_f32_16x16x32_bf16 v[34:37], v[178:181], v[208:211], v[34:37]
	v_mfma_f32_16x16x32_bf16 v[22:25], v[170:173], v[216:219], v[22:25]
	v_mfma_f32_16x16x32_bf16 v[18:21], v[178:181], v[216:219], v[18:21]
	v_mfma_f32_16x16x32_bf16 v[6:9], v[170:173], v[224:227], v[6:9]
	v_mfma_f32_16x16x32_bf16 v[2:5], v[178:181], v[224:227], v[2:5]
	v_mfma_f32_16x16x32_bf16 v[54:57], v[174:177], v[202:205], v[54:57]
	v_mfma_f32_16x16x32_bf16 v[50:53], v[182:185], v[202:205], v[50:53]
	v_mfma_f32_16x16x32_bf16 v[38:41], v[174:177], v[212:215], v[38:41]
	v_mfma_f32_16x16x32_bf16 v[34:37], v[182:185], v[212:215], v[34:37]
	v_mfma_f32_16x16x32_bf16 v[22:25], v[174:177], v[220:223], v[22:25]
	v_mfma_f32_16x16x32_bf16 v[18:21], v[182:185], v[220:223], v[18:21]
	v_mfma_f32_16x16x32_bf16 v[6:9], v[174:177], v[228:231], v[6:9]
	s_setprio 3
	s_barrier
	v_mfma_f32_16x16x32_bf16 v[2:5], v[182:185], v[228:231], v[2:5]
	s_setprio 0
	s_add_i32 vcc_hi, 0, 0x18000
	s_add_i32 s52, 0, 0x1c000
	v_add_u32_e32 v142, vcc_hi, v157
	v_add_u32_e32 v154, s52, v157
	ds_read_b128 v[130:133], v142
	ds_read_b128 v[134:137], v142 offset:1024
	ds_read_b128 v[138:141], v142 offset:2048
	ds_read_b128 v[142:145], v142 offset:3072
	ds_read_b128 v[170:173], v154
	ds_read_b128 v[174:177], v154 offset:1024
	ds_read_b128 v[178:181], v154 offset:2048
	ds_read_b128 v[182:185], v154 offset:3072
	s_add_u32 s18, s86, 0x40000
	s_addc_u32 s19, s87, 0
	s_mov_b32 m0, s93
	v_lshl_add_u64 v[240:241], s[18:19], 0, v[146:147]
	ds_read_b128 v[186:189], v198 offset:32768
	ds_read_b128 v[202:205], v198 offset:33792
	ds_read_b128 v[208:211], v198 offset:34816
	ds_read_b128 v[212:215], v198 offset:35840
	ds_read_b128 v[216:219], v198 offset:36864
	ds_read_b128 v[220:223], v198 offset:37888
	ds_read_b128 v[224:227], v198 offset:38912
	ds_read_b128 v[228:231], v198 offset:39936
	global_load_lds_dwordx4 v[240:241], off
	v_lshl_add_u64 v[240:241], s[18:19], 0, v[150:151]
	s_mov_b32 m0, s95
	s_nop 0
	global_load_lds_dwordx4 v[240:241], off
	s_waitcnt vmcnt(8)
	s_waitcnt lgkmcnt(0)
	s_barrier
	s_setprio 1
	s_waitcnt lgkmcnt(0)
	v_mfma_f32_16x16x32_bf16 v[126:129], v[130:133], v[186:189], v[126:129]
	v_mfma_f32_16x16x32_bf16 v[122:125], v[138:141], v[186:189], v[122:125]
	v_mfma_f32_16x16x32_bf16 v[110:113], v[130:133], v[208:211], v[110:113]
	v_mfma_f32_16x16x32_bf16 v[106:109], v[138:141], v[208:211], v[106:109]
	v_mfma_f32_16x16x32_bf16 v[94:97], v[130:133], v[216:219], v[94:97]
	v_mfma_f32_16x16x32_bf16 v[90:93], v[138:141], v[216:219], v[90:93]
	v_mfma_f32_16x16x32_bf16 v[78:81], v[130:133], v[224:227], v[78:81]
	v_mfma_f32_16x16x32_bf16 v[74:77], v[138:141], v[224:227], v[74:77]
	v_mfma_f32_16x16x32_bf16 v[126:129], v[134:137], v[202:205], v[126:129]
	v_mfma_f32_16x16x32_bf16 v[122:125], v[142:145], v[202:205], v[122:125]
	v_mfma_f32_16x16x32_bf16 v[110:113], v[134:137], v[212:215], v[110:113]
	v_mfma_f32_16x16x32_bf16 v[106:109], v[142:145], v[212:215], v[106:109]
	v_mfma_f32_16x16x32_bf16 v[94:97], v[134:137], v[220:223], v[94:97]
	v_mfma_f32_16x16x32_bf16 v[90:93], v[142:145], v[220:223], v[90:93]
	v_mfma_f32_16x16x32_bf16 v[78:81], v[134:137], v[228:231], v[78:81]
	v_mfma_f32_16x16x32_bf16 v[74:77], v[142:145], v[228:231], v[74:77]
	s_setprio 0
	s_setprio 1
	v_mfma_f32_16x16x32_bf16 v[118:121], v[170:173], v[186:189], v[118:121]
	v_mfma_f32_16x16x32_bf16 v[114:117], v[178:181], v[186:189], v[114:117]
	v_mfma_f32_16x16x32_bf16 v[102:105], v[170:173], v[208:211], v[102:105]
	v_mfma_f32_16x16x32_bf16 v[98:101], v[178:181], v[208:211], v[98:101]
	v_mfma_f32_16x16x32_bf16 v[86:89], v[170:173], v[216:219], v[86:89]
	v_mfma_f32_16x16x32_bf16 v[82:85], v[178:181], v[216:219], v[82:85]
	v_mfma_f32_16x16x32_bf16 v[70:73], v[170:173], v[224:227], v[70:73]
	v_mfma_f32_16x16x32_bf16 v[66:69], v[178:181], v[224:227], v[66:69]
	v_mfma_f32_16x16x32_bf16 v[118:121], v[174:177], v[202:205], v[118:121]
	v_mfma_f32_16x16x32_bf16 v[114:117], v[182:185], v[202:205], v[114:117]
	v_mfma_f32_16x16x32_bf16 v[102:105], v[174:177], v[212:215], v[102:105]
	v_mfma_f32_16x16x32_bf16 v[98:101], v[182:185], v[212:215], v[98:101]
	v_mfma_f32_16x16x32_bf16 v[86:89], v[174:177], v[220:223], v[86:89]
	v_mfma_f32_16x16x32_bf16 v[82:85], v[182:185], v[220:223], v[82:85]
	v_mfma_f32_16x16x32_bf16 v[70:73], v[174:177], v[228:231], v[70:73]
	s_setprio 3
	s_barrier
; #define PG8_STAGE(bufoff, gbase, voff) do { _Pragma("unroll") for (int _i = 0; _i < 2; ++_i) \
;         __builtin_amdgcn_global_load_lds((const unsigned*)((const char*)(gbase) + (voff)[_i]), (PG8_LAS unsigned*)(lds + (bufoff) + ldsw + _i * 8192), 16, 0, 0); } while (0)
; #define PG8_LDA(dst, b, h) do { _Pragma("unroll") for (int m = 0; m < 4; ++m) _Pragma("unroll") for (int k = 0; k < 2; ++k) dst[m][k] = *(const PG8_LAS bf16x8*)(lds + PG8_SA(b, h) + aoff + m * 2048 + k * 1024); } while (0)
; #define PG8_LDB(dst, b, h) do { _Pragma("unroll") for (int n = 0; n < 2; ++n) _Pragma("unroll") for (int k = 0; k < 2; ++k) dst[n][k] = *(const PG8_LAS bf16x8*)(lds + PG8_SB(b, h) + boff + n * 2048 + k * 1024); } while (0)
; #define PG8_MMA(ai, bj, At, Bt) do { __builtin_amdgcn_s_setprio(1); _Pragma("unroll") for (int m = 0; m < 4; ++m) _Pragma("unroll") for (int n = 0; n < 2; ++n) _Pragma("unroll") for (int k = 0; k < 2; ++k) \
;         acc[ai][bj][m][n] = __builtin_amdgcn_mfma_f32_16x16x32_bf16(Bt[n][k], At[m][k], acc[ai][bj][m][n], 0, 0, 0); __builtin_amdgcn_s_setprio(0); } while (0)
; template <class Epi, class Sched, bool ALIGN_EPI = false, bool SP2 = false>
; __device__ __forceinline__ void gemm_phase(PG8_LAS unsigned char* lds, const Gemm g, const Sched& S, const Epi& E) {
;     ...
;             PG8_LDB(B0, 0, 0); PG8_LDB(B1, 0, 1); PG8_SCHED; PG8_LDA(At, 0, 0); PG8_STAGE(PG8_SA(1, 1), a1 + hstep, voffA);
;             PG8_WAIT_V(8); PG8_WAIT_L(0); PG8_BAR; PG8_MMA(0, 0, At, B0); PG8_MMA(0, 1, At, B1); PG8_BAR; PG8_SCHED;
;             PG8_LDA(At, 0, 1); PG8_STAGE(PG8_SB(0, 0), b2, voffB); PG8_STAGE(PG8_SB(0, 1), b2 + hstep, voffB); PG8_STAGE(PG8_SA(0, 0), a2, voffA);
;             PG8_WAIT_V(8); PG8_WAIT_L(0); PG8_BAR; PG8_MMA(1, 0, At, B0); PG8_MMA(1, 1, At, B1); PG8_BAR; PG8_SCHED;
;             PG8_LDB(B0, 1, 0); PG8_LDB(B1, 1, 1); PG8_SCHED; PG8_LDA(At, 1, 0); PG8_STAGE(PG8_SA(0, 1), a2 + hstep, voffA);
;             PG8_WAIT_V(8); PG8_WAIT_L(0); PG8_BAR; PG8_MMA(0, 0, At, B0); PG8_MMA(0, 1, At, B1); PG8_BAR; PG8_SCHED;
;             PG8_LDA(At, 1, 1); PG8_STAGE(PG8_SB(1, 0), b3, voffB); PG8_STAGE(PG8_SB(1, 1), b3 + hstep, voffB); PG8_STAGE(PG8_SA(1, 0), a3, voffA);
;             PG8_WAIT_V(8); PG8_WAIT_L(0); PG8_BAR; PG8_MMA(1, 0, At, B0); PG8_MMA(1, 1, At, B1); PG8_BAR; PG8_SCHED;
;     ...
;         if constexpr (ALIGN_EPI) { if (wr == 0) PG8_BAR; }
	v_mfma_f32_16x16x32_bf16 v[66:69], v[182:185], v[228:231], v[66:69]
	s_setprio 0
	s_add_i32 s18, vcc_hi, s88
	v_lshl_add_u64 v[190:191], v[190:191], 0, s[16:17]
	s_mov_b32 m0, s18
	ds_read_b128 v[186:189], v198 offset:49152
	ds_read_b128 v[202:205], v198 offset:50176
	ds_read_b128 v[208:211], v198 offset:51200
	ds_read_b128 v[212:215], v198 offset:52224
	ds_read_b128 v[216:219], v198 offset:53248
	ds_read_b128 v[220:223], v198 offset:54272
	ds_read_b128 v[224:227], v198 offset:55296
	ds_read_b128 v[228:231], v198 offset:56320
	global_load_lds_dwordx4 v[190:191], off
	s_add_i32 m0, s18, 0x2000
	s_add_u32 s18, s30, 0x40080
	v_lshl_add_u64 v[190:191], v[232:233], 0, s[16:17]
	s_addc_u32 s19, s31, 0
	s_add_i32 s30, s52, s88
	global_load_lds_dwordx4 v[190:191], off
	v_lshl_add_u64 v[190:191], s[18:19], 0, v[148:149]
	s_mov_b32 m0, s30
	s_nop 0
	global_load_lds_dwordx4 v[190:191], off
	v_lshl_add_u64 v[190:191], s[18:19], 0, v[152:153]
	s_add_i32 m0, s30, 0x2000
	s_nop 0
	global_load_lds_dwordx4 v[190:191], off
	v_lshl_add_u64 v[190:191], v[234:235], 0, s[16:17]
	s_mov_b32 m0, s24
	s_nop 0
	global_load_lds_dwordx4 v[190:191], off
	v_lshl_add_u64 v[190:191], v[238:239], 0, s[16:17]
	s_mov_b32 m0, s25
	s_nop 0
	global_load_lds_dwordx4 v[190:191], off
	s_waitcnt vmcnt(8)
	s_waitcnt lgkmcnt(0)
	s_barrier
	s_setprio 1
	s_waitcnt lgkmcnt(0)
	v_mfma_f32_16x16x32_bf16 v[62:65], v[130:133], v[186:189], v[62:65]
	v_mfma_f32_16x16x32_bf16 v[58:61], v[138:141], v[186:189], v[58:61]
	v_mfma_f32_16x16x32_bf16 v[46:49], v[130:133], v[208:211], v[46:49]
	v_mfma_f32_16x16x32_bf16 v[42:45], v[138:141], v[208:211], v[42:45]
	v_mfma_f32_16x16x32_bf16 v[30:33], v[130:133], v[216:219], v[30:33]
	v_mfma_f32_16x16x32_bf16 v[26:29], v[138:141], v[216:219], v[26:29]
	v_mfma_f32_16x16x32_bf16 v[14:17], v[130:133], v[224:227], v[14:17]
	v_mfma_f32_16x16x32_bf16 v[10:13], v[138:141], v[224:227], v[10:13]
	v_mfma_f32_16x16x32_bf16 v[62:65], v[134:137], v[202:205], v[62:65]
	v_mfma_f32_16x16x32_bf16 v[58:61], v[142:145], v[202:205], v[58:61]
	v_mfma_f32_16x16x32_bf16 v[46:49], v[134:137], v[212:215], v[46:49]
	v_mfma_f32_16x16x32_bf16 v[42:45], v[142:145], v[212:215], v[42:45]
	v_mfma_f32_16x16x32_bf16 v[30:33], v[134:137], v[220:223], v[30:33]
	v_mfma_f32_16x16x32_bf16 v[26:29], v[142:145], v[220:223], v[26:29]
	v_mfma_f32_16x16x32_bf16 v[14:17], v[134:137], v[228:231], v[14:17]
	v_mfma_f32_16x16x32_bf16 v[10:13], v[142:145], v[228:231], v[10:13]
	s_setprio 0
	s_setprio 1
	v_mfma_f32_16x16x32_bf16 v[54:57], v[170:173], v[186:189], v[54:57]
	v_mfma_f32_16x16x32_bf16 v[50:53], v[178:181], v[186:189], v[50:53]
	v_mfma_f32_16x16x32_bf16 v[38:41], v[170:173], v[208:211], v[38:41]
	v_mfma_f32_16x16x32_bf16 v[34:37], v[178:181], v[208:211], v[34:37]
	v_mfma_f32_16x16x32_bf16 v[22:25], v[170:173], v[216:219], v[22:25]
	v_mfma_f32_16x16x32_bf16 v[18:21], v[178:181], v[216:219], v[18:21]
	v_mfma_f32_16x16x32_bf16 v[6:9], v[170:173], v[224:227], v[6:9]
	v_mfma_f32_16x16x32_bf16 v[2:5], v[178:181], v[224:227], v[2:5]
	v_mfma_f32_16x16x32_bf16 v[54:57], v[174:177], v[202:205], v[54:57]
	v_mfma_f32_16x16x32_bf16 v[50:53], v[182:185], v[202:205], v[50:53]
	v_mfma_f32_16x16x32_bf16 v[38:41], v[174:177], v[212:215], v[38:41]
	v_mfma_f32_16x16x32_bf16 v[34:37], v[182:185], v[212:215], v[34:37]
	v_mfma_f32_16x16x32_bf16 v[22:25], v[174:177], v[220:223], v[22:25]
	v_mfma_f32_16x16x32_bf16 v[18:21], v[182:185], v[220:223], v[18:21]
	v_mfma_f32_16x16x32_bf16 v[6:9], v[174:177], v[228:231], v[6:9]
	s_setprio 3
	s_barrier
	v_mfma_f32_16x16x32_bf16 v[2:5], v[182:185], v[228:231], v[2:5]
	s_setprio 0
	s_add_i32 vcc_lo, vcc_lo, 2
	s_add_u32 s84, s84, 0x100
	s_addc_u32 s85, s85, 0
	s_add_u32 s73, s73, 0x100
	s_addc_u32 s75, s75, 0
	s_cmp_gt_u32 vcc_lo, 13
	s_cbranch_scc0 .LBB0_141
	s_and_b64 vcc, exec, s[26:27]
	s_cbranch_vccz .LBB0_144
	s_barrier

; #define PG8_STAGE(bufoff, gbase, voff) do { _Pragma("unroll") for (int _i = 0; _i < 2; ++_i) \
;         __builtin_amdgcn_global_load_lds((const unsigned*)((const char*)(gbase) + (voff)[_i]), (PG8_LAS unsigned*)(lds + (bufoff) + ldsw + _i * 8192), 16, 0, 0); } while (0)
; #define PG8_LDA(dst, b, h) do { _Pragma("unroll") for (int m = 0; m < 4; ++m) _Pragma("unroll") for (int k = 0; k < 2; ++k) dst[m][k] = *(const PG8_LAS bf16x8*)(lds + PG8_SA(b, h) + aoff + m * 2048 + k * 1024); } while (0)
; #define PG8_LDB(dst, b, h) do { _Pragma("unroll") for (int n = 0; n < 2; ++n) _Pragma("unroll") for (int k = 0; k < 2; ++k) dst[n][k] = *(const PG8_LAS bf16x8*)(lds + PG8_SB(b, h) + boff + n * 2048 + k * 1024); } while (0)
; #define PG8_MMA(ai, bj, At, Bt) do { __builtin_amdgcn_s_setprio(1); _Pragma("unroll") for (int m = 0; m < 4; ++m) _Pragma("unroll") for (int n = 0; n < 2; ++n) _Pragma("unroll") for (int k = 0; k < 2; ++k) \
;         acc[ai][bj][m][n] = __builtin_amdgcn_mfma_f32_16x16x32_bf16(Bt[n][k], At[m][k], acc[ai][bj][m][n], 0, 0, 0); __builtin_amdgcn_s_setprio(0); } while (0)
; #define PG8_WAIT_V(n) asm volatile("s_waitcnt vmcnt(" #n ")" ::: "memory")
; template <class Epi, class Sched, bool ALIGN_EPI = false, bool SP2 = false>
; __device__ __forceinline__ void gemm_phase(PG8_LAS unsigned char* lds, const Gemm g, const Sched& S, const Epi& E) {
;     ...
;             PG8_LDB(B0, 0, 0); PG8_LDB(B1, 0, 1); PG8_SCHED; PG8_LDA(At, 0, 0); PG8_STAGE(PG8_SA(1, 1), a1 + hstep, voffA);
;             PG8_WAIT_V(8); PG8_WAIT_L(0); PG8_BAR; PG8_MMA(0, 0, At, B0); PG8_MMA(0, 1, At, B1); PG8_BAR; PG8_SCHED;
;             PG8_LDA(At, 0, 1); PG8_STAGE(PG8_SB(0, 0), b2, voffB); PG8_STAGE(PG8_SB(0, 1), b2 + hstep, voffB); PG8_STAGE(PG8_SA(0, 0), a2, voffA);
;             PG8_WAIT_V(8); PG8_WAIT_L(0); PG8_BAR; PG8_MMA(1, 0, At, B0); PG8_MMA(1, 1, At, B1); PG8_BAR; PG8_SCHED;
;             PG8_LDB(B0, 1, 0); PG8_LDB(B1, 1, 1); PG8_SCHED; PG8_LDA(At, 1, 0); PG8_STAGE(PG8_SA(0, 1), a2 + hstep, voffA);
;             PG8_WAIT_V(8); PG8_WAIT_L(0); PG8_BAR; PG8_MMA(0, 0, At, B0); PG8_MMA(0, 1, At, B1); PG8_BAR; PG8_SCHED;
;             PG8_LDA(At, 1, 1); PG8_STAGE(PG8_SB(1, 0), b3, voffB); PG8_STAGE(PG8_SB(1, 1), b3 + hstep, voffB); PG8_STAGE(PG8_SA(1, 0), a3, voffA);
;             PG8_WAIT_V(8); PG8_WAIT_L(0); PG8_BAR; PG8_MMA(1, 0, At, B0); PG8_MMA(1, 1, At, B1); PG8_BAR; PG8_SCHED;
.LBB0_609:
	ds_read_b128 v[98:101], v239
	ds_read_b128 v[110:113], v239 offset:1024
	ds_read_b128 v[122:125], v239 offset:2048
	ds_read_b128 v[134:137], v239 offset:3072
	ds_read_b128 v[138:141], v240
	ds_read_b128 v[142:145], v240 offset:1024
	ds_read_b128 v[146:149], v240 offset:2048
	ds_read_b128 v[150:153], v240 offset:3072
	s_add_u32 s18, s40, 0xfffc0080
	s_addc_u32 s19, s41, -1
	s_cmp_eq_u32 s62, 12
	s_cselect_b32 s43, s27, s19
	s_cselect_b32 s42, s39, s18
	s_cselect_b32 s31, s17, s61
	s_cselect_b32 s30, s59, s60
	v_lshl_add_u64 v[208:209], s[40:41], 0, v[198:199]
	s_add_i32 m0, s45, 0xc000
	ds_read_b128 v[162:165], v241
	ds_read_b128 v[166:169], v241 offset:1024
	ds_read_b128 v[170:173], v241 offset:2048
	ds_read_b128 v[174:177], v241 offset:3072
	ds_read_b128 v[178:181], v241 offset:4096
	ds_read_b128 v[182:185], v241 offset:5120
	ds_read_b128 v[186:189], v241 offset:6144
	ds_read_b128 v[204:207], v241 offset:7168
	global_load_lds_dwordx4 v[208:209], off
	v_lshl_add_u64 v[208:209], s[40:41], 0, v[200:201]
	s_add_i32 m0, s45, 0xe000
	s_nop 0
	global_load_lds_dwordx4 v[208:209], off
	s_waitcnt vmcnt(8)
	s_waitcnt lgkmcnt(0)
	s_barrier
	s_setprio 1
	s_waitcnt lgkmcnt(0)
	v_mfma_f32_16x16x32_bf16 v[158:161], v[98:101], v[162:165], v[158:161]
	v_mfma_f32_16x16x32_bf16 v[154:157], v[122:125], v[162:165], v[154:157]
	v_mfma_f32_16x16x32_bf16 v[118:121], v[98:101], v[170:173], v[118:121]
	v_mfma_f32_16x16x32_bf16 v[114:117], v[122:125], v[170:173], v[114:117]
	v_mfma_f32_16x16x32_bf16 v[94:97], v[98:101], v[178:181], v[94:97]
	v_mfma_f32_16x16x32_bf16 v[90:93], v[122:125], v[178:181], v[90:93]
	v_mfma_f32_16x16x32_bf16 v[78:81], v[98:101], v[186:189], v[78:81]
	v_mfma_f32_16x16x32_bf16 v[74:77], v[122:125], v[186:189], v[74:77]
	v_mfma_f32_16x16x32_bf16 v[158:161], v[110:113], v[166:169], v[158:161]
	v_mfma_f32_16x16x32_bf16 v[154:157], v[134:137], v[166:169], v[154:157]
	v_mfma_f32_16x16x32_bf16 v[118:121], v[110:113], v[174:177], v[118:121]
	v_mfma_f32_16x16x32_bf16 v[114:117], v[134:137], v[174:177], v[114:117]
	v_mfma_f32_16x16x32_bf16 v[94:97], v[110:113], v[182:185], v[94:97]
	v_mfma_f32_16x16x32_bf16 v[90:93], v[134:137], v[182:185], v[90:93]
	v_mfma_f32_16x16x32_bf16 v[78:81], v[110:113], v[204:207], v[78:81]
	v_mfma_f32_16x16x32_bf16 v[74:77], v[134:137], v[204:207], v[74:77]
	s_setprio 0
	s_setprio 1
	v_mfma_f32_16x16x32_bf16 v[130:133], v[138:141], v[162:165], v[130:133]
	v_mfma_f32_16x16x32_bf16 v[126:129], v[146:149], v[162:165], v[126:129]
	v_mfma_f32_16x16x32_bf16 v[106:109], v[138:141], v[170:173], v[106:109]
	v_mfma_f32_16x16x32_bf16 v[102:105], v[146:149], v[170:173], v[102:105]
	v_mfma_f32_16x16x32_bf16 v[86:89], v[138:141], v[178:181], v[86:89]
	v_mfma_f32_16x16x32_bf16 v[82:85], v[146:149], v[178:181], v[82:85]
	v_mfma_f32_16x16x32_bf16 v[70:73], v[138:141], v[186:189], v[70:73]
	v_mfma_f32_16x16x32_bf16 v[66:69], v[146:149], v[186:189], v[66:69]
	v_mfma_f32_16x16x32_bf16 v[130:133], v[142:145], v[166:169], v[130:133]
	v_mfma_f32_16x16x32_bf16 v[126:129], v[150:153], v[166:169], v[126:129]
	v_mfma_f32_16x16x32_bf16 v[106:109], v[142:145], v[174:177], v[106:109]
	v_mfma_f32_16x16x32_bf16 v[102:105], v[150:153], v[174:177], v[102:105]
	v_mfma_f32_16x16x32_bf16 v[86:89], v[142:145], v[182:185], v[86:89]
	v_mfma_f32_16x16x32_bf16 v[82:85], v[150:153], v[182:185], v[82:85]
	v_mfma_f32_16x16x32_bf16 v[70:73], v[142:145], v[204:207], v[70:73]
	s_setprio 3
	s_barrier
	v_mfma_f32_16x16x32_bf16 v[66:69], v[150:153], v[204:207], v[66:69]
	s_setprio 0
	s_add_i32 s18, s56, s44
	v_lshl_add_u64 v[208:209], s[30:31], 0, v[192:193]
	s_mov_b32 m0, s18
	ds_read_b128 v[162:165], v241 offset:16384
	ds_read_b128 v[166:169], v241 offset:17408
	ds_read_b128 v[170:173], v241 offset:18432
	ds_read_b128 v[174:177], v241 offset:19456
	ds_read_b128 v[178:181], v241 offset:20480
	ds_read_b128 v[182:185], v241 offset:21504
	ds_read_b128 v[186:189], v241 offset:22528
	ds_read_b128 v[204:207], v241 offset:23552
	global_load_lds_dwordx4 v[208:209], off
	s_add_i32 m0, s18, 0x2000
	s_add_u32 s18, s30, 0x40000
	v_lshl_add_u64 v[210:211], s[30:31], 0, v[196:197]
	s_addc_u32 s19, s31, 0
	s_add_i32 s63, s57, s44
	global_load_lds_dwordx4 v[210:211], off
	v_lshl_add_u64 v[212:213], s[18:19], 0, v[192:193]
	s_mov_b32 m0, s63
	v_lshl_add_u64 v[214:215], s[42:43], 0, v[194:195]
	global_load_lds_dwordx4 v[212:213], off
	v_lshl_add_u64 v[212:213], s[18:19], 0, v[196:197]
	s_add_i32 m0, s63, 0x2000
	s_nop 0
	global_load_lds_dwordx4 v[212:213], off
	v_lshl_add_u64 v[212:213], s[42:43], 0, v[190:191]
	s_mov_b32 m0, s45
	s_nop 0
	global_load_lds_dwordx4 v[212:213], off
	s_mov_b32 m0, s46
	s_nop 0
	global_load_lds_dwordx4 v[214:215], off
	s_waitcnt vmcnt(8)
	s_waitcnt lgkmcnt(0)
	s_barrier
; #define PG8_STAGE(bufoff, gbase, voff) do { _Pragma("unroll") for (int _i = 0; _i < 2; ++_i) \
;         __builtin_amdgcn_global_load_lds((const unsigned*)((const char*)(gbase) + (voff)[_i]), (PG8_LAS unsigned*)(lds + (bufoff) + ldsw + _i * 8192), 16, 0, 0); } while (0)
; #define PG8_LDA(dst, b, h) do { _Pragma("unroll") for (int m = 0; m < 4; ++m) _Pragma("unroll") for (int k = 0; k < 2; ++k) dst[m][k] = *(const PG8_LAS bf16x8*)(lds + PG8_SA(b, h) + aoff + m * 2048 + k * 1024); } while (0)
; #define PG8_LDB(dst, b, h) do { _Pragma("unroll") for (int n = 0; n < 2; ++n) _Pragma("unroll") for (int k = 0; k < 2; ++k) dst[n][k] = *(const PG8_LAS bf16x8*)(lds + PG8_SB(b, h) + boff + n * 2048 + k * 1024); } while (0)
; #define PG8_MMA(ai, bj, At, Bt) do { __builtin_amdgcn_s_setprio(1); _Pragma("unroll") for (int m = 0; m < 4; ++m) _Pragma("unroll") for (int n = 0; n < 2; ++n) _Pragma("unroll") for (int k = 0; k < 2; ++k) \
;         acc[ai][bj][m][n] = __builtin_amdgcn_mfma_f32_16x16x32_bf16(Bt[n][k], At[m][k], acc[ai][bj][m][n], 0, 0, 0); __builtin_amdgcn_s_setprio(0); } while (0)
; #define PG8_WAIT_V(n) asm volatile("s_waitcnt vmcnt(" #n ")" ::: "memory")
; template <class Epi, class Sched, bool ALIGN_EPI = false, bool SP2 = false>
; __device__ __forceinline__ void gemm_phase(PG8_LAS unsigned char* lds, const Gemm g, const Sched& S, const Epi& E) {
;     ...
;             PG8_LDB(B0, 0, 0); PG8_LDB(B1, 0, 1); PG8_SCHED; PG8_LDA(At, 0, 0); PG8_STAGE(PG8_SA(1, 1), a1 + hstep, voffA);
;             PG8_WAIT_V(8); PG8_WAIT_L(0); PG8_BAR; PG8_MMA(0, 0, At, B0); PG8_MMA(0, 1, At, B1); PG8_BAR; PG8_SCHED;
;             PG8_LDA(At, 0, 1); PG8_STAGE(PG8_SB(0, 0), b2, voffB); PG8_STAGE(PG8_SB(0, 1), b2 + hstep, voffB); PG8_STAGE(PG8_SA(0, 0), a2, voffA);
;             PG8_WAIT_V(8); PG8_WAIT_L(0); PG8_BAR; PG8_MMA(1, 0, At, B0); PG8_MMA(1, 1, At, B1); PG8_BAR; PG8_SCHED;
;             PG8_LDB(B0, 1, 0); PG8_LDB(B1, 1, 1); PG8_SCHED; PG8_LDA(At, 1, 0); PG8_STAGE(PG8_SA(0, 1), a2 + hstep, voffA);
;             PG8_WAIT_V(8); PG8_WAIT_L(0); PG8_BAR; PG8_MMA(0, 0, At, B0); PG8_MMA(0, 1, At, B1); PG8_BAR; PG8_SCHED;
;             PG8_LDA(At, 1, 1); PG8_STAGE(PG8_SB(1, 0), b3, voffB); PG8_STAGE(PG8_SB(1, 1), b3 + hstep, voffB); PG8_STAGE(PG8_SA(1, 0), a3, voffA);
;             PG8_WAIT_V(8); PG8_WAIT_L(0); PG8_BAR; PG8_MMA(1, 0, At, B0); PG8_MMA(1, 1, At, B1); PG8_BAR; PG8_SCHED;
	s_setprio 1
	s_waitcnt lgkmcnt(0)
	v_mfma_f32_16x16x32_bf16 v[62:65], v[98:101], v[162:165], v[62:65]
	v_mfma_f32_16x16x32_bf16 v[58:61], v[122:125], v[162:165], v[58:61]
	v_mfma_f32_16x16x32_bf16 v[46:49], v[98:101], v[170:173], v[46:49]
	v_mfma_f32_16x16x32_bf16 v[42:45], v[122:125], v[170:173], v[42:45]
	v_mfma_f32_16x16x32_bf16 v[30:33], v[98:101], v[178:181], v[30:33]
	v_mfma_f32_16x16x32_bf16 v[26:29], v[122:125], v[178:181], v[26:29]
	v_mfma_f32_16x16x32_bf16 v[14:17], v[98:101], v[186:189], v[14:17]
	v_mfma_f32_16x16x32_bf16 v[10:13], v[122:125], v[186:189], v[10:13]
	v_mfma_f32_16x16x32_bf16 v[62:65], v[110:113], v[166:169], v[62:65]
	v_mfma_f32_16x16x32_bf16 v[58:61], v[134:137], v[166:169], v[58:61]
	v_mfma_f32_16x16x32_bf16 v[46:49], v[110:113], v[174:177], v[46:49]
	v_mfma_f32_16x16x32_bf16 v[42:45], v[134:137], v[174:177], v[42:45]
	v_mfma_f32_16x16x32_bf16 v[30:33], v[110:113], v[182:185], v[30:33]
	v_mfma_f32_16x16x32_bf16 v[26:29], v[134:137], v[182:185], v[26:29]
	v_mfma_f32_16x16x32_bf16 v[14:17], v[110:113], v[204:207], v[14:17]
	v_mfma_f32_16x16x32_bf16 v[10:13], v[134:137], v[204:207], v[10:13]
	s_setprio 0
	s_setprio 1
	v_mfma_f32_16x16x32_bf16 v[54:57], v[138:141], v[162:165], v[54:57]
	v_mfma_f32_16x16x32_bf16 v[50:53], v[146:149], v[162:165], v[50:53]
	v_mfma_f32_16x16x32_bf16 v[38:41], v[138:141], v[170:173], v[38:41]
	v_mfma_f32_16x16x32_bf16 v[34:37], v[146:149], v[170:173], v[34:37]
	v_mfma_f32_16x16x32_bf16 v[22:25], v[138:141], v[178:181], v[22:25]
	v_mfma_f32_16x16x32_bf16 v[18:21], v[146:149], v[178:181], v[18:21]
	v_mfma_f32_16x16x32_bf16 v[6:9], v[138:141], v[186:189], v[6:9]
	v_mfma_f32_16x16x32_bf16 v[2:5], v[146:149], v[186:189], v[2:5]
	v_mfma_f32_16x16x32_bf16 v[54:57], v[142:145], v[166:169], v[54:57]
	v_mfma_f32_16x16x32_bf16 v[50:53], v[150:153], v[166:169], v[50:53]
	v_mfma_f32_16x16x32_bf16 v[38:41], v[142:145], v[174:177], v[38:41]
	v_mfma_f32_16x16x32_bf16 v[34:37], v[150:153], v[174:177], v[34:37]
	v_mfma_f32_16x16x32_bf16 v[22:25], v[142:145], v[182:185], v[22:25]
	v_mfma_f32_16x16x32_bf16 v[18:21], v[150:153], v[182:185], v[18:21]
	v_mfma_f32_16x16x32_bf16 v[6:9], v[142:145], v[204:207], v[6:9]
	s_setprio 3
	s_barrier
	v_mfma_f32_16x16x32_bf16 v[2:5], v[150:153], v[204:207], v[2:5]
	s_setprio 0
	s_add_i32 s63, 0, 0x18000
	s_add_i32 s64, 0, 0x1c000
	v_add_u32_e32 v134, s63, v237
	v_add_u32_e32 v150, s64, v237
	ds_read_b128 v[98:101], v134
	ds_read_b128 v[110:113], v134 offset:1024
	ds_read_b128 v[122:125], v134 offset:2048
	ds_read_b128 v[134:137], v134 offset:3072
	ds_read_b128 v[138:141], v150
	ds_read_b128 v[142:145], v150 offset:1024
	ds_read_b128 v[146:149], v150 offset:2048
	ds_read_b128 v[150:153], v150 offset:3072
	s_add_u32 s18, s42, 0x40000
	s_addc_u32 s19, s43, 0
	s_mov_b32 m0, s47
	v_lshl_add_u64 v[216:217], s[18:19], 0, v[190:191]
	ds_read_b128 v[162:165], v241 offset:32768
	ds_read_b128 v[166:169], v241 offset:33792
	ds_read_b128 v[170:173], v241 offset:34816
	ds_read_b128 v[174:177], v241 offset:35840
	ds_read_b128 v[178:181], v241 offset:36864
	ds_read_b128 v[182:185], v241 offset:37888
	ds_read_b128 v[186:189], v241 offset:38912
	ds_read_b128 v[204:207], v241 offset:39936
	global_load_lds_dwordx4 v[216:217], off
	v_lshl_add_u64 v[216:217], s[18:19], 0, v[194:195]
	s_mov_b32 m0, s48
	s_nop 0
	global_load_lds_dwordx4 v[216:217], off
	s_waitcnt vmcnt(8)
	s_waitcnt lgkmcnt(0)
	s_barrier
	s_setprio 1
	s_waitcnt lgkmcnt(0)
	v_mfma_f32_16x16x32_bf16 v[158:161], v[98:101], v[162:165], v[158:161]
	v_mfma_f32_16x16x32_bf16 v[154:157], v[122:125], v[162:165], v[154:157]
	v_mfma_f32_16x16x32_bf16 v[118:121], v[98:101], v[170:173], v[118:121]
	v_mfma_f32_16x16x32_bf16 v[114:117], v[122:125], v[170:173], v[114:117]
	v_mfma_f32_16x16x32_bf16 v[94:97], v[98:101], v[178:181], v[94:97]
	v_mfma_f32_16x16x32_bf16 v[90:93], v[122:125], v[178:181], v[90:93]
	v_mfma_f32_16x16x32_bf16 v[78:81], v[98:101], v[186:189], v[78:81]
	v_mfma_f32_16x16x32_bf16 v[74:77], v[122:125], v[186:189], v[74:77]
	v_mfma_f32_16x16x32_bf16 v[158:161], v[110:113], v[166:169], v[158:161]
	v_mfma_f32_16x16x32_bf16 v[154:157], v[134:137], v[166:169], v[154:157]
	v_mfma_f32_16x16x32_bf16 v[118:121], v[110:113], v[174:177], v[118:121]
	v_mfma_f32_16x16x32_bf16 v[114:117], v[134:137], v[174:177], v[114:117]
	v_mfma_f32_16x16x32_bf16 v[94:97], v[110:113], v[182:185], v[94:97]
	v_mfma_f32_16x16x32_bf16 v[90:93], v[134:137], v[182:185], v[90:93]
	v_mfma_f32_16x16x32_bf16 v[78:81], v[110:113], v[204:207], v[78:81]
	v_mfma_f32_16x16x32_bf16 v[74:77], v[134:137], v[204:207], v[74:77]
	s_setprio 0
	s_setprio 1
	v_mfma_f32_16x16x32_bf16 v[130:133], v[138:141], v[162:165], v[130:133]
	v_mfma_f32_16x16x32_bf16 v[126:129], v[146:149], v[162:165], v[126:129]
	v_mfma_f32_16x16x32_bf16 v[106:109], v[138:141], v[170:173], v[106:109]
	v_mfma_f32_16x16x32_bf16 v[102:105], v[146:149], v[170:173], v[102:105]
	v_mfma_f32_16x16x32_bf16 v[86:89], v[138:141], v[178:181], v[86:89]
	v_mfma_f32_16x16x32_bf16 v[82:85], v[146:149], v[178:181], v[82:85]
	v_mfma_f32_16x16x32_bf16 v[70:73], v[138:141], v[186:189], v[70:73]
	v_mfma_f32_16x16x32_bf16 v[66:69], v[146:149], v[186:189], v[66:69]
	v_mfma_f32_16x16x32_bf16 v[130:133], v[142:145], v[166:169], v[130:133]
	v_mfma_f32_16x16x32_bf16 v[126:129], v[150:153], v[166:169], v[126:129]
	v_mfma_f32_16x16x32_bf16 v[106:109], v[142:145], v[174:177], v[106:109]
	v_mfma_f32_16x16x32_bf16 v[102:105], v[150:153], v[174:177], v[102:105]
	v_mfma_f32_16x16x32_bf16 v[86:89], v[142:145], v[182:185], v[86:89]
	v_mfma_f32_16x16x32_bf16 v[82:85], v[150:153], v[182:185], v[82:85]
	v_mfma_f32_16x16x32_bf16 v[70:73], v[142:145], v[204:207], v[70:73]
	s_setprio 3
	s_barrier
; #define PG8_STAGE(bufoff, gbase, voff) do { _Pragma("unroll") for (int _i = 0; _i < 2; ++_i) \
;         __builtin_amdgcn_global_load_lds((const unsigned*)((const char*)(gbase) + (voff)[_i]), (PG8_LAS unsigned*)(lds + (bufoff) + ldsw + _i * 8192), 16, 0, 0); } while (0)
; #define PG8_LDA(dst, b, h) do { _Pragma("unroll") for (int m = 0; m < 4; ++m) _Pragma("unroll") for (int k = 0; k < 2; ++k) dst[m][k] = *(const PG8_LAS bf16x8*)(lds + PG8_SA(b, h) + aoff + m * 2048 + k * 1024); } while (0)
; #define PG8_LDB(dst, b, h) do { _Pragma("unroll") for (int n = 0; n < 2; ++n) _Pragma("unroll") for (int k = 0; k < 2; ++k) dst[n][k] = *(const PG8_LAS bf16x8*)(lds + PG8_SB(b, h) + boff + n * 2048 + k * 1024); } while (0)
; #define PG8_WAIT_V(n) asm volatile("s_waitcnt vmcnt(" #n ")" ::: "memory")
; #define PG8_WAIT_L(n) asm volatile("s_waitcnt lgkmcnt(" #n ")" ::: "memory")
;     __device__ __forceinline__ void operator()(const f32x4 (&acc)[2][2][4][2], const Unit& u, int wr, int wc, int fr, int fq) const {
;     ...
;                 for (int bj = 0; bj < 2; ++bj) bva[ai][m][bj] = *(const u32x4*)(Xb + (size_t)(row0 + ai * HALF + m * 16) * DM + col0 + bj * HALF);
; template <class Epi, class Sched, bool ALIGN_EPI = false, bool SP2 = false>
; __device__ __forceinline__ void gemm_phase(PG8_LAS unsigned char* lds, const Gemm g, const Sched& S, const Epi& E) {
;     ...
;             PG8_LDB(B0, 0, 0); PG8_LDB(B1, 0, 1); PG8_SCHED; PG8_LDA(At, 0, 0); PG8_STAGE(PG8_SA(1, 1), a1 + hstep, voffA);
;             PG8_WAIT_V(8); PG8_WAIT_L(0); PG8_BAR; PG8_MMA(0, 0, At, B0); PG8_MMA(0, 1, At, B1); PG8_BAR; PG8_SCHED;
;             PG8_LDA(At, 0, 1); PG8_STAGE(PG8_SB(0, 0), b2, voffB); PG8_STAGE(PG8_SB(0, 1), b2 + hstep, voffB); PG8_STAGE(PG8_SA(0, 0), a2, voffA);
;             PG8_WAIT_V(8); PG8_WAIT_L(0); PG8_BAR; PG8_MMA(1, 0, At, B0); PG8_MMA(1, 1, At, B1); PG8_BAR; PG8_SCHED;
;             PG8_LDB(B0, 1, 0); PG8_LDB(B1, 1, 1); PG8_SCHED; PG8_LDA(At, 1, 0); PG8_STAGE(PG8_SA(0, 1), a2 + hstep, voffA);
;             PG8_WAIT_V(8); PG8_WAIT_L(0); PG8_BAR; PG8_MMA(0, 0, At, B0); PG8_MMA(0, 1, At, B1); PG8_BAR; PG8_SCHED;
;             PG8_LDA(At, 1, 1); PG8_STAGE(PG8_SB(1, 0), b3, voffB); PG8_STAGE(PG8_SB(1, 1), b3 + hstep, voffB); PG8_STAGE(PG8_SA(1, 0), a3, voffA);
;             PG8_WAIT_V(8); PG8_WAIT_L(0); PG8_BAR; PG8_MMA(1, 0, At, B0); PG8_MMA(1, 1, At, B1); PG8_BAR; PG8_SCHED;
	v_mfma_f32_16x16x32_bf16 v[66:69], v[150:153], v[204:207], v[66:69]
	s_setprio 0
	s_add_i32 s18, s63, s44
	v_lshl_add_u64 v[208:209], v[208:209], 0, s[12:13]
	s_mov_b32 m0, s18
	ds_read_b128 v[162:165], v241 offset:49152
	ds_read_b128 v[166:169], v241 offset:50176
	ds_read_b128 v[170:173], v241 offset:51200
	ds_read_b128 v[174:177], v241 offset:52224
	ds_read_b128 v[178:181], v241 offset:53248
	ds_read_b128 v[182:185], v241 offset:54272
	ds_read_b128 v[186:189], v241 offset:55296
	ds_read_b128 v[204:207], v241 offset:56320
	global_load_lds_dwordx4 v[208:209], off
	s_add_i32 m0, s18, 0x2000
	s_add_u32 s18, s30, 0x40080
	v_lshl_add_u64 v[208:209], v[210:211], 0, s[12:13]
	s_addc_u32 s19, s31, 0
	s_add_i32 s30, s64, s44
	global_load_lds_dwordx4 v[208:209], off
	v_lshl_add_u64 v[208:209], s[18:19], 0, v[192:193]
	s_mov_b32 m0, s30
	s_nop 0
	global_load_lds_dwordx4 v[208:209], off
	v_lshl_add_u64 v[208:209], s[18:19], 0, v[196:197]
	s_add_i32 m0, s30, 0x2000
	s_nop 0
	global_load_lds_dwordx4 v[208:209], off
	v_lshl_add_u64 v[208:209], v[212:213], 0, s[12:13]
	s_mov_b32 m0, s52
	s_nop 0
	global_load_lds_dwordx4 v[208:209], off
	v_lshl_add_u64 v[208:209], v[214:215], 0, s[12:13]
	s_mov_b32 m0, s53
	s_nop 0
	global_load_lds_dwordx4 v[208:209], off
	s_waitcnt vmcnt(8)
	s_waitcnt lgkmcnt(0)
	s_barrier
	s_setprio 1
	s_waitcnt lgkmcnt(0)
	v_mfma_f32_16x16x32_bf16 v[62:65], v[98:101], v[162:165], v[62:65]
	v_mfma_f32_16x16x32_bf16 v[58:61], v[122:125], v[162:165], v[58:61]
	v_mfma_f32_16x16x32_bf16 v[46:49], v[98:101], v[170:173], v[46:49]
	v_mfma_f32_16x16x32_bf16 v[42:45], v[122:125], v[170:173], v[42:45]
	v_mfma_f32_16x16x32_bf16 v[30:33], v[98:101], v[178:181], v[30:33]
	v_mfma_f32_16x16x32_bf16 v[26:29], v[122:125], v[178:181], v[26:29]
	v_mfma_f32_16x16x32_bf16 v[14:17], v[98:101], v[186:189], v[14:17]
	v_mfma_f32_16x16x32_bf16 v[10:13], v[122:125], v[186:189], v[10:13]
	v_mfma_f32_16x16x32_bf16 v[62:65], v[110:113], v[166:169], v[62:65]
	v_mfma_f32_16x16x32_bf16 v[58:61], v[134:137], v[166:169], v[58:61]
	v_mfma_f32_16x16x32_bf16 v[46:49], v[110:113], v[174:177], v[46:49]
	v_mfma_f32_16x16x32_bf16 v[42:45], v[134:137], v[174:177], v[42:45]
	v_mfma_f32_16x16x32_bf16 v[30:33], v[110:113], v[182:185], v[30:33]
	v_mfma_f32_16x16x32_bf16 v[26:29], v[134:137], v[182:185], v[26:29]
	v_mfma_f32_16x16x32_bf16 v[14:17], v[110:113], v[204:207], v[14:17]
	v_mfma_f32_16x16x32_bf16 v[10:13], v[134:137], v[204:207], v[10:13]
	s_setprio 0
	s_setprio 1
	v_mfma_f32_16x16x32_bf16 v[54:57], v[138:141], v[162:165], v[54:57]
	v_mfma_f32_16x16x32_bf16 v[50:53], v[146:149], v[162:165], v[50:53]
	v_mfma_f32_16x16x32_bf16 v[38:41], v[138:141], v[170:173], v[38:41]
	v_mfma_f32_16x16x32_bf16 v[34:37], v[146:149], v[170:173], v[34:37]
	v_mfma_f32_16x16x32_bf16 v[22:25], v[138:141], v[178:181], v[22:25]
	v_mfma_f32_16x16x32_bf16 v[18:21], v[146:149], v[178:181], v[18:21]
	v_mfma_f32_16x16x32_bf16 v[6:9], v[138:141], v[186:189], v[6:9]
	v_mfma_f32_16x16x32_bf16 v[2:5], v[146:149], v[186:189], v[2:5]
	v_mfma_f32_16x16x32_bf16 v[54:57], v[142:145], v[166:169], v[54:57]
	v_mfma_f32_16x16x32_bf16 v[50:53], v[150:153], v[166:169], v[50:53]
	v_mfma_f32_16x16x32_bf16 v[38:41], v[142:145], v[174:177], v[38:41]
	v_mfma_f32_16x16x32_bf16 v[34:37], v[150:153], v[174:177], v[34:37]
	v_mfma_f32_16x16x32_bf16 v[22:25], v[142:145], v[182:185], v[22:25]
	v_mfma_f32_16x16x32_bf16 v[18:21], v[150:153], v[182:185], v[18:21]
	v_mfma_f32_16x16x32_bf16 v[6:9], v[142:145], v[204:207], v[6:9]
	s_setprio 3
	s_barrier
	v_mfma_f32_16x16x32_bf16 v[2:5], v[150:153], v[204:207], v[2:5]
	s_setprio 0
	s_add_i32 s62, s62, 2
	s_add_u32 s40, s40, 0x100
	s_addc_u32 s41, s41, 0
	s_add_u32 s60, s60, 0x100
	s_addc_u32 s61, s61, 0
	s_cmp_gt_u32 s62, 13
	s_cbranch_scc1 .Lrp_gen_p3
	s_cmp_lg_u32 s62, 12
	s_cbranch_scc1 .LBB0_609
	s_cmpk_lg_i32 s33, 0x100
	s_cbranch_scc1 .LBB0_609
	ds_read_b128 v[98:101], v239
	ds_read_b128 v[110:113], v239 offset:1024
	ds_read_b128 v[122:125], v239 offset:2048
	ds_read_b128 v[134:137], v239 offset:3072
	ds_read_b128 v[138:141], v240
	ds_read_b128 v[142:145], v240 offset:1024
	ds_read_b128 v[146:149], v240 offset:2048
	ds_read_b128 v[150:153], v240 offset:3072
	s_add_u32 s18, s40, 0xfffc0080
	s_addc_u32 s19, s41, -1
	s_cmp_eq_u32 s62, 12
	s_cselect_b32 s43, s27, s19
	s_cselect_b32 s42, s39, s18
	s_cselect_b32 s31, s17, s61
	s_cselect_b32 s30, s59, s60
	v_lshl_add_u64 v[208:209], s[40:41], 0, v[198:199]
	s_add_i32 m0, s45, 0xc000
	ds_read_b128 v[162:165], v241
	ds_read_b128 v[166:169], v241 offset:1024
	ds_read_b128 v[170:173], v241 offset:2048
	ds_read_b128 v[174:177], v241 offset:3072
	ds_read_b128 v[178:181], v241 offset:4096
	ds_read_b128 v[182:185], v241 offset:5120
	ds_read_b128 v[186:189], v241 offset:6144
	ds_read_b128 v[204:207], v241 offset:7168
	global_load_lds_dwordx4 v[208:209], off
	v_lshl_add_u64 v[208:209], s[40:41], 0, v[200:201]
	s_add_i32 m0, s45, 0xe000
	s_nop 0
	global_load_lds_dwordx4 v[208:209], off
	v_lshl_or_b32 v255, s0, 8, v238
	v_lshl_add_u32 v235, s38, 8, v1
	v_lshlrev_b32_e32 v255, 1, v255
	v_lshl_add_u32 v255, v235, 11, v255
	s_mov_b64 s[84:85], s[20:21]
	global_load_dwordx4 v[242:245], v255, s[84:85]
	global_load_dwordx4 v[208:211], v255, s[84:85] offset:256
	s_add_u32 s84, s20, 0x8000
	s_addc_u32 s85, s21, 0
	global_load_dwordx4 v[212:215], v255, s[84:85]
	global_load_dwordx4 v[216:219], v255, s[84:85] offset:256
	s_add_u32 s84, s20, 0x10000
	s_addc_u32 s85, s21, 0
	global_load_dwordx4 v[220:223], v255, s[84:85]
	global_load_dwordx4 v[224:227], v255, s[84:85] offset:256
	s_add_u32 s84, s20, 0x18000
	s_addc_u32 s85, s21, 0
	global_load_dwordx4 v[228:231], v255, s[84:85]
	global_load_dwordx4 v[232:235], v255, s[84:85] offset:256
	s_add_u32 s84, s20, 0x40000
	s_addc_u32 s85, s21, 0
	global_load_dwordx4 v[246:249], v255, s[84:85]
	global_load_dwordx4 v[250:253], v255, s[84:85] offset:256
	s_waitcnt vmcnt(18)
	s_waitcnt lgkmcnt(0)
	s_barrier
; #define PG8_STAGE(bufoff, gbase, voff) do { _Pragma("unroll") for (int _i = 0; _i < 2; ++_i) \
;         __builtin_amdgcn_global_load_lds((const unsigned*)((const char*)(gbase) + (voff)[_i]), (PG8_LAS unsigned*)(lds + (bufoff) + ldsw + _i * 8192), 16, 0, 0); } while (0)
; #define PG8_LDA(dst, b, h) do { _Pragma("unroll") for (int m = 0; m < 4; ++m) _Pragma("unroll") for (int k = 0; k < 2; ++k) dst[m][k] = *(const PG8_LAS bf16x8*)(lds + PG8_SA(b, h) + aoff + m * 2048 + k * 1024); } while (0)
; #define PG8_LDB(dst, b, h) do { _Pragma("unroll") for (int n = 0; n < 2; ++n) _Pragma("unroll") for (int k = 0; k < 2; ++k) dst[n][k] = *(const PG8_LAS bf16x8*)(lds + PG8_SB(b, h) + boff + n * 2048 + k * 1024); } while (0)
; #define PG8_MMA(ai, bj, At, Bt) do { __builtin_amdgcn_s_setprio(1); _Pragma("unroll") for (int m = 0; m < 4; ++m) _Pragma("unroll") for (int n = 0; n < 2; ++n) _Pragma("unroll") for (int k = 0; k < 2; ++k) \
;         acc[ai][bj][m][n] = __builtin_amdgcn_mfma_f32_16x16x32_bf16(Bt[n][k], At[m][k], acc[ai][bj][m][n], 0, 0, 0); __builtin_amdgcn_s_setprio(0); } while (0)
; #define PG8_WAIT_V(n) asm volatile("s_waitcnt vmcnt(" #n ")" ::: "memory")
; template <class Epi, class Sched, bool ALIGN_EPI = false, bool SP2 = false>
; __device__ __forceinline__ void gemm_phase(PG8_LAS unsigned char* lds, const Gemm g, const Sched& S, const Epi& E) {
;     ...
;             PG8_LDB(B0, 0, 0); PG8_LDB(B1, 0, 1); PG8_SCHED; PG8_LDA(At, 0, 0); PG8_STAGE(PG8_SA(1, 1), a1 + hstep, voffA);
;             PG8_WAIT_V(8); PG8_WAIT_L(0); PG8_BAR; PG8_MMA(0, 0, At, B0); PG8_MMA(0, 1, At, B1); PG8_BAR; PG8_SCHED;
;             PG8_LDA(At, 0, 1); PG8_STAGE(PG8_SB(0, 0), b2, voffB); PG8_STAGE(PG8_SB(0, 1), b2 + hstep, voffB); PG8_STAGE(PG8_SA(0, 0), a2, voffA);
;             PG8_WAIT_V(8); PG8_WAIT_L(0); PG8_BAR; PG8_MMA(1, 0, At, B0); PG8_MMA(1, 1, At, B1); PG8_BAR; PG8_SCHED;
;             PG8_LDB(B0, 1, 0); PG8_LDB(B1, 1, 1); PG8_SCHED; PG8_LDA(At, 1, 0); PG8_STAGE(PG8_SA(0, 1), a2 + hstep, voffA);
;             PG8_WAIT_V(8); PG8_WAIT_L(0); PG8_BAR; PG8_MMA(0, 0, At, B0); PG8_MMA(0, 1, At, B1); PG8_BAR; PG8_SCHED;
;             PG8_LDA(At, 1, 1); PG8_STAGE(PG8_SB(1, 0), b3, voffB); PG8_STAGE(PG8_SB(1, 1), b3 + hstep, voffB); PG8_STAGE(PG8_SA(1, 0), a3, voffA);
;             PG8_WAIT_V(8); PG8_WAIT_L(0); PG8_BAR; PG8_MMA(1, 0, At, B0); PG8_MMA(1, 1, At, B1); PG8_BAR; PG8_SCHED;
	s_setprio 1
	s_waitcnt lgkmcnt(0)
	v_mfma_f32_16x16x32_bf16 v[158:161], v[98:101], v[162:165], v[158:161]
	v_mfma_f32_16x16x32_bf16 v[154:157], v[122:125], v[162:165], v[154:157]
	v_mfma_f32_16x16x32_bf16 v[118:121], v[98:101], v[170:173], v[118:121]
	v_mfma_f32_16x16x32_bf16 v[114:117], v[122:125], v[170:173], v[114:117]
	v_mfma_f32_16x16x32_bf16 v[94:97], v[98:101], v[178:181], v[94:97]
	v_mfma_f32_16x16x32_bf16 v[90:93], v[122:125], v[178:181], v[90:93]
	v_mfma_f32_16x16x32_bf16 v[78:81], v[98:101], v[186:189], v[78:81]
	v_mfma_f32_16x16x32_bf16 v[74:77], v[122:125], v[186:189], v[74:77]
	v_mfma_f32_16x16x32_bf16 v[158:161], v[110:113], v[166:169], v[158:161]
	v_mfma_f32_16x16x32_bf16 v[154:157], v[134:137], v[166:169], v[154:157]
	v_mfma_f32_16x16x32_bf16 v[118:121], v[110:113], v[174:177], v[118:121]
	v_mfma_f32_16x16x32_bf16 v[114:117], v[134:137], v[174:177], v[114:117]
	v_mfma_f32_16x16x32_bf16 v[94:97], v[110:113], v[182:185], v[94:97]
	v_mfma_f32_16x16x32_bf16 v[90:93], v[134:137], v[182:185], v[90:93]
	v_mfma_f32_16x16x32_bf16 v[78:81], v[110:113], v[204:207], v[78:81]
	v_mfma_f32_16x16x32_bf16 v[74:77], v[134:137], v[204:207], v[74:77]
	s_setprio 0
	s_setprio 1
	v_mfma_f32_16x16x32_bf16 v[130:133], v[138:141], v[162:165], v[130:133]
	v_mfma_f32_16x16x32_bf16 v[126:129], v[146:149], v[162:165], v[126:129]
	v_mfma_f32_16x16x32_bf16 v[106:109], v[138:141], v[170:173], v[106:109]
	v_mfma_f32_16x16x32_bf16 v[102:105], v[146:149], v[170:173], v[102:105]
	v_mfma_f32_16x16x32_bf16 v[86:89], v[138:141], v[178:181], v[86:89]
	v_mfma_f32_16x16x32_bf16 v[82:85], v[146:149], v[178:181], v[82:85]
	v_mfma_f32_16x16x32_bf16 v[70:73], v[138:141], v[186:189], v[70:73]
	v_mfma_f32_16x16x32_bf16 v[66:69], v[146:149], v[186:189], v[66:69]
	v_mfma_f32_16x16x32_bf16 v[130:133], v[142:145], v[166:169], v[130:133]
	v_mfma_f32_16x16x32_bf16 v[126:129], v[150:153], v[166:169], v[126:129]
	v_mfma_f32_16x16x32_bf16 v[106:109], v[142:145], v[174:177], v[106:109]
	v_mfma_f32_16x16x32_bf16 v[102:105], v[150:153], v[174:177], v[102:105]
	v_mfma_f32_16x16x32_bf16 v[86:89], v[142:145], v[182:185], v[86:89]
	v_mfma_f32_16x16x32_bf16 v[82:85], v[150:153], v[182:185], v[82:85]
	v_mfma_f32_16x16x32_bf16 v[70:73], v[142:145], v[204:207], v[70:73]
	s_setprio 3
	s_barrier
	v_mfma_f32_16x16x32_bf16 v[66:69], v[150:153], v[204:207], v[66:69]
	s_setprio 0
	s_add_i32 s18, s56, s44
	s_mov_b32 m0, s18
	ds_read_b128 v[162:165], v241 offset:16384
	ds_read_b128 v[166:169], v241 offset:17408
	ds_read_b128 v[170:173], v241 offset:18432
	ds_read_b128 v[174:177], v241 offset:19456
	ds_read_b128 v[178:181], v241 offset:20480
	ds_read_b128 v[182:185], v241 offset:21504
	ds_read_b128 v[186:189], v241 offset:22528
	ds_read_b128 v[204:207], v241 offset:23552
	s_add_i32 m0, s18, 0x2000
	s_add_u32 s18, s30, 0x40000
	s_addc_u32 s19, s31, 0
	s_add_i32 s63, s57, s44
	s_mov_b32 m0, s63
	s_add_i32 m0, s63, 0x2000
	s_nop 0
	s_mov_b32 m0, s45
	s_nop 0
	s_mov_b32 m0, s46
	s_nop 0
	s_waitcnt vmcnt(12)
	s_waitcnt lgkmcnt(0)
	s_barrier
	s_setprio 1
	s_waitcnt lgkmcnt(0)
	v_mfma_f32_16x16x32_bf16 v[62:65], v[98:101], v[162:165], v[62:65]
	v_mfma_f32_16x16x32_bf16 v[58:61], v[122:125], v[162:165], v[58:61]
	v_mfma_f32_16x16x32_bf16 v[46:49], v[98:101], v[170:173], v[46:49]
	v_mfma_f32_16x16x32_bf16 v[42:45], v[122:125], v[170:173], v[42:45]
	v_mfma_f32_16x16x32_bf16 v[30:33], v[98:101], v[178:181], v[30:33]
	v_mfma_f32_16x16x32_bf16 v[26:29], v[122:125], v[178:181], v[26:29]
	v_mfma_f32_16x16x32_bf16 v[14:17], v[98:101], v[186:189], v[14:17]
	v_mfma_f32_16x16x32_bf16 v[10:13], v[122:125], v[186:189], v[10:13]
	v_mfma_f32_16x16x32_bf16 v[62:65], v[110:113], v[166:169], v[62:65]
	v_mfma_f32_16x16x32_bf16 v[58:61], v[134:137], v[166:169], v[58:61]
	v_mfma_f32_16x16x32_bf16 v[46:49], v[110:113], v[174:177], v[46:49]
	v_mfma_f32_16x16x32_bf16 v[42:45], v[134:137], v[174:177], v[42:45]
	v_mfma_f32_16x16x32_bf16 v[30:33], v[110:113], v[182:185], v[30:33]
	v_mfma_f32_16x16x32_bf16 v[26:29], v[134:137], v[182:185], v[26:29]
	v_mfma_f32_16x16x32_bf16 v[14:17], v[110:113], v[204:207], v[14:17]
	v_mfma_f32_16x16x32_bf16 v[10:13], v[134:137], v[204:207], v[10:13]
	s_setprio 0
	s_setprio 1
	v_mfma_f32_16x16x32_bf16 v[54:57], v[138:141], v[162:165], v[54:57]
	v_mfma_f32_16x16x32_bf16 v[50:53], v[146:149], v[162:165], v[50:53]
	v_mfma_f32_16x16x32_bf16 v[38:41], v[138:141], v[170:173], v[38:41]
	v_mfma_f32_16x16x32_bf16 v[34:37], v[146:149], v[170:173], v[34:37]
	v_mfma_f32_16x16x32_bf16 v[22:25], v[138:141], v[178:181], v[22:25]
	v_mfma_f32_16x16x32_bf16 v[18:21], v[146:149], v[178:181], v[18:21]
	v_mfma_f32_16x16x32_bf16 v[6:9], v[138:141], v[186:189], v[6:9]
	v_mfma_f32_16x16x32_bf16 v[2:5], v[146:149], v[186:189], v[2:5]
	v_mfma_f32_16x16x32_bf16 v[54:57], v[142:145], v[166:169], v[54:57]
	v_mfma_f32_16x16x32_bf16 v[50:53], v[150:153], v[166:169], v[50:53]
	v_mfma_f32_16x16x32_bf16 v[38:41], v[142:145], v[174:177], v[38:41]
	v_mfma_f32_16x16x32_bf16 v[34:37], v[150:153], v[174:177], v[34:37]
	v_mfma_f32_16x16x32_bf16 v[22:25], v[142:145], v[182:185], v[22:25]
	v_mfma_f32_16x16x32_bf16 v[18:21], v[150:153], v[182:185], v[18:21]
	v_mfma_f32_16x16x32_bf16 v[6:9], v[142:145], v[204:207], v[6:9]
	s_setprio 3
	s_barrier
; #define PG8_STAGE(bufoff, gbase, voff) do { _Pragma("unroll") for (int _i = 0; _i < 2; ++_i) \
;         __builtin_amdgcn_global_load_lds((const unsigned*)((const char*)(gbase) + (voff)[_i]), (PG8_LAS unsigned*)(lds + (bufoff) + ldsw + _i * 8192), 16, 0, 0); } while (0)
; #define PG8_LDA(dst, b, h) do { _Pragma("unroll") for (int m = 0; m < 4; ++m) _Pragma("unroll") for (int k = 0; k < 2; ++k) dst[m][k] = *(const PG8_LAS bf16x8*)(lds + PG8_SA(b, h) + aoff + m * 2048 + k * 1024); } while (0)
; #define PG8_LDB(dst, b, h) do { _Pragma("unroll") for (int n = 0; n < 2; ++n) _Pragma("unroll") for (int k = 0; k < 2; ++k) dst[n][k] = *(const PG8_LAS bf16x8*)(lds + PG8_SB(b, h) + boff + n * 2048 + k * 1024); } while (0)
; #define PG8_MMA(ai, bj, At, Bt) do { __builtin_amdgcn_s_setprio(1); _Pragma("unroll") for (int m = 0; m < 4; ++m) _Pragma("unroll") for (int n = 0; n < 2; ++n) _Pragma("unroll") for (int k = 0; k < 2; ++k) \
;         acc[ai][bj][m][n] = __builtin_amdgcn_mfma_f32_16x16x32_bf16(Bt[n][k], At[m][k], acc[ai][bj][m][n], 0, 0, 0); __builtin_amdgcn_s_setprio(0); } while (0)
; #define PG8_WAIT_V(n) asm volatile("s_waitcnt vmcnt(" #n ")" ::: "memory")
; template <class Epi, class Sched, bool ALIGN_EPI = false, bool SP2 = false>
; __device__ __forceinline__ void gemm_phase(PG8_LAS unsigned char* lds, const Gemm g, const Sched& S, const Epi& E) {
;     ...
;             PG8_LDB(B0, 0, 0); PG8_LDB(B1, 0, 1); PG8_SCHED; PG8_LDA(At, 0, 0); PG8_STAGE(PG8_SA(1, 1), a1 + hstep, voffA);
;             PG8_WAIT_V(8); PG8_WAIT_L(0); PG8_BAR; PG8_MMA(0, 0, At, B0); PG8_MMA(0, 1, At, B1); PG8_BAR; PG8_SCHED;
;             PG8_LDA(At, 0, 1); PG8_STAGE(PG8_SB(0, 0), b2, voffB); PG8_STAGE(PG8_SB(0, 1), b2 + hstep, voffB); PG8_STAGE(PG8_SA(0, 0), a2, voffA);
;             PG8_WAIT_V(8); PG8_WAIT_L(0); PG8_BAR; PG8_MMA(1, 0, At, B0); PG8_MMA(1, 1, At, B1); PG8_BAR; PG8_SCHED;
;             PG8_LDB(B0, 1, 0); PG8_LDB(B1, 1, 1); PG8_SCHED; PG8_LDA(At, 1, 0); PG8_STAGE(PG8_SA(0, 1), a2 + hstep, voffA);
;             PG8_WAIT_V(8); PG8_WAIT_L(0); PG8_BAR; PG8_MMA(0, 0, At, B0); PG8_MMA(0, 1, At, B1); PG8_BAR; PG8_SCHED;
;             PG8_LDA(At, 1, 1); PG8_STAGE(PG8_SB(1, 0), b3, voffB); PG8_STAGE(PG8_SB(1, 1), b3 + hstep, voffB); PG8_STAGE(PG8_SA(1, 0), a3, voffA);
;             PG8_WAIT_V(8); PG8_WAIT_L(0); PG8_BAR; PG8_MMA(1, 0, At, B0); PG8_MMA(1, 1, At, B1); PG8_BAR; PG8_SCHED;
	v_mfma_f32_16x16x32_bf16 v[2:5], v[150:153], v[204:207], v[2:5]
	s_setprio 0
	s_add_i32 s63, 0, 0x18000
	s_add_i32 s64, 0, 0x1c000
	v_add_u32_e32 v134, s63, v237
	v_add_u32_e32 v150, s64, v237
	ds_read_b128 v[98:101], v134
	ds_read_b128 v[110:113], v134 offset:1024
	ds_read_b128 v[122:125], v134 offset:2048
	ds_read_b128 v[134:137], v134 offset:3072
	ds_read_b128 v[138:141], v150
	ds_read_b128 v[142:145], v150 offset:1024
	ds_read_b128 v[146:149], v150 offset:2048
	ds_read_b128 v[150:153], v150 offset:3072
	s_add_u32 s18, s42, 0x40000
	s_addc_u32 s19, s43, 0
	s_mov_b32 m0, s47
	ds_read_b128 v[162:165], v241 offset:32768
	ds_read_b128 v[166:169], v241 offset:33792
	ds_read_b128 v[170:173], v241 offset:34816
	ds_read_b128 v[174:177], v241 offset:35840
	ds_read_b128 v[178:181], v241 offset:36864
	ds_read_b128 v[182:185], v241 offset:37888
	ds_read_b128 v[186:189], v241 offset:38912
	ds_read_b128 v[204:207], v241 offset:39936
	s_mov_b32 m0, s48
	s_nop 0
	s_waitcnt vmcnt(10)
	s_waitcnt lgkmcnt(0)
	s_barrier
	s_setprio 1
	s_waitcnt lgkmcnt(0)
	v_mfma_f32_16x16x32_bf16 v[158:161], v[98:101], v[162:165], v[158:161]
	v_mfma_f32_16x16x32_bf16 v[154:157], v[122:125], v[162:165], v[154:157]
	v_mfma_f32_16x16x32_bf16 v[118:121], v[98:101], v[170:173], v[118:121]
	v_mfma_f32_16x16x32_bf16 v[114:117], v[122:125], v[170:173], v[114:117]
	v_mfma_f32_16x16x32_bf16 v[94:97], v[98:101], v[178:181], v[94:97]
	v_mfma_f32_16x16x32_bf16 v[90:93], v[122:125], v[178:181], v[90:93]
	v_mfma_f32_16x16x32_bf16 v[78:81], v[98:101], v[186:189], v[78:81]
	v_mfma_f32_16x16x32_bf16 v[74:77], v[122:125], v[186:189], v[74:77]
	v_mfma_f32_16x16x32_bf16 v[158:161], v[110:113], v[166:169], v[158:161]
	v_mfma_f32_16x16x32_bf16 v[154:157], v[134:137], v[166:169], v[154:157]
	v_mfma_f32_16x16x32_bf16 v[118:121], v[110:113], v[174:177], v[118:121]
	v_mfma_f32_16x16x32_bf16 v[114:117], v[134:137], v[174:177], v[114:117]
	v_mfma_f32_16x16x32_bf16 v[94:97], v[110:113], v[182:185], v[94:97]
	v_mfma_f32_16x16x32_bf16 v[90:93], v[134:137], v[182:185], v[90:93]
	v_mfma_f32_16x16x32_bf16 v[78:81], v[110:113], v[204:207], v[78:81]
	v_mfma_f32_16x16x32_bf16 v[74:77], v[134:137], v[204:207], v[74:77]
	s_setprio 0
	s_setprio 1
	v_mfma_f32_16x16x32_bf16 v[130:133], v[138:141], v[162:165], v[130:133]
	v_mfma_f32_16x16x32_bf16 v[126:129], v[146:149], v[162:165], v[126:129]
	v_mfma_f32_16x16x32_bf16 v[106:109], v[138:141], v[170:173], v[106:109]
	v_mfma_f32_16x16x32_bf16 v[102:105], v[146:149], v[170:173], v[102:105]
	v_mfma_f32_16x16x32_bf16 v[86:89], v[138:141], v[178:181], v[86:89]
	v_mfma_f32_16x16x32_bf16 v[82:85], v[146:149], v[178:181], v[82:85]
	v_mfma_f32_16x16x32_bf16 v[70:73], v[138:141], v[186:189], v[70:73]
	v_mfma_f32_16x16x32_bf16 v[66:69], v[146:149], v[186:189], v[66:69]
	v_mfma_f32_16x16x32_bf16 v[130:133], v[142:145], v[166:169], v[130:133]
	v_mfma_f32_16x16x32_bf16 v[126:129], v[150:153], v[166:169], v[126:129]
	v_mfma_f32_16x16x32_bf16 v[106:109], v[142:145], v[174:177], v[106:109]
	v_mfma_f32_16x16x32_bf16 v[102:105], v[150:153], v[174:177], v[102:105]
	v_mfma_f32_16x16x32_bf16 v[86:89], v[142:145], v[182:185], v[86:89]
	v_mfma_f32_16x16x32_bf16 v[82:85], v[150:153], v[182:185], v[82:85]
	v_mfma_f32_16x16x32_bf16 v[70:73], v[142:145], v[204:207], v[70:73]
	s_setprio 3
	s_barrier
	v_mfma_f32_16x16x32_bf16 v[66:69], v[150:153], v[204:207], v[66:69]
	s_setprio 0
	s_add_i32 s18, s63, s44
	s_mov_b32 m0, s18
	ds_read_b128 v[162:165], v241 offset:49152
	ds_read_b128 v[166:169], v241 offset:50176
	ds_read_b128 v[170:173], v241 offset:51200
	ds_read_b128 v[174:177], v241 offset:52224
	ds_read_b128 v[178:181], v241 offset:53248
	ds_read_b128 v[182:185], v241 offset:54272
	ds_read_b128 v[186:189], v241 offset:55296
	ds_read_b128 v[204:207], v241 offset:56320
	s_add_i32 m0, s18, 0x2000
	s_add_u32 s18, s30, 0x40080
	s_addc_u32 s19, s31, 0
	s_add_i32 s30, s64, s44
	s_mov_b32 m0, s30
	s_nop 0
	s_add_i32 m0, s30, 0x2000
	s_nop 0
	s_mov_b32 m0, s52
	s_nop 0
	s_mov_b32 m0, s53
	s_nop 0
	s_waitcnt vmcnt(10)
	s_waitcnt lgkmcnt(0)
	s_barrier
	s_setprio 1
	s_waitcnt lgkmcnt(0)
	v_mfma_f32_16x16x32_bf16 v[62:65], v[98:101], v[162:165], v[62:65]
	v_mfma_f32_16x16x32_bf16 v[58:61], v[122:125], v[162:165], v[58:61]
	v_mfma_f32_16x16x32_bf16 v[46:49], v[98:101], v[170:173], v[46:49]
	v_mfma_f32_16x16x32_bf16 v[42:45], v[122:125], v[170:173], v[42:45]
	v_mfma_f32_16x16x32_bf16 v[30:33], v[98:101], v[178:181], v[30:33]
	v_mfma_f32_16x16x32_bf16 v[26:29], v[122:125], v[178:181], v[26:29]
	v_mfma_f32_16x16x32_bf16 v[14:17], v[98:101], v[186:189], v[14:17]
	v_mfma_f32_16x16x32_bf16 v[10:13], v[122:125], v[186:189], v[10:13]
	v_mfma_f32_16x16x32_bf16 v[62:65], v[110:113], v[166:169], v[62:65]
	v_mfma_f32_16x16x32_bf16 v[58:61], v[134:137], v[166:169], v[58:61]
	v_mfma_f32_16x16x32_bf16 v[46:49], v[110:113], v[174:177], v[46:49]
	v_mfma_f32_16x16x32_bf16 v[42:45], v[134:137], v[174:177], v[42:45]
	v_mfma_f32_16x16x32_bf16 v[30:33], v[110:113], v[182:185], v[30:33]
	v_mfma_f32_16x16x32_bf16 v[26:29], v[134:137], v[182:185], v[26:29]
	v_mfma_f32_16x16x32_bf16 v[14:17], v[110:113], v[204:207], v[14:17]
	v_mfma_f32_16x16x32_bf16 v[10:13], v[134:137], v[204:207], v[10:13]
	s_setprio 0
	s_setprio 1
	v_mfma_f32_16x16x32_bf16 v[54:57], v[138:141], v[162:165], v[54:57]
	v_mfma_f32_16x16x32_bf16 v[50:53], v[146:149], v[162:165], v[50:53]
	v_mfma_f32_16x16x32_bf16 v[38:41], v[138:141], v[170:173], v[38:41]
	v_mfma_f32_16x16x32_bf16 v[34:37], v[146:149], v[170:173], v[34:37]
	v_mfma_f32_16x16x32_bf16 v[22:25], v[138:141], v[178:181], v[22:25]
	v_mfma_f32_16x16x32_bf16 v[18:21], v[146:149], v[178:181], v[18:21]
	v_mfma_f32_16x16x32_bf16 v[6:9], v[138:141], v[186:189], v[6:9]
	v_mfma_f32_16x16x32_bf16 v[2:5], v[146:149], v[186:189], v[2:5]
	v_mfma_f32_16x16x32_bf16 v[54:57], v[142:145], v[166:169], v[54:57]
	v_mfma_f32_16x16x32_bf16 v[50:53], v[150:153], v[166:169], v[50:53]
	v_mfma_f32_16x16x32_bf16 v[38:41], v[142:145], v[174:177], v[38:41]
	v_mfma_f32_16x16x32_bf16 v[34:37], v[150:153], v[174:177], v[34:37]
	v_mfma_f32_16x16x32_bf16 v[22:25], v[142:145], v[182:185], v[22:25]
	v_mfma_f32_16x16x32_bf16 v[18:21], v[150:153], v[182:185], v[18:21]
	v_mfma_f32_16x16x32_bf16 v[6:9], v[142:145], v[204:207], v[6:9]
	s_setprio 3
	s_barrier
	v_mfma_f32_16x16x32_bf16 v[2:5], v[150:153], v[204:207], v[2:5]
	s_setprio 0
	s_add_i32 s62, s62, 2
	s_add_u32 s40, s40, 0x100
	s_addc_u32 s41, s41, 0
	s_add_u32 s60, s60, 0x100
	s_addc_u32 s61, s61, 0
	s_branch .Lrp_done_p3

; #define PG8_STAGE(bufoff, gbase, voff) do { _Pragma("unroll") for (int _i = 0; _i < 2; ++_i) \
;         __builtin_amdgcn_global_load_lds((const unsigned*)((const char*)(gbase) + (voff)[_i]), (PG8_LAS unsigned*)(lds + (bufoff) + ldsw + _i * 8192), 16, 0, 0); } while (0)
; #define PG8_LDA(dst, b, h) do { _Pragma("unroll") for (int m = 0; m < 4; ++m) _Pragma("unroll") for (int k = 0; k < 2; ++k) dst[m][k] = *(const PG8_LAS bf16x8*)(lds + PG8_SA(b, h) + aoff + m * 2048 + k * 1024); } while (0)
; #define PG8_LDB(dst, b, h) do { _Pragma("unroll") for (int n = 0; n < 2; ++n) _Pragma("unroll") for (int k = 0; k < 2; ++k) dst[n][k] = *(const PG8_LAS bf16x8*)(lds + PG8_SB(b, h) + boff + n * 2048 + k * 1024); } while (0)
; #define PG8_MMA(ai, bj, At, Bt) do { __builtin_amdgcn_s_setprio(1); _Pragma("unroll") for (int m = 0; m < 4; ++m) _Pragma("unroll") for (int n = 0; n < 2; ++n) _Pragma("unroll") for (int k = 0; k < 2; ++k) \
;         acc[ai][bj][m][n] = __builtin_amdgcn_mfma_f32_16x16x32_bf16(Bt[n][k], At[m][k], acc[ai][bj][m][n], 0, 0, 0); __builtin_amdgcn_s_setprio(0); } while (0)
; #define PG8_WAIT_V(n) asm volatile("s_waitcnt vmcnt(" #n ")" ::: "memory")
; template <class Epi, class Sched, bool ALIGN_EPI = false, bool SP2 = false>
; __device__ __forceinline__ void gemm_phase(PG8_LAS unsigned char* lds, const Gemm g, const Sched& S, const Epi& E) {
;     ...
;             PG8_LDB(B0, 0, 0); PG8_LDB(B1, 0, 1); PG8_SCHED; PG8_LDA(At, 0, 0); PG8_STAGE(PG8_SA(1, 1), a1 + hstep, voffA);
;             PG8_WAIT_V(8); PG8_WAIT_L(0); PG8_BAR; PG8_MMA(0, 0, At, B0); PG8_MMA(0, 1, At, B1); PG8_BAR; PG8_SCHED;
;             PG8_LDA(At, 0, 1); PG8_STAGE(PG8_SB(0, 0), b2, voffB); PG8_STAGE(PG8_SB(0, 1), b2 + hstep, voffB); PG8_STAGE(PG8_SA(0, 0), a2, voffA);
;             PG8_WAIT_V(8); PG8_WAIT_L(0); PG8_BAR; PG8_MMA(1, 0, At, B0); PG8_MMA(1, 1, At, B1); PG8_BAR; PG8_SCHED;
;             PG8_LDB(B0, 1, 0); PG8_LDB(B1, 1, 1); PG8_SCHED; PG8_LDA(At, 1, 0); PG8_STAGE(PG8_SA(0, 1), a2 + hstep, voffA);
;             PG8_WAIT_V(8); PG8_WAIT_L(0); PG8_BAR; PG8_MMA(0, 0, At, B0); PG8_MMA(0, 1, At, B1); PG8_BAR; PG8_SCHED;
;             PG8_LDA(At, 1, 1); PG8_STAGE(PG8_SB(1, 0), b3, voffB); PG8_STAGE(PG8_SB(1, 1), b3 + hstep, voffB); PG8_STAGE(PG8_SA(1, 0), a3, voffA);
;             PG8_WAIT_V(8); PG8_WAIT_L(0); PG8_BAR; PG8_MMA(1, 0, At, B0); PG8_MMA(1, 1, At, B1); PG8_BAR; PG8_SCHED;
.LBB0_738:
	ds_read_b128 v[148:151], v195
	ds_read_b128 v[152:155], v195 offset:1024
	ds_read_b128 v[156:159], v195 offset:2048
	ds_read_b128 v[160:163], v195 offset:3072
	ds_read_b128 v[164:167], v196
	ds_read_b128 v[168:171], v196 offset:1024
	ds_read_b128 v[172:175], v196 offset:2048
	ds_read_b128 v[198:201], v196 offset:3072
	s_add_u32 s6, s4, 0xfffc0080
	s_addc_u32 s7, s5, -1
	s_cmp_eq_u32 s66, 12
	s_cselect_b32 s31, s1, s7
	s_cselect_b32 s30, s41, s6
	s_cselect_b32 s7, s39, s47
	s_cselect_b32 s6, s65, s46
	v_lshl_add_u64 v[176:177], s[4:5], 0, v[140:141]
	s_add_i32 m0, s49, 0xc000
	ds_read_b128 v[202:205], v197
	ds_read_b128 v[206:209], v197 offset:1024
	ds_read_b128 v[210:213], v197 offset:2048
	ds_read_b128 v[214:217], v197 offset:3072
	ds_read_b128 v[218:221], v197 offset:4096
	ds_read_b128 v[222:225], v197 offset:5120
	ds_read_b128 v[226:229], v197 offset:6144
	ds_read_b128 v[230:233], v197 offset:7168
	global_load_lds_dwordx4 v[176:177], off
	v_lshl_add_u64 v[176:177], s[4:5], 0, v[142:143]
	s_add_i32 m0, s49, 0xe000
	s_nop 0
	global_load_lds_dwordx4 v[176:177], off
	s_waitcnt vmcnt(8)
	s_waitcnt lgkmcnt(0)
	s_barrier
	s_setprio 1
	s_waitcnt lgkmcnt(0)
	v_mfma_f32_16x16x32_bf16 v[126:129], v[148:151], v[202:205], v[126:129]
	v_mfma_f32_16x16x32_bf16 v[118:121], v[156:159], v[202:205], v[118:121]
	v_mfma_f32_16x16x32_bf16 v[110:113], v[148:151], v[210:213], v[110:113]
	v_mfma_f32_16x16x32_bf16 v[102:105], v[156:159], v[210:213], v[102:105]
	v_mfma_f32_16x16x32_bf16 v[94:97], v[148:151], v[218:221], v[94:97]
	v_mfma_f32_16x16x32_bf16 v[86:89], v[156:159], v[218:221], v[86:89]
	v_mfma_f32_16x16x32_bf16 v[78:81], v[148:151], v[226:229], v[78:81]
	v_mfma_f32_16x16x32_bf16 v[70:73], v[156:159], v[226:229], v[70:73]
	v_mfma_f32_16x16x32_bf16 v[126:129], v[152:155], v[206:209], v[126:129]
	v_mfma_f32_16x16x32_bf16 v[118:121], v[160:163], v[206:209], v[118:121]
	v_mfma_f32_16x16x32_bf16 v[110:113], v[152:155], v[214:217], v[110:113]
	v_mfma_f32_16x16x32_bf16 v[102:105], v[160:163], v[214:217], v[102:105]
	v_mfma_f32_16x16x32_bf16 v[94:97], v[152:155], v[222:225], v[94:97]
	v_mfma_f32_16x16x32_bf16 v[86:89], v[160:163], v[222:225], v[86:89]
	v_mfma_f32_16x16x32_bf16 v[78:81], v[152:155], v[230:233], v[78:81]
	v_mfma_f32_16x16x32_bf16 v[70:73], v[160:163], v[230:233], v[70:73]
	s_setprio 0
	s_setprio 1
	v_mfma_f32_16x16x32_bf16 v[122:125], v[164:167], v[202:205], v[122:125]
	v_mfma_f32_16x16x32_bf16 v[114:117], v[172:175], v[202:205], v[114:117]
	v_mfma_f32_16x16x32_bf16 v[106:109], v[164:167], v[210:213], v[106:109]
	v_mfma_f32_16x16x32_bf16 v[98:101], v[172:175], v[210:213], v[98:101]
	v_mfma_f32_16x16x32_bf16 v[90:93], v[164:167], v[218:221], v[90:93]
	v_mfma_f32_16x16x32_bf16 v[82:85], v[172:175], v[218:221], v[82:85]
	v_mfma_f32_16x16x32_bf16 v[74:77], v[164:167], v[226:229], v[74:77]
	v_mfma_f32_16x16x32_bf16 v[66:69], v[172:175], v[226:229], v[66:69]
	v_mfma_f32_16x16x32_bf16 v[122:125], v[168:171], v[206:209], v[122:125]
	v_mfma_f32_16x16x32_bf16 v[114:117], v[198:201], v[206:209], v[114:117]
	v_mfma_f32_16x16x32_bf16 v[106:109], v[168:171], v[214:217], v[106:109]
	v_mfma_f32_16x16x32_bf16 v[98:101], v[198:201], v[214:217], v[98:101]
	v_mfma_f32_16x16x32_bf16 v[90:93], v[168:171], v[222:225], v[90:93]
	v_mfma_f32_16x16x32_bf16 v[82:85], v[198:201], v[222:225], v[82:85]
	v_mfma_f32_16x16x32_bf16 v[74:77], v[168:171], v[230:233], v[74:77]
	s_setprio 3
	s_barrier
	v_mfma_f32_16x16x32_bf16 v[66:69], v[198:201], v[230:233], v[66:69]
	s_setprio 0
	s_add_i32 s18, s59, s25
	v_lshl_add_u64 v[176:177], s[6:7], 0, v[134:135]
	s_mov_b32 m0, s18
	ds_read_b128 v[202:205], v197 offset:16384
	ds_read_b128 v[206:209], v197 offset:17408
	ds_read_b128 v[210:213], v197 offset:18432
	ds_read_b128 v[214:217], v197 offset:19456
	ds_read_b128 v[218:221], v197 offset:20480
	ds_read_b128 v[222:225], v197 offset:21504
	ds_read_b128 v[226:229], v197 offset:22528
	ds_read_b128 v[230:233], v197 offset:23552
	global_load_lds_dwordx4 v[176:177], off
	s_add_i32 m0, s18, 0x2000
	s_add_u32 s18, s6, 0x40000
	v_lshl_add_u64 v[234:235], s[6:7], 0, v[130:131]
	s_addc_u32 s19, s7, 0
	s_add_i32 s67, s60, s25
	global_load_lds_dwordx4 v[234:235], off
	v_lshl_add_u64 v[238:239], s[18:19], 0, v[134:135]
	s_mov_b32 m0, s67
	v_lshl_add_u64 v[240:241], s[30:31], 0, v[132:133]
	global_load_lds_dwordx4 v[238:239], off
	v_lshl_add_u64 v[238:239], s[18:19], 0, v[130:131]
	s_add_i32 m0, s67, 0x2000
	s_nop 0
	global_load_lds_dwordx4 v[238:239], off
	v_lshl_add_u64 v[238:239], s[30:31], 0, v[136:137]
	s_mov_b32 m0, s49
	s_nop 0
	global_load_lds_dwordx4 v[238:239], off
	s_mov_b32 m0, s52
	s_nop 0
	global_load_lds_dwordx4 v[240:241], off
	s_waitcnt vmcnt(8)
	s_waitcnt lgkmcnt(0)
	s_barrier
; #define PG8_STAGE(bufoff, gbase, voff) do { _Pragma("unroll") for (int _i = 0; _i < 2; ++_i) \
;         __builtin_amdgcn_global_load_lds((const unsigned*)((const char*)(gbase) + (voff)[_i]), (PG8_LAS unsigned*)(lds + (bufoff) + ldsw + _i * 8192), 16, 0, 0); } while (0)
; #define PG8_LDA(dst, b, h) do { _Pragma("unroll") for (int m = 0; m < 4; ++m) _Pragma("unroll") for (int k = 0; k < 2; ++k) dst[m][k] = *(const PG8_LAS bf16x8*)(lds + PG8_SA(b, h) + aoff + m * 2048 + k * 1024); } while (0)
; #define PG8_LDB(dst, b, h) do { _Pragma("unroll") for (int n = 0; n < 2; ++n) _Pragma("unroll") for (int k = 0; k < 2; ++k) dst[n][k] = *(const PG8_LAS bf16x8*)(lds + PG8_SB(b, h) + boff + n * 2048 + k * 1024); } while (0)
; #define PG8_MMA(ai, bj, At, Bt) do { __builtin_amdgcn_s_setprio(1); _Pragma("unroll") for (int m = 0; m < 4; ++m) _Pragma("unroll") for (int n = 0; n < 2; ++n) _Pragma("unroll") for (int k = 0; k < 2; ++k) \
;         acc[ai][bj][m][n] = __builtin_amdgcn_mfma_f32_16x16x32_bf16(Bt[n][k], At[m][k], acc[ai][bj][m][n], 0, 0, 0); __builtin_amdgcn_s_setprio(0); } while (0)
; #define PG8_WAIT_V(n) asm volatile("s_waitcnt vmcnt(" #n ")" ::: "memory")
; template <class Epi, class Sched, bool ALIGN_EPI = false, bool SP2 = false>
; __device__ __forceinline__ void gemm_phase(PG8_LAS unsigned char* lds, const Gemm g, const Sched& S, const Epi& E) {
;     ...
;             PG8_LDB(B0, 0, 0); PG8_LDB(B1, 0, 1); PG8_SCHED; PG8_LDA(At, 0, 0); PG8_STAGE(PG8_SA(1, 1), a1 + hstep, voffA);
;             PG8_WAIT_V(8); PG8_WAIT_L(0); PG8_BAR; PG8_MMA(0, 0, At, B0); PG8_MMA(0, 1, At, B1); PG8_BAR; PG8_SCHED;
;             PG8_LDA(At, 0, 1); PG8_STAGE(PG8_SB(0, 0), b2, voffB); PG8_STAGE(PG8_SB(0, 1), b2 + hstep, voffB); PG8_STAGE(PG8_SA(0, 0), a2, voffA);
;             PG8_WAIT_V(8); PG8_WAIT_L(0); PG8_BAR; PG8_MMA(1, 0, At, B0); PG8_MMA(1, 1, At, B1); PG8_BAR; PG8_SCHED;
;             PG8_LDB(B0, 1, 0); PG8_LDB(B1, 1, 1); PG8_SCHED; PG8_LDA(At, 1, 0); PG8_STAGE(PG8_SA(0, 1), a2 + hstep, voffA);
;             PG8_WAIT_V(8); PG8_WAIT_L(0); PG8_BAR; PG8_MMA(0, 0, At, B0); PG8_MMA(0, 1, At, B1); PG8_BAR; PG8_SCHED;
;             PG8_LDA(At, 1, 1); PG8_STAGE(PG8_SB(1, 0), b3, voffB); PG8_STAGE(PG8_SB(1, 1), b3 + hstep, voffB); PG8_STAGE(PG8_SA(1, 0), a3, voffA);
;             PG8_WAIT_V(8); PG8_WAIT_L(0); PG8_BAR; PG8_MMA(1, 0, At, B0); PG8_MMA(1, 1, At, B1); PG8_BAR; PG8_SCHED;
	s_setprio 1
	s_waitcnt lgkmcnt(0)
	v_mfma_f32_16x16x32_bf16 v[62:65], v[148:151], v[202:205], v[62:65]
	v_mfma_f32_16x16x32_bf16 v[54:57], v[156:159], v[202:205], v[54:57]
	v_mfma_f32_16x16x32_bf16 v[46:49], v[148:151], v[210:213], v[46:49]
	v_mfma_f32_16x16x32_bf16 v[38:41], v[156:159], v[210:213], v[38:41]
	v_mfma_f32_16x16x32_bf16 v[30:33], v[148:151], v[218:221], v[30:33]
	v_mfma_f32_16x16x32_bf16 v[22:25], v[156:159], v[218:221], v[22:25]
	v_mfma_f32_16x16x32_bf16 v[14:17], v[148:151], v[226:229], v[14:17]
	v_mfma_f32_16x16x32_bf16 v[6:9], v[156:159], v[226:229], v[6:9]
	v_mfma_f32_16x16x32_bf16 v[62:65], v[152:155], v[206:209], v[62:65]
	v_mfma_f32_16x16x32_bf16 v[54:57], v[160:163], v[206:209], v[54:57]
	v_mfma_f32_16x16x32_bf16 v[46:49], v[152:155], v[214:217], v[46:49]
	v_mfma_f32_16x16x32_bf16 v[38:41], v[160:163], v[214:217], v[38:41]
	v_mfma_f32_16x16x32_bf16 v[30:33], v[152:155], v[222:225], v[30:33]
	v_mfma_f32_16x16x32_bf16 v[22:25], v[160:163], v[222:225], v[22:25]
	v_mfma_f32_16x16x32_bf16 v[14:17], v[152:155], v[230:233], v[14:17]
	v_mfma_f32_16x16x32_bf16 v[6:9], v[160:163], v[230:233], v[6:9]
	s_setprio 0
	s_setprio 1
	v_mfma_f32_16x16x32_bf16 v[58:61], v[164:167], v[202:205], v[58:61]
	v_mfma_f32_16x16x32_bf16 v[50:53], v[172:175], v[202:205], v[50:53]
	v_mfma_f32_16x16x32_bf16 v[42:45], v[164:167], v[210:213], v[42:45]
	v_mfma_f32_16x16x32_bf16 v[34:37], v[172:175], v[210:213], v[34:37]
	v_mfma_f32_16x16x32_bf16 v[26:29], v[164:167], v[218:221], v[26:29]
	v_mfma_f32_16x16x32_bf16 v[18:21], v[172:175], v[218:221], v[18:21]
	v_mfma_f32_16x16x32_bf16 v[10:13], v[164:167], v[226:229], v[10:13]
	v_mfma_f32_16x16x32_bf16 v[2:5], v[172:175], v[226:229], v[2:5]
	v_mfma_f32_16x16x32_bf16 v[58:61], v[168:171], v[206:209], v[58:61]
	v_mfma_f32_16x16x32_bf16 v[50:53], v[198:201], v[206:209], v[50:53]
	v_mfma_f32_16x16x32_bf16 v[42:45], v[168:171], v[214:217], v[42:45]
	v_mfma_f32_16x16x32_bf16 v[34:37], v[198:201], v[214:217], v[34:37]
	v_mfma_f32_16x16x32_bf16 v[26:29], v[168:171], v[222:225], v[26:29]
	v_mfma_f32_16x16x32_bf16 v[18:21], v[198:201], v[222:225], v[18:21]
	v_mfma_f32_16x16x32_bf16 v[10:13], v[168:171], v[230:233], v[10:13]
	s_setprio 3
	s_barrier
	v_mfma_f32_16x16x32_bf16 v[2:5], v[198:201], v[230:233], v[2:5]
	s_setprio 0
	s_add_i32 s67, 0, 0x18000
	s_add_i32 s68, 0, 0x1c000
	v_add_u32_e32 v160, s67, v192
	v_add_u32_e32 v198, s68, v192
	ds_read_b128 v[148:151], v160
	ds_read_b128 v[152:155], v160 offset:1024
	ds_read_b128 v[156:159], v160 offset:2048
	ds_read_b128 v[160:163], v160 offset:3072
	ds_read_b128 v[164:167], v198
	ds_read_b128 v[168:171], v198 offset:1024
	ds_read_b128 v[172:175], v198 offset:2048
	ds_read_b128 v[198:201], v198 offset:3072
	s_add_u32 s18, s30, 0x40000
	s_addc_u32 s19, s31, 0
	s_mov_b32 m0, s53
	v_lshl_add_u64 v[242:243], s[18:19], 0, v[136:137]
	ds_read_b128 v[202:205], v197 offset:32768
	ds_read_b128 v[206:209], v197 offset:33792
	ds_read_b128 v[210:213], v197 offset:34816
	ds_read_b128 v[214:217], v197 offset:35840
	ds_read_b128 v[218:221], v197 offset:36864
	ds_read_b128 v[222:225], v197 offset:37888
	ds_read_b128 v[226:229], v197 offset:38912
	ds_read_b128 v[230:233], v197 offset:39936
	global_load_lds_dwordx4 v[242:243], off
	v_lshl_add_u64 v[242:243], s[18:19], 0, v[132:133]
	s_mov_b32 m0, s54
	s_nop 0
	global_load_lds_dwordx4 v[242:243], off
	s_waitcnt vmcnt(8)
	s_waitcnt lgkmcnt(0)
	s_barrier
	s_setprio 1
	s_waitcnt lgkmcnt(0)
	v_mfma_f32_16x16x32_bf16 v[126:129], v[148:151], v[202:205], v[126:129]
	v_mfma_f32_16x16x32_bf16 v[118:121], v[156:159], v[202:205], v[118:121]
	v_mfma_f32_16x16x32_bf16 v[110:113], v[148:151], v[210:213], v[110:113]
	v_mfma_f32_16x16x32_bf16 v[102:105], v[156:159], v[210:213], v[102:105]
	v_mfma_f32_16x16x32_bf16 v[94:97], v[148:151], v[218:221], v[94:97]
	v_mfma_f32_16x16x32_bf16 v[86:89], v[156:159], v[218:221], v[86:89]
	v_mfma_f32_16x16x32_bf16 v[78:81], v[148:151], v[226:229], v[78:81]
	v_mfma_f32_16x16x32_bf16 v[70:73], v[156:159], v[226:229], v[70:73]
	v_mfma_f32_16x16x32_bf16 v[126:129], v[152:155], v[206:209], v[126:129]
	v_mfma_f32_16x16x32_bf16 v[118:121], v[160:163], v[206:209], v[118:121]
	v_mfma_f32_16x16x32_bf16 v[110:113], v[152:155], v[214:217], v[110:113]
	v_mfma_f32_16x16x32_bf16 v[102:105], v[160:163], v[214:217], v[102:105]
	v_mfma_f32_16x16x32_bf16 v[94:97], v[152:155], v[222:225], v[94:97]
	v_mfma_f32_16x16x32_bf16 v[86:89], v[160:163], v[222:225], v[86:89]
	v_mfma_f32_16x16x32_bf16 v[78:81], v[152:155], v[230:233], v[78:81]
	v_mfma_f32_16x16x32_bf16 v[70:73], v[160:163], v[230:233], v[70:73]
	s_setprio 0
	s_setprio 1
	v_mfma_f32_16x16x32_bf16 v[122:125], v[164:167], v[202:205], v[122:125]
	v_mfma_f32_16x16x32_bf16 v[114:117], v[172:175], v[202:205], v[114:117]
	v_mfma_f32_16x16x32_bf16 v[106:109], v[164:167], v[210:213], v[106:109]
	v_mfma_f32_16x16x32_bf16 v[98:101], v[172:175], v[210:213], v[98:101]
	v_mfma_f32_16x16x32_bf16 v[90:93], v[164:167], v[218:221], v[90:93]
	v_mfma_f32_16x16x32_bf16 v[82:85], v[172:175], v[218:221], v[82:85]
	v_mfma_f32_16x16x32_bf16 v[74:77], v[164:167], v[226:229], v[74:77]
	v_mfma_f32_16x16x32_bf16 v[66:69], v[172:175], v[226:229], v[66:69]
	v_mfma_f32_16x16x32_bf16 v[122:125], v[168:171], v[206:209], v[122:125]
	v_mfma_f32_16x16x32_bf16 v[114:117], v[198:201], v[206:209], v[114:117]
	v_mfma_f32_16x16x32_bf16 v[106:109], v[168:171], v[214:217], v[106:109]
	v_mfma_f32_16x16x32_bf16 v[98:101], v[198:201], v[214:217], v[98:101]
	v_mfma_f32_16x16x32_bf16 v[90:93], v[168:171], v[222:225], v[90:93]
	v_mfma_f32_16x16x32_bf16 v[82:85], v[198:201], v[222:225], v[82:85]
	v_mfma_f32_16x16x32_bf16 v[74:77], v[168:171], v[230:233], v[74:77]
	s_setprio 3
	s_barrier
; #define PG8_STAGE(bufoff, gbase, voff) do { _Pragma("unroll") for (int _i = 0; _i < 2; ++_i) \
;         __builtin_amdgcn_global_load_lds((const unsigned*)((const char*)(gbase) + (voff)[_i]), (PG8_LAS unsigned*)(lds + (bufoff) + ldsw + _i * 8192), 16, 0, 0); } while (0)
; #define PG8_LDA(dst, b, h) do { _Pragma("unroll") for (int m = 0; m < 4; ++m) _Pragma("unroll") for (int k = 0; k < 2; ++k) dst[m][k] = *(const PG8_LAS bf16x8*)(lds + PG8_SA(b, h) + aoff + m * 2048 + k * 1024); } while (0)
; #define PG8_LDB(dst, b, h) do { _Pragma("unroll") for (int n = 0; n < 2; ++n) _Pragma("unroll") for (int k = 0; k < 2; ++k) dst[n][k] = *(const PG8_LAS bf16x8*)(lds + PG8_SB(b, h) + boff + n * 2048 + k * 1024); } while (0)
; #define PG8_MMA(ai, bj, At, Bt) do { __builtin_amdgcn_s_setprio(1); _Pragma("unroll") for (int m = 0; m < 4; ++m) _Pragma("unroll") for (int n = 0; n < 2; ++n) _Pragma("unroll") for (int k = 0; k < 2; ++k) \
;         acc[ai][bj][m][n] = __builtin_amdgcn_mfma_f32_16x16x32_bf16(Bt[n][k], At[m][k], acc[ai][bj][m][n], 0, 0, 0); __builtin_amdgcn_s_setprio(0); } while (0)
; template <class Epi, class Sched, bool ALIGN_EPI = false, bool SP2 = false>
; __device__ __forceinline__ void gemm_phase(PG8_LAS unsigned char* lds, const Gemm g, const Sched& S, const Epi& E) {
;     ...
;             PG8_LDB(B0, 0, 0); PG8_LDB(B1, 0, 1); PG8_SCHED; PG8_LDA(At, 0, 0); PG8_STAGE(PG8_SA(1, 1), a1 + hstep, voffA);
;             PG8_WAIT_V(8); PG8_WAIT_L(0); PG8_BAR; PG8_MMA(0, 0, At, B0); PG8_MMA(0, 1, At, B1); PG8_BAR; PG8_SCHED;
;             PG8_LDA(At, 0, 1); PG8_STAGE(PG8_SB(0, 0), b2, voffB); PG8_STAGE(PG8_SB(0, 1), b2 + hstep, voffB); PG8_STAGE(PG8_SA(0, 0), a2, voffA);
;             PG8_WAIT_V(8); PG8_WAIT_L(0); PG8_BAR; PG8_MMA(1, 0, At, B0); PG8_MMA(1, 1, At, B1); PG8_BAR; PG8_SCHED;
;             PG8_LDB(B0, 1, 0); PG8_LDB(B1, 1, 1); PG8_SCHED; PG8_LDA(At, 1, 0); PG8_STAGE(PG8_SA(0, 1), a2 + hstep, voffA);
;             PG8_WAIT_V(8); PG8_WAIT_L(0); PG8_BAR; PG8_MMA(0, 0, At, B0); PG8_MMA(0, 1, At, B1); PG8_BAR; PG8_SCHED;
;             PG8_LDA(At, 1, 1); PG8_STAGE(PG8_SB(1, 0), b3, voffB); PG8_STAGE(PG8_SB(1, 1), b3 + hstep, voffB); PG8_STAGE(PG8_SA(1, 0), a3, voffA);
;             PG8_WAIT_V(8); PG8_WAIT_L(0); PG8_BAR; PG8_MMA(1, 0, At, B0); PG8_MMA(1, 1, At, B1); PG8_BAR; PG8_SCHED;
;     ...
;         if constexpr (ALIGN_EPI) { if (wr == 0) PG8_BAR; }
	v_mfma_f32_16x16x32_bf16 v[66:69], v[198:201], v[230:233], v[66:69]
	s_setprio 0
	s_add_i32 s18, s67, s25
	v_lshl_add_u64 v[176:177], v[176:177], 0, s[14:15]
	s_mov_b32 m0, s18
	ds_read_b128 v[202:205], v197 offset:49152
	ds_read_b128 v[206:209], v197 offset:50176
	ds_read_b128 v[210:213], v197 offset:51200
	ds_read_b128 v[214:217], v197 offset:52224
	ds_read_b128 v[218:221], v197 offset:53248
	ds_read_b128 v[222:225], v197 offset:54272
	ds_read_b128 v[226:229], v197 offset:55296
	ds_read_b128 v[230:233], v197 offset:56320
	global_load_lds_dwordx4 v[176:177], off
	s_add_i32 m0, s18, 0x2000
	s_add_u32 s6, s6, 0x40080
	v_lshl_add_u64 v[176:177], v[234:235], 0, s[14:15]
	s_addc_u32 s7, s7, 0
	s_add_i32 s18, s68, s25
	global_load_lds_dwordx4 v[176:177], off
	v_lshl_add_u64 v[176:177], s[6:7], 0, v[134:135]
	s_mov_b32 m0, s18
	s_nop 0
	global_load_lds_dwordx4 v[176:177], off
	v_lshl_add_u64 v[176:177], s[6:7], 0, v[130:131]
	s_add_i32 m0, s18, 0x2000
	s_nop 0
	global_load_lds_dwordx4 v[176:177], off
	v_lshl_add_u64 v[176:177], v[238:239], 0, s[14:15]
	s_mov_b32 m0, s56
	s_nop 0
	global_load_lds_dwordx4 v[176:177], off
	v_lshl_add_u64 v[176:177], v[240:241], 0, s[14:15]
	s_mov_b32 m0, s57
	s_nop 0
	global_load_lds_dwordx4 v[176:177], off
	s_waitcnt vmcnt(8)
	s_waitcnt lgkmcnt(0)
	s_barrier
	s_setprio 1
	s_waitcnt lgkmcnt(0)
	v_mfma_f32_16x16x32_bf16 v[62:65], v[148:151], v[202:205], v[62:65]
	v_mfma_f32_16x16x32_bf16 v[54:57], v[156:159], v[202:205], v[54:57]
	v_mfma_f32_16x16x32_bf16 v[46:49], v[148:151], v[210:213], v[46:49]
	v_mfma_f32_16x16x32_bf16 v[38:41], v[156:159], v[210:213], v[38:41]
	v_mfma_f32_16x16x32_bf16 v[30:33], v[148:151], v[218:221], v[30:33]
	v_mfma_f32_16x16x32_bf16 v[22:25], v[156:159], v[218:221], v[22:25]
	v_mfma_f32_16x16x32_bf16 v[14:17], v[148:151], v[226:229], v[14:17]
	v_mfma_f32_16x16x32_bf16 v[6:9], v[156:159], v[226:229], v[6:9]
	v_mfma_f32_16x16x32_bf16 v[62:65], v[152:155], v[206:209], v[62:65]
	v_mfma_f32_16x16x32_bf16 v[54:57], v[160:163], v[206:209], v[54:57]
	v_mfma_f32_16x16x32_bf16 v[46:49], v[152:155], v[214:217], v[46:49]
	v_mfma_f32_16x16x32_bf16 v[38:41], v[160:163], v[214:217], v[38:41]
	v_mfma_f32_16x16x32_bf16 v[30:33], v[152:155], v[222:225], v[30:33]
	v_mfma_f32_16x16x32_bf16 v[22:25], v[160:163], v[222:225], v[22:25]
	v_mfma_f32_16x16x32_bf16 v[14:17], v[152:155], v[230:233], v[14:17]
	v_mfma_f32_16x16x32_bf16 v[6:9], v[160:163], v[230:233], v[6:9]
	s_setprio 0
	s_setprio 1
	v_mfma_f32_16x16x32_bf16 v[58:61], v[164:167], v[202:205], v[58:61]
	v_mfma_f32_16x16x32_bf16 v[50:53], v[172:175], v[202:205], v[50:53]
	v_mfma_f32_16x16x32_bf16 v[42:45], v[164:167], v[210:213], v[42:45]
	v_mfma_f32_16x16x32_bf16 v[34:37], v[172:175], v[210:213], v[34:37]
	v_mfma_f32_16x16x32_bf16 v[26:29], v[164:167], v[218:221], v[26:29]
	v_mfma_f32_16x16x32_bf16 v[18:21], v[172:175], v[218:221], v[18:21]
	v_mfma_f32_16x16x32_bf16 v[10:13], v[164:167], v[226:229], v[10:13]
	v_mfma_f32_16x16x32_bf16 v[2:5], v[172:175], v[226:229], v[2:5]
	v_mfma_f32_16x16x32_bf16 v[58:61], v[168:171], v[206:209], v[58:61]
	v_mfma_f32_16x16x32_bf16 v[50:53], v[198:201], v[206:209], v[50:53]
	v_mfma_f32_16x16x32_bf16 v[42:45], v[168:171], v[214:217], v[42:45]
	v_mfma_f32_16x16x32_bf16 v[34:37], v[198:201], v[214:217], v[34:37]
	v_mfma_f32_16x16x32_bf16 v[26:29], v[168:171], v[222:225], v[26:29]
	v_mfma_f32_16x16x32_bf16 v[18:21], v[198:201], v[222:225], v[18:21]
	v_mfma_f32_16x16x32_bf16 v[10:13], v[168:171], v[230:233], v[10:13]
	s_setprio 3
	s_barrier
	v_mfma_f32_16x16x32_bf16 v[2:5], v[198:201], v[230:233], v[2:5]
	s_setprio 0
	s_add_i32 s66, s66, 2
	s_add_u32 s4, s4, 0x100
	s_addc_u32 s5, s5, 0
	s_add_u32 s46, s46, 0x100
	s_addc_u32 s47, s47, 0
	s_cmp_gt_u32 s66, 13
	s_cbranch_scc0 .LBB0_738
	s_and_b64 vcc, exec, s[16:17]
	s_cbranch_vccz .LBB0_741
	s_barrier

; #define PG8_STAGE(bufoff, gbase, voff) do { _Pragma("unroll") for (int _i = 0; _i < 2; ++_i) \
;         __builtin_amdgcn_global_load_lds((const unsigned*)((const char*)(gbase) + (voff)[_i]), (PG8_LAS unsigned*)(lds + (bufoff) + ldsw + _i * 8192), 16, 0, 0); } while (0)
; #define PG8_LDA(dst, b, h) do { _Pragma("unroll") for (int m = 0; m < 4; ++m) _Pragma("unroll") for (int k = 0; k < 2; ++k) dst[m][k] = *(const PG8_LAS bf16x8*)(lds + PG8_SA(b, h) + aoff + m * 2048 + k * 1024); } while (0)
; #define PG8_LDB(dst, b, h) do { _Pragma("unroll") for (int n = 0; n < 2; ++n) _Pragma("unroll") for (int k = 0; k < 2; ++k) dst[n][k] = *(const PG8_LAS bf16x8*)(lds + PG8_SB(b, h) + boff + n * 2048 + k * 1024); } while (0)
; #define PG8_BAR __builtin_amdgcn_s_barrier()
; template <class Epi, class Sched, bool ALIGN_EPI = false, bool SP2 = false>
; __device__ __forceinline__ void gemm_phase(PG8_LAS unsigned char* lds, const Gemm g, const Sched& S, const Epi& E) {
;     ...
;             const bool last = (t == nt - 2);
;             const char* a1 = cA + (size_t)(t + 1) * kstep;
;             const char* a2 = last ? nA : cA + (size_t)(t + 2) * kstep; const char* b2 = last ? nB : cB + (size_t)(t + 2) * kstep;
;             const char* a3 = a2 + kstep; const char* b3 = b2 + kstep;
;             if (last && has_next) S.a_ready(nxt);
;             if constexpr (SP2) {
;             PG8_LDB(B0, 0, 0); PG8_LDB(B1, 0, 1); PG8_SCHED; PG8_LDA(At, 0, 0); PG8_STAGE(PG8_SA(1, 1), a1 + hstep, voffA);
;             PG8_WAIT_V(8); PG8_WAIT_L(0); PG8_BAR; PG8_MMA(0, 0, At, B0); PG8_MMA(0, 1, At, B1); PG8_BAR; PG8_SCHED;
;             PG8_LDA(At, 0, 1); PG8_STAGE(PG8_SB(0, 0), b2, voffB); PG8_STAGE(PG8_SB(0, 1), b2 + hstep, voffB); PG8_STAGE(PG8_SA(0, 0), a2, voffA);
;             PG8_WAIT_V(8); PG8_WAIT_L(0); PG8_BAR; PG8_MMA(1, 0, At, B0); PG8_MMA(1, 1, At, B1); PG8_BAR; PG8_SCHED;
;             PG8_LDB(B0, 1, 0); PG8_LDB(B1, 1, 1); PG8_SCHED; PG8_LDA(At, 1, 0); PG8_STAGE(PG8_SA(0, 1), a2 + hstep, voffA);
;             PG8_WAIT_V(8); PG8_WAIT_L(0); PG8_BAR; PG8_MMA(0, 0, At, B0); PG8_MMA(0, 1, At, B1); PG8_BAR; PG8_SCHED;
;             PG8_LDA(At, 1, 1); PG8_STAGE(PG8_SB(1, 0), b3, voffB); PG8_STAGE(PG8_SB(1, 1), b3 + hstep, voffB); PG8_STAGE(PG8_SA(1, 0), a3, voffA);
;             PG8_WAIT_V(8); PG8_WAIT_L(0); PG8_BAR; PG8_MMA(1, 0, At, B0); PG8_MMA(1, 1, At, B1); PG8_BAR; PG8_SCHED;
.LBB0_777:
	ds_read_b128 v[148:151], v1
	ds_read_b128 v[152:155], v1 offset:1024
	ds_read_b128 v[156:159], v1 offset:2048
	ds_read_b128 v[160:163], v1 offset:3072
	ds_read_b128 v[164:167], v145
	ds_read_b128 v[168:171], v145 offset:1024
	ds_read_b128 v[172:175], v145 offset:2048
	ds_read_b128 v[176:179], v145 offset:3072
	s_add_i32 s76, s30, 2
	s_add_u32 s18, s46, 0x80
	s_addc_u32 s19, s47, 0
	s_cmp_eq_u32 s67, s30
	s_cselect_b32 s30, s42, s18
	s_cselect_b32 s31, s43, s19
	s_cselect_b32 s19, s45, s49
	s_cselect_b32 s18, s44, s48
	v_lshl_add_u64 v[212:213], s[46:47], 0, v[138:139]
	s_add_i32 m0, s53, 0xc000
	ds_read_b128 v[180:183], v146
	ds_read_b128 v[184:187], v146 offset:1024
	ds_read_b128 v[188:191], v146 offset:2048
	ds_read_b128 v[192:195], v146 offset:3072
	ds_read_b128 v[196:199], v146 offset:4096
	ds_read_b128 v[200:203], v146 offset:5120
	ds_read_b128 v[204:207], v146 offset:6144
	ds_read_b128 v[208:211], v146 offset:7168
	global_load_lds_dwordx4 v[212:213], off
	v_lshl_add_u64 v[212:213], s[46:47], 0, v[140:141]
	s_add_i32 m0, s53, 0xe000
	s_nop 0
	global_load_lds_dwordx4 v[212:213], off
	s_waitcnt vmcnt(8)
	s_waitcnt lgkmcnt(0)
	s_barrier
	s_setprio 1
	s_waitcnt lgkmcnt(0)
	v_mfma_f32_16x16x32_bf16 v[122:125], v[148:151], v[180:183], v[122:125]
	v_mfma_f32_16x16x32_bf16 v[126:129], v[156:159], v[180:183], v[126:129]
	v_mfma_f32_16x16x32_bf16 v[110:113], v[148:151], v[188:191], v[110:113]
	v_mfma_f32_16x16x32_bf16 v[106:109], v[156:159], v[188:191], v[106:109]
	v_mfma_f32_16x16x32_bf16 v[94:97], v[148:151], v[196:199], v[94:97]
	v_mfma_f32_16x16x32_bf16 v[90:93], v[156:159], v[196:199], v[90:93]
	v_mfma_f32_16x16x32_bf16 v[78:81], v[148:151], v[204:207], v[78:81]
	v_mfma_f32_16x16x32_bf16 v[74:77], v[156:159], v[204:207], v[74:77]
	v_mfma_f32_16x16x32_bf16 v[122:125], v[152:155], v[184:187], v[122:125]
	v_mfma_f32_16x16x32_bf16 v[126:129], v[160:163], v[184:187], v[126:129]
	v_mfma_f32_16x16x32_bf16 v[110:113], v[152:155], v[192:195], v[110:113]
	v_mfma_f32_16x16x32_bf16 v[106:109], v[160:163], v[192:195], v[106:109]
	v_mfma_f32_16x16x32_bf16 v[94:97], v[152:155], v[200:203], v[94:97]
	v_mfma_f32_16x16x32_bf16 v[90:93], v[160:163], v[200:203], v[90:93]
	v_mfma_f32_16x16x32_bf16 v[78:81], v[152:155], v[208:211], v[78:81]
	v_mfma_f32_16x16x32_bf16 v[74:77], v[160:163], v[208:211], v[74:77]
	s_setprio 0
	s_setprio 1
	v_mfma_f32_16x16x32_bf16 v[118:121], v[164:167], v[180:183], v[118:121]
	v_mfma_f32_16x16x32_bf16 v[114:117], v[172:175], v[180:183], v[114:117]
	v_mfma_f32_16x16x32_bf16 v[102:105], v[164:167], v[188:191], v[102:105]
	v_mfma_f32_16x16x32_bf16 v[98:101], v[172:175], v[188:191], v[98:101]
	v_mfma_f32_16x16x32_bf16 v[86:89], v[164:167], v[196:199], v[86:89]
	v_mfma_f32_16x16x32_bf16 v[82:85], v[172:175], v[196:199], v[82:85]
	v_mfma_f32_16x16x32_bf16 v[70:73], v[164:167], v[204:207], v[70:73]
	v_mfma_f32_16x16x32_bf16 v[66:69], v[172:175], v[204:207], v[66:69]
	v_mfma_f32_16x16x32_bf16 v[118:121], v[168:171], v[184:187], v[118:121]
	v_mfma_f32_16x16x32_bf16 v[114:117], v[176:179], v[184:187], v[114:117]
	v_mfma_f32_16x16x32_bf16 v[102:105], v[168:171], v[192:195], v[102:105]
	v_mfma_f32_16x16x32_bf16 v[98:101], v[176:179], v[192:195], v[98:101]
	v_mfma_f32_16x16x32_bf16 v[86:89], v[168:171], v[200:203], v[86:89]
	v_mfma_f32_16x16x32_bf16 v[82:85], v[176:179], v[200:203], v[82:85]
	v_mfma_f32_16x16x32_bf16 v[70:73], v[168:171], v[208:211], v[70:73]
	s_setprio 3
	s_barrier
	v_mfma_f32_16x16x32_bf16 v[66:69], v[176:179], v[208:211], v[66:69]
	s_setprio 0
	s_add_i32 s77, s68, s52
	v_lshl_add_u64 v[212:213], s[18:19], 0, v[132:133]
	s_mov_b32 m0, s77
	ds_read_b128 v[180:183], v146 offset:16384
	ds_read_b128 v[184:187], v146 offset:17408
	ds_read_b128 v[188:191], v146 offset:18432
	ds_read_b128 v[192:195], v146 offset:19456
	ds_read_b128 v[196:199], v146 offset:20480
	ds_read_b128 v[200:203], v146 offset:21504
	ds_read_b128 v[204:207], v146 offset:22528
	ds_read_b128 v[208:211], v146 offset:23552
	global_load_lds_dwordx4 v[212:213], off
	s_add_i32 m0, s77, 0x2000
	v_lshl_add_u64 v[214:215], s[18:19], 0, v[136:137]
	s_add_u32 s18, s18, s4
	s_addc_u32 s19, s19, s5
	s_add_i32 s77, s69, s52
	global_load_lds_dwordx4 v[214:215], off
	v_lshl_add_u64 v[216:217], s[18:19], 0, v[132:133]
	s_mov_b32 m0, s77
	v_lshl_add_u64 v[218:219], s[18:19], 0, v[136:137]
	global_load_lds_dwordx4 v[216:217], off
	s_add_i32 m0, s77, 0x2000
	v_lshl_add_u64 v[220:221], s[30:31], 0, v[130:131]
	global_load_lds_dwordx4 v[218:219], off
	s_mov_b32 m0, s53
	v_lshl_add_u64 v[222:223], s[30:31], 0, v[134:135]
	global_load_lds_dwordx4 v[220:221], off
	s_mov_b32 m0, s54
	s_nop 0
	global_load_lds_dwordx4 v[222:223], off
	s_waitcnt vmcnt(8)
	s_waitcnt lgkmcnt(0)
	s_barrier
; #define PG8_STAGE(bufoff, gbase, voff) do { _Pragma("unroll") for (int _i = 0; _i < 2; ++_i) \
;         __builtin_amdgcn_global_load_lds((const unsigned*)((const char*)(gbase) + (voff)[_i]), (PG8_LAS unsigned*)(lds + (bufoff) + ldsw + _i * 8192), 16, 0, 0); } while (0)
; #define PG8_LDA(dst, b, h) do { _Pragma("unroll") for (int m = 0; m < 4; ++m) _Pragma("unroll") for (int k = 0; k < 2; ++k) dst[m][k] = *(const PG8_LAS bf16x8*)(lds + PG8_SA(b, h) + aoff + m * 2048 + k * 1024); } while (0)
; #define PG8_LDB(dst, b, h) do { _Pragma("unroll") for (int n = 0; n < 2; ++n) _Pragma("unroll") for (int k = 0; k < 2; ++k) dst[n][k] = *(const PG8_LAS bf16x8*)(lds + PG8_SB(b, h) + boff + n * 2048 + k * 1024); } while (0)
; #define PG8_MMA(ai, bj, At, Bt) do { __builtin_amdgcn_s_setprio(1); _Pragma("unroll") for (int m = 0; m < 4; ++m) _Pragma("unroll") for (int n = 0; n < 2; ++n) _Pragma("unroll") for (int k = 0; k < 2; ++k) \
;         acc[ai][bj][m][n] = __builtin_amdgcn_mfma_f32_16x16x32_bf16(Bt[n][k], At[m][k], acc[ai][bj][m][n], 0, 0, 0); __builtin_amdgcn_s_setprio(0); } while (0)
; #define PG8_WAIT_V(n) asm volatile("s_waitcnt vmcnt(" #n ")" ::: "memory")
; template <class Epi, class Sched, bool ALIGN_EPI = false, bool SP2 = false>
; __device__ __forceinline__ void gemm_phase(PG8_LAS unsigned char* lds, const Gemm g, const Sched& S, const Epi& E) {
;     ...
;             PG8_LDB(B0, 0, 0); PG8_LDB(B1, 0, 1); PG8_SCHED; PG8_LDA(At, 0, 0); PG8_STAGE(PG8_SA(1, 1), a1 + hstep, voffA);
;             PG8_WAIT_V(8); PG8_WAIT_L(0); PG8_BAR; PG8_MMA(0, 0, At, B0); PG8_MMA(0, 1, At, B1); PG8_BAR; PG8_SCHED;
;             PG8_LDA(At, 0, 1); PG8_STAGE(PG8_SB(0, 0), b2, voffB); PG8_STAGE(PG8_SB(0, 1), b2 + hstep, voffB); PG8_STAGE(PG8_SA(0, 0), a2, voffA);
;             PG8_WAIT_V(8); PG8_WAIT_L(0); PG8_BAR; PG8_MMA(1, 0, At, B0); PG8_MMA(1, 1, At, B1); PG8_BAR; PG8_SCHED;
;             PG8_LDB(B0, 1, 0); PG8_LDB(B1, 1, 1); PG8_SCHED; PG8_LDA(At, 1, 0); PG8_STAGE(PG8_SA(0, 1), a2 + hstep, voffA);
;             PG8_WAIT_V(8); PG8_WAIT_L(0); PG8_BAR; PG8_MMA(0, 0, At, B0); PG8_MMA(0, 1, At, B1); PG8_BAR; PG8_SCHED;
;             PG8_LDA(At, 1, 1); PG8_STAGE(PG8_SB(1, 0), b3, voffB); PG8_STAGE(PG8_SB(1, 1), b3 + hstep, voffB); PG8_STAGE(PG8_SA(1, 0), a3, voffA);
;             PG8_WAIT_V(8); PG8_WAIT_L(0); PG8_BAR; PG8_MMA(1, 0, At, B0); PG8_MMA(1, 1, At, B1); PG8_BAR; PG8_SCHED;
	s_setprio 1
	s_waitcnt lgkmcnt(0)
	v_mfma_f32_16x16x32_bf16 v[62:65], v[148:151], v[180:183], v[62:65]
	v_mfma_f32_16x16x32_bf16 v[58:61], v[156:159], v[180:183], v[58:61]
	v_mfma_f32_16x16x32_bf16 v[46:49], v[148:151], v[188:191], v[46:49]
	v_mfma_f32_16x16x32_bf16 v[42:45], v[156:159], v[188:191], v[42:45]
	v_mfma_f32_16x16x32_bf16 v[30:33], v[148:151], v[196:199], v[30:33]
	v_mfma_f32_16x16x32_bf16 v[26:29], v[156:159], v[196:199], v[26:29]
	v_mfma_f32_16x16x32_bf16 v[14:17], v[148:151], v[204:207], v[14:17]
	v_mfma_f32_16x16x32_bf16 v[10:13], v[156:159], v[204:207], v[10:13]
	v_mfma_f32_16x16x32_bf16 v[62:65], v[152:155], v[184:187], v[62:65]
	v_mfma_f32_16x16x32_bf16 v[58:61], v[160:163], v[184:187], v[58:61]
	v_mfma_f32_16x16x32_bf16 v[46:49], v[152:155], v[192:195], v[46:49]
	v_mfma_f32_16x16x32_bf16 v[42:45], v[160:163], v[192:195], v[42:45]
	v_mfma_f32_16x16x32_bf16 v[30:33], v[152:155], v[200:203], v[30:33]
	v_mfma_f32_16x16x32_bf16 v[26:29], v[160:163], v[200:203], v[26:29]
	v_mfma_f32_16x16x32_bf16 v[14:17], v[152:155], v[208:211], v[14:17]
	v_mfma_f32_16x16x32_bf16 v[10:13], v[160:163], v[208:211], v[10:13]
	s_setprio 0
	s_setprio 1
	v_mfma_f32_16x16x32_bf16 v[54:57], v[164:167], v[180:183], v[54:57]
	v_mfma_f32_16x16x32_bf16 v[50:53], v[172:175], v[180:183], v[50:53]
	v_mfma_f32_16x16x32_bf16 v[38:41], v[164:167], v[188:191], v[38:41]
	v_mfma_f32_16x16x32_bf16 v[34:37], v[172:175], v[188:191], v[34:37]
	v_mfma_f32_16x16x32_bf16 v[22:25], v[164:167], v[196:199], v[22:25]
	v_mfma_f32_16x16x32_bf16 v[18:21], v[172:175], v[196:199], v[18:21]
	v_mfma_f32_16x16x32_bf16 v[6:9], v[164:167], v[204:207], v[6:9]
	v_mfma_f32_16x16x32_bf16 v[2:5], v[172:175], v[204:207], v[2:5]
	v_mfma_f32_16x16x32_bf16 v[54:57], v[168:171], v[184:187], v[54:57]
	v_mfma_f32_16x16x32_bf16 v[50:53], v[176:179], v[184:187], v[50:53]
	v_mfma_f32_16x16x32_bf16 v[38:41], v[168:171], v[192:195], v[38:41]
	v_mfma_f32_16x16x32_bf16 v[34:37], v[176:179], v[192:195], v[34:37]
	v_mfma_f32_16x16x32_bf16 v[22:25], v[168:171], v[200:203], v[22:25]
	v_mfma_f32_16x16x32_bf16 v[18:21], v[176:179], v[200:203], v[18:21]
	v_mfma_f32_16x16x32_bf16 v[6:9], v[168:171], v[208:211], v[6:9]
	s_setprio 3
	s_barrier
	v_mfma_f32_16x16x32_bf16 v[2:5], v[176:179], v[208:211], v[2:5]
	s_setprio 0
	s_add_i32 s77, 0, 0x18000
	v_add_u32_e32 v147, s77, v143
	s_add_i32 s78, 0, 0x1c000
	ds_read_b128 v[148:151], v147
	ds_read_b128 v[152:155], v147 offset:1024
	ds_read_b128 v[156:159], v147 offset:2048
	ds_read_b128 v[160:163], v147 offset:3072
	v_add_u32_e32 v147, s78, v143
	ds_read_b128 v[164:167], v147
	ds_read_b128 v[168:171], v147 offset:1024
	ds_read_b128 v[172:175], v147 offset:2048
	ds_read_b128 v[176:179], v147 offset:3072
	s_add_u32 s18, s30, s4
	s_addc_u32 s19, s31, s5
	s_mov_b32 m0, s55
	v_lshl_add_u64 v[224:225], s[18:19], 0, v[130:131]
	ds_read_b128 v[180:183], v146 offset:32768
	ds_read_b128 v[184:187], v146 offset:33792
	ds_read_b128 v[188:191], v146 offset:34816
	ds_read_b128 v[192:195], v146 offset:35840
	ds_read_b128 v[196:199], v146 offset:36864
	ds_read_b128 v[200:203], v146 offset:37888
	ds_read_b128 v[204:207], v146 offset:38912
	ds_read_b128 v[208:211], v146 offset:39936
	global_load_lds_dwordx4 v[224:225], off
	v_lshl_add_u64 v[224:225], s[18:19], 0, v[134:135]
	s_mov_b32 m0, s56
	s_nop 0
	global_load_lds_dwordx4 v[224:225], off
	s_waitcnt vmcnt(8)
	s_waitcnt lgkmcnt(0)
	s_barrier
	s_setprio 1
	s_waitcnt lgkmcnt(0)
	v_mfma_f32_16x16x32_bf16 v[122:125], v[148:151], v[180:183], v[122:125]
	v_mfma_f32_16x16x32_bf16 v[126:129], v[156:159], v[180:183], v[126:129]
	v_mfma_f32_16x16x32_bf16 v[110:113], v[148:151], v[188:191], v[110:113]
	v_mfma_f32_16x16x32_bf16 v[106:109], v[156:159], v[188:191], v[106:109]
	v_mfma_f32_16x16x32_bf16 v[94:97], v[148:151], v[196:199], v[94:97]
	v_mfma_f32_16x16x32_bf16 v[90:93], v[156:159], v[196:199], v[90:93]
	v_mfma_f32_16x16x32_bf16 v[78:81], v[148:151], v[204:207], v[78:81]
	v_mfma_f32_16x16x32_bf16 v[74:77], v[156:159], v[204:207], v[74:77]
	v_mfma_f32_16x16x32_bf16 v[122:125], v[152:155], v[184:187], v[122:125]
	v_mfma_f32_16x16x32_bf16 v[126:129], v[160:163], v[184:187], v[126:129]
	v_mfma_f32_16x16x32_bf16 v[110:113], v[152:155], v[192:195], v[110:113]
	v_mfma_f32_16x16x32_bf16 v[106:109], v[160:163], v[192:195], v[106:109]
	v_mfma_f32_16x16x32_bf16 v[94:97], v[152:155], v[200:203], v[94:97]
	v_mfma_f32_16x16x32_bf16 v[90:93], v[160:163], v[200:203], v[90:93]
	v_mfma_f32_16x16x32_bf16 v[78:81], v[152:155], v[208:211], v[78:81]
	v_mfma_f32_16x16x32_bf16 v[74:77], v[160:163], v[208:211], v[74:77]
	s_setprio 0
	s_setprio 1
	v_mfma_f32_16x16x32_bf16 v[118:121], v[164:167], v[180:183], v[118:121]
	v_mfma_f32_16x16x32_bf16 v[114:117], v[172:175], v[180:183], v[114:117]
	v_mfma_f32_16x16x32_bf16 v[102:105], v[164:167], v[188:191], v[102:105]
	v_mfma_f32_16x16x32_bf16 v[98:101], v[172:175], v[188:191], v[98:101]
	v_mfma_f32_16x16x32_bf16 v[86:89], v[164:167], v[196:199], v[86:89]
	v_mfma_f32_16x16x32_bf16 v[82:85], v[172:175], v[196:199], v[82:85]
	v_mfma_f32_16x16x32_bf16 v[70:73], v[164:167], v[204:207], v[70:73]
	v_mfma_f32_16x16x32_bf16 v[66:69], v[172:175], v[204:207], v[66:69]
	v_mfma_f32_16x16x32_bf16 v[118:121], v[168:171], v[184:187], v[118:121]
	v_mfma_f32_16x16x32_bf16 v[114:117], v[176:179], v[184:187], v[114:117]
	v_mfma_f32_16x16x32_bf16 v[102:105], v[168:171], v[192:195], v[102:105]
	v_mfma_f32_16x16x32_bf16 v[98:101], v[176:179], v[192:195], v[98:101]
	v_mfma_f32_16x16x32_bf16 v[86:89], v[168:171], v[200:203], v[86:89]
	v_mfma_f32_16x16x32_bf16 v[82:85], v[176:179], v[200:203], v[82:85]
	v_mfma_f32_16x16x32_bf16 v[70:73], v[168:171], v[208:211], v[70:73]
	s_setprio 3
	s_barrier
; #define PG8_STAGE(bufoff, gbase, voff) do { _Pragma("unroll") for (int _i = 0; _i < 2; ++_i) \
;         __builtin_amdgcn_global_load_lds((const unsigned*)((const char*)(gbase) + (voff)[_i]), (PG8_LAS unsigned*)(lds + (bufoff) + ldsw + _i * 8192), 16, 0, 0); } while (0)
; #define PG8_LDA(dst, b, h) do { _Pragma("unroll") for (int m = 0; m < 4; ++m) _Pragma("unroll") for (int k = 0; k < 2; ++k) dst[m][k] = *(const PG8_LAS bf16x8*)(lds + PG8_SA(b, h) + aoff + m * 2048 + k * 1024); } while (0)
; #define PG8_LDB(dst, b, h) do { _Pragma("unroll") for (int n = 0; n < 2; ++n) _Pragma("unroll") for (int k = 0; k < 2; ++k) dst[n][k] = *(const PG8_LAS bf16x8*)(lds + PG8_SB(b, h) + boff + n * 2048 + k * 1024); } while (0)
; template <class Epi, class Sched, bool ALIGN_EPI = false, bool SP2 = false>
; __device__ __forceinline__ void gemm_phase(PG8_LAS unsigned char* lds, const Gemm g, const Sched& S, const Epi& E) {
;     ...
;         for (int t = 0; t < nt; t += 2) {
;             const bool last = (t == nt - 2);
;             const char* a1 = cA + (size_t)(t + 1) * kstep;
;             const char* a2 = last ? nA : cA + (size_t)(t + 2) * kstep; const char* b2 = last ? nB : cB + (size_t)(t + 2) * kstep;
;             const char* a3 = a2 + kstep; const char* b3 = b2 + kstep;
;             if (last && has_next) S.a_ready(nxt);
;             if constexpr (SP2) {
;             PG8_LDB(B0, 0, 0); PG8_LDB(B1, 0, 1); PG8_SCHED; PG8_LDA(At, 0, 0); PG8_STAGE(PG8_SA(1, 1), a1 + hstep, voffA);
;             PG8_WAIT_V(8); PG8_WAIT_L(0); PG8_BAR; PG8_MMA(0, 0, At, B0); PG8_MMA(0, 1, At, B1); PG8_BAR; PG8_SCHED;
;             PG8_LDA(At, 0, 1); PG8_STAGE(PG8_SB(0, 0), b2, voffB); PG8_STAGE(PG8_SB(0, 1), b2 + hstep, voffB); PG8_STAGE(PG8_SA(0, 0), a2, voffA);
;             PG8_WAIT_V(8); PG8_WAIT_L(0); PG8_BAR; PG8_MMA(1, 0, At, B0); PG8_MMA(1, 1, At, B1); PG8_BAR; PG8_SCHED;
;             PG8_LDB(B0, 1, 0); PG8_LDB(B1, 1, 1); PG8_SCHED; PG8_LDA(At, 1, 0); PG8_STAGE(PG8_SA(0, 1), a2 + hstep, voffA);
;             PG8_WAIT_V(8); PG8_WAIT_L(0); PG8_BAR; PG8_MMA(0, 0, At, B0); PG8_MMA(0, 1, At, B1); PG8_BAR; PG8_SCHED;
;             PG8_LDA(At, 1, 1); PG8_STAGE(PG8_SB(1, 0), b3, voffB); PG8_STAGE(PG8_SB(1, 1), b3 + hstep, voffB); PG8_STAGE(PG8_SA(1, 0), a3, voffA);
;             PG8_WAIT_V(8); PG8_WAIT_L(0); PG8_BAR; PG8_MMA(1, 0, At, B0); PG8_MMA(1, 1, At, B1); PG8_BAR; PG8_SCHED;
	v_mfma_f32_16x16x32_bf16 v[66:69], v[176:179], v[208:211], v[66:69]
	s_setprio 0
	s_add_i32 s18, s77, s52
	v_lshl_add_u64 v[212:213], v[212:213], 0, s[14:15]
	s_mov_b32 m0, s18
	ds_read_b128 v[180:183], v146 offset:49152
	ds_read_b128 v[184:187], v146 offset:50176
	ds_read_b128 v[188:191], v146 offset:51200
	ds_read_b128 v[192:195], v146 offset:52224
	ds_read_b128 v[196:199], v146 offset:53248
	ds_read_b128 v[200:203], v146 offset:54272
	ds_read_b128 v[204:207], v146 offset:55296
	ds_read_b128 v[208:211], v146 offset:56320
	global_load_lds_dwordx4 v[212:213], off
	v_lshl_add_u64 v[212:213], v[214:215], 0, s[14:15]
	s_add_i32 m0, s18, 0x2000
	s_add_i32 s18, s78, s52
	global_load_lds_dwordx4 v[212:213], off
	v_lshl_add_u64 v[212:213], v[216:217], 0, s[14:15]
	s_mov_b32 m0, s18
	s_nop 0
	global_load_lds_dwordx4 v[212:213], off
	v_lshl_add_u64 v[212:213], v[218:219], 0, s[14:15]
	s_add_i32 m0, s18, 0x2000
	s_nop 0
	global_load_lds_dwordx4 v[212:213], off
	v_lshl_add_u64 v[212:213], v[220:221], 0, s[14:15]
	s_mov_b32 m0, s58
	s_nop 0
	global_load_lds_dwordx4 v[212:213], off
	v_lshl_add_u64 v[212:213], v[222:223], 0, s[14:15]
	s_mov_b32 m0, s59
	s_nop 0
	global_load_lds_dwordx4 v[212:213], off
	s_waitcnt vmcnt(8)
	s_waitcnt lgkmcnt(0)
	s_barrier
	s_setprio 1
	s_waitcnt lgkmcnt(0)
	v_mfma_f32_16x16x32_bf16 v[62:65], v[148:151], v[180:183], v[62:65]
	v_mfma_f32_16x16x32_bf16 v[58:61], v[156:159], v[180:183], v[58:61]
	v_mfma_f32_16x16x32_bf16 v[46:49], v[148:151], v[188:191], v[46:49]
	v_mfma_f32_16x16x32_bf16 v[42:45], v[156:159], v[188:191], v[42:45]
	v_mfma_f32_16x16x32_bf16 v[30:33], v[148:151], v[196:199], v[30:33]
	v_mfma_f32_16x16x32_bf16 v[26:29], v[156:159], v[196:199], v[26:29]
	v_mfma_f32_16x16x32_bf16 v[14:17], v[148:151], v[204:207], v[14:17]
	v_mfma_f32_16x16x32_bf16 v[10:13], v[156:159], v[204:207], v[10:13]
	v_mfma_f32_16x16x32_bf16 v[62:65], v[152:155], v[184:187], v[62:65]
	v_mfma_f32_16x16x32_bf16 v[58:61], v[160:163], v[184:187], v[58:61]
	v_mfma_f32_16x16x32_bf16 v[46:49], v[152:155], v[192:195], v[46:49]
	v_mfma_f32_16x16x32_bf16 v[42:45], v[160:163], v[192:195], v[42:45]
	v_mfma_f32_16x16x32_bf16 v[30:33], v[152:155], v[200:203], v[30:33]
	v_mfma_f32_16x16x32_bf16 v[26:29], v[160:163], v[200:203], v[26:29]
	v_mfma_f32_16x16x32_bf16 v[14:17], v[152:155], v[208:211], v[14:17]
	v_mfma_f32_16x16x32_bf16 v[10:13], v[160:163], v[208:211], v[10:13]
	s_setprio 0
	s_setprio 1
	v_mfma_f32_16x16x32_bf16 v[54:57], v[164:167], v[180:183], v[54:57]
	v_mfma_f32_16x16x32_bf16 v[50:53], v[172:175], v[180:183], v[50:53]
	v_mfma_f32_16x16x32_bf16 v[38:41], v[164:167], v[188:191], v[38:41]
	v_mfma_f32_16x16x32_bf16 v[34:37], v[172:175], v[188:191], v[34:37]
	v_mfma_f32_16x16x32_bf16 v[22:25], v[164:167], v[196:199], v[22:25]
	v_mfma_f32_16x16x32_bf16 v[18:21], v[172:175], v[196:199], v[18:21]
	v_mfma_f32_16x16x32_bf16 v[6:9], v[164:167], v[204:207], v[6:9]
	v_mfma_f32_16x16x32_bf16 v[2:5], v[172:175], v[204:207], v[2:5]
	v_mfma_f32_16x16x32_bf16 v[54:57], v[168:171], v[184:187], v[54:57]
	v_mfma_f32_16x16x32_bf16 v[50:53], v[176:179], v[184:187], v[50:53]
	v_mfma_f32_16x16x32_bf16 v[38:41], v[168:171], v[192:195], v[38:41]
	v_mfma_f32_16x16x32_bf16 v[34:37], v[176:179], v[192:195], v[34:37]
	v_mfma_f32_16x16x32_bf16 v[22:25], v[168:171], v[200:203], v[22:25]
	v_mfma_f32_16x16x32_bf16 v[18:21], v[176:179], v[200:203], v[18:21]
	v_mfma_f32_16x16x32_bf16 v[6:9], v[168:171], v[208:211], v[6:9]
	s_setprio 3
	s_barrier
	v_mfma_f32_16x16x32_bf16 v[2:5], v[176:179], v[208:211], v[2:5]
	s_setprio 0
	s_add_u32 s46, s46, 0x100
	s_addc_u32 s47, s47, 0
	s_add_u32 s48, s48, 0x100
	s_addc_u32 s49, s49, 0
	s_cmp_ge_i32 s76, s60
	s_mov_b32 s30, s76
	s_cbranch_scc0 .LBB0_777

; #define PG8_STAGE(bufoff, gbase, voff) do { _Pragma("unroll") for (int _i = 0; _i < 2; ++_i) \
;         __builtin_amdgcn_global_load_lds((const unsigned*)((const char*)(gbase) + (voff)[_i]), (PG8_LAS unsigned*)(lds + (bufoff) + ldsw + _i * 8192), 16, 0, 0); } while (0)
; #define PG8_LDA(dst, b, h) do { _Pragma("unroll") for (int m = 0; m < 4; ++m) _Pragma("unroll") for (int k = 0; k < 2; ++k) dst[m][k] = *(const PG8_LAS bf16x8*)(lds + PG8_SA(b, h) + aoff + m * 2048 + k * 1024); } while (0)
; #define PG8_LDB(dst, b, h) do { _Pragma("unroll") for (int n = 0; n < 2; ++n) _Pragma("unroll") for (int k = 0; k < 2; ++k) dst[n][k] = *(const PG8_LAS bf16x8*)(lds + PG8_SB(b, h) + boff + n * 2048 + k * 1024); } while (0)
; #define PG8_MMA(ai, bj, At, Bt) do { __builtin_amdgcn_s_setprio(1); _Pragma("unroll") for (int m = 0; m < 4; ++m) _Pragma("unroll") for (int n = 0; n < 2; ++n) _Pragma("unroll") for (int k = 0; k < 2; ++k) \
;         acc[ai][bj][m][n] = __builtin_amdgcn_mfma_f32_16x16x32_bf16(Bt[n][k], At[m][k], acc[ai][bj][m][n], 0, 0, 0); __builtin_amdgcn_s_setprio(0); } while (0)
; #define PG8_WAIT_V(n) asm volatile("s_waitcnt vmcnt(" #n ")" ::: "memory")
; template <class Epi, class Sched, bool ALIGN_EPI = false, bool SP2 = false>
; __device__ __forceinline__ void gemm_phase(PG8_LAS unsigned char* lds, const Gemm g, const Sched& S, const Epi& E) {
;     ...
;             PG8_LDB(B0, 0, 0); PG8_LDB(B1, 0, 1); PG8_SCHED; PG8_LDA(At, 0, 0); PG8_STAGE(PG8_SA(1, 1), a1 + hstep, voffA);
;             PG8_WAIT_V(8); PG8_WAIT_L(0); PG8_BAR; PG8_MMA(0, 0, At, B0); PG8_MMA(0, 1, At, B1); PG8_BAR; PG8_SCHED;
;             PG8_LDA(At, 0, 1); PG8_STAGE(PG8_SB(0, 0), b2, voffB); PG8_STAGE(PG8_SB(0, 1), b2 + hstep, voffB); PG8_STAGE(PG8_SA(0, 0), a2, voffA);
;             PG8_WAIT_V(8); PG8_WAIT_L(0); PG8_BAR; PG8_MMA(1, 0, At, B0); PG8_MMA(1, 1, At, B1); PG8_BAR; PG8_SCHED;
;             PG8_LDB(B0, 1, 0); PG8_LDB(B1, 1, 1); PG8_SCHED; PG8_LDA(At, 1, 0); PG8_STAGE(PG8_SA(0, 1), a2 + hstep, voffA);
;             PG8_WAIT_V(8); PG8_WAIT_L(0); PG8_BAR; PG8_MMA(0, 0, At, B0); PG8_MMA(0, 1, At, B1); PG8_BAR; PG8_SCHED;
;             PG8_LDA(At, 1, 1); PG8_STAGE(PG8_SB(1, 0), b3, voffB); PG8_STAGE(PG8_SB(1, 1), b3 + hstep, voffB); PG8_STAGE(PG8_SA(1, 0), a3, voffA);
;             PG8_WAIT_V(8); PG8_WAIT_L(0); PG8_BAR; PG8_MMA(1, 0, At, B0); PG8_MMA(1, 1, At, B1); PG8_BAR; PG8_SCHED;
.LBB0_892:
	ds_read_b128 v[98:101], v239
	ds_read_b128 v[110:113], v239 offset:1024
	ds_read_b128 v[122:125], v239 offset:2048
	ds_read_b128 v[134:137], v239 offset:3072
	ds_read_b128 v[138:141], v240
	ds_read_b128 v[142:145], v240 offset:1024
	ds_read_b128 v[146:149], v240 offset:2048
	ds_read_b128 v[150:153], v240 offset:3072
	s_add_u32 s18, s34, 0xfff50080
	s_addc_u32 s19, s35, -1
	s_cmp_eq_u32 s60, 40
	s_cselect_b32 s39, s1, s19
	s_cselect_b32 s38, s0, s18
	s_cselect_b32 s37, s31, s59
	s_cselect_b32 s36, s30, s58
	v_lshl_add_u64 v[208:209], s[34:35], 0, v[198:199]
	s_add_i32 m0, s41, 0xc000
	ds_read_b128 v[162:165], v241
	ds_read_b128 v[166:169], v241 offset:1024
	ds_read_b128 v[170:173], v241 offset:2048
	ds_read_b128 v[174:177], v241 offset:3072
	ds_read_b128 v[178:181], v241 offset:4096
	ds_read_b128 v[182:185], v241 offset:5120
	ds_read_b128 v[186:189], v241 offset:6144
	ds_read_b128 v[204:207], v241 offset:7168
	global_load_lds_dwordx4 v[208:209], off
	v_lshl_add_u64 v[208:209], s[34:35], 0, v[200:201]
	s_add_i32 m0, s41, 0xe000
	s_nop 0
	global_load_lds_dwordx4 v[208:209], off
	s_waitcnt vmcnt(8)
	s_waitcnt lgkmcnt(0)
	s_barrier
	s_setprio 1
	s_waitcnt lgkmcnt(0)
	v_mfma_f32_16x16x32_bf16 v[158:161], v[98:101], v[162:165], v[158:161]
	v_mfma_f32_16x16x32_bf16 v[154:157], v[122:125], v[162:165], v[154:157]
	v_mfma_f32_16x16x32_bf16 v[118:121], v[98:101], v[170:173], v[118:121]
	v_mfma_f32_16x16x32_bf16 v[114:117], v[122:125], v[170:173], v[114:117]
	v_mfma_f32_16x16x32_bf16 v[94:97], v[98:101], v[178:181], v[94:97]
	v_mfma_f32_16x16x32_bf16 v[90:93], v[122:125], v[178:181], v[90:93]
	v_mfma_f32_16x16x32_bf16 v[78:81], v[98:101], v[186:189], v[78:81]
	v_mfma_f32_16x16x32_bf16 v[74:77], v[122:125], v[186:189], v[74:77]
	v_mfma_f32_16x16x32_bf16 v[158:161], v[110:113], v[166:169], v[158:161]
	v_mfma_f32_16x16x32_bf16 v[154:157], v[134:137], v[166:169], v[154:157]
	v_mfma_f32_16x16x32_bf16 v[118:121], v[110:113], v[174:177], v[118:121]
	v_mfma_f32_16x16x32_bf16 v[114:117], v[134:137], v[174:177], v[114:117]
	v_mfma_f32_16x16x32_bf16 v[94:97], v[110:113], v[182:185], v[94:97]
	v_mfma_f32_16x16x32_bf16 v[90:93], v[134:137], v[182:185], v[90:93]
	v_mfma_f32_16x16x32_bf16 v[78:81], v[110:113], v[204:207], v[78:81]
	v_mfma_f32_16x16x32_bf16 v[74:77], v[134:137], v[204:207], v[74:77]
	s_setprio 0
	s_setprio 1
	v_mfma_f32_16x16x32_bf16 v[130:133], v[138:141], v[162:165], v[130:133]
	v_mfma_f32_16x16x32_bf16 v[126:129], v[146:149], v[162:165], v[126:129]
	v_mfma_f32_16x16x32_bf16 v[106:109], v[138:141], v[170:173], v[106:109]
	v_mfma_f32_16x16x32_bf16 v[102:105], v[146:149], v[170:173], v[102:105]
	v_mfma_f32_16x16x32_bf16 v[86:89], v[138:141], v[178:181], v[86:89]
	v_mfma_f32_16x16x32_bf16 v[82:85], v[146:149], v[178:181], v[82:85]
	v_mfma_f32_16x16x32_bf16 v[70:73], v[138:141], v[186:189], v[70:73]
	v_mfma_f32_16x16x32_bf16 v[66:69], v[146:149], v[186:189], v[66:69]
	v_mfma_f32_16x16x32_bf16 v[130:133], v[142:145], v[166:169], v[130:133]
	v_mfma_f32_16x16x32_bf16 v[126:129], v[150:153], v[166:169], v[126:129]
	v_mfma_f32_16x16x32_bf16 v[106:109], v[142:145], v[174:177], v[106:109]
	v_mfma_f32_16x16x32_bf16 v[102:105], v[150:153], v[174:177], v[102:105]
	v_mfma_f32_16x16x32_bf16 v[86:89], v[142:145], v[182:185], v[86:89]
	v_mfma_f32_16x16x32_bf16 v[82:85], v[150:153], v[182:185], v[82:85]
	v_mfma_f32_16x16x32_bf16 v[70:73], v[142:145], v[204:207], v[70:73]
	s_setprio 3
	s_barrier
	v_mfma_f32_16x16x32_bf16 v[66:69], v[150:153], v[204:207], v[66:69]
	s_setprio 0
	s_add_i32 s18, s52, s40
	v_lshl_add_u64 v[208:209], s[36:37], 0, v[192:193]
	s_mov_b32 m0, s18
	ds_read_b128 v[162:165], v241 offset:16384
	ds_read_b128 v[166:169], v241 offset:17408
	ds_read_b128 v[170:173], v241 offset:18432
	ds_read_b128 v[174:177], v241 offset:19456
	ds_read_b128 v[178:181], v241 offset:20480
	ds_read_b128 v[182:185], v241 offset:21504
	ds_read_b128 v[186:189], v241 offset:22528
	ds_read_b128 v[204:207], v241 offset:23552
	global_load_lds_dwordx4 v[208:209], off
	s_add_i32 m0, s18, 0x2000
	s_add_u32 s18, s36, 0xb0000
	v_lshl_add_u64 v[210:211], s[36:37], 0, v[196:197]
	s_addc_u32 s19, s37, 0
	s_add_i32 s61, s53, s40
	global_load_lds_dwordx4 v[210:211], off
	v_lshl_add_u64 v[212:213], s[18:19], 0, v[192:193]
	s_mov_b32 m0, s61
	v_lshl_add_u64 v[214:215], s[38:39], 0, v[194:195]
	global_load_lds_dwordx4 v[212:213], off
	v_lshl_add_u64 v[212:213], s[18:19], 0, v[196:197]
	s_add_i32 m0, s61, 0x2000
	s_nop 0
	global_load_lds_dwordx4 v[212:213], off
	v_lshl_add_u64 v[212:213], s[38:39], 0, v[190:191]
	s_mov_b32 m0, s41
	s_nop 0
	global_load_lds_dwordx4 v[212:213], off
	s_mov_b32 m0, s42
	s_nop 0
	global_load_lds_dwordx4 v[214:215], off
	s_waitcnt vmcnt(8)
	s_waitcnt lgkmcnt(0)
	s_barrier
; #define PG8_STAGE(bufoff, gbase, voff) do { _Pragma("unroll") for (int _i = 0; _i < 2; ++_i) \
;         __builtin_amdgcn_global_load_lds((const unsigned*)((const char*)(gbase) + (voff)[_i]), (PG8_LAS unsigned*)(lds + (bufoff) + ldsw + _i * 8192), 16, 0, 0); } while (0)
; #define PG8_LDA(dst, b, h) do { _Pragma("unroll") for (int m = 0; m < 4; ++m) _Pragma("unroll") for (int k = 0; k < 2; ++k) dst[m][k] = *(const PG8_LAS bf16x8*)(lds + PG8_SA(b, h) + aoff + m * 2048 + k * 1024); } while (0)
; #define PG8_LDB(dst, b, h) do { _Pragma("unroll") for (int n = 0; n < 2; ++n) _Pragma("unroll") for (int k = 0; k < 2; ++k) dst[n][k] = *(const PG8_LAS bf16x8*)(lds + PG8_SB(b, h) + boff + n * 2048 + k * 1024); } while (0)
; #define PG8_MMA(ai, bj, At, Bt) do { __builtin_amdgcn_s_setprio(1); _Pragma("unroll") for (int m = 0; m < 4; ++m) _Pragma("unroll") for (int n = 0; n < 2; ++n) _Pragma("unroll") for (int k = 0; k < 2; ++k) \
;         acc[ai][bj][m][n] = __builtin_amdgcn_mfma_f32_16x16x32_bf16(Bt[n][k], At[m][k], acc[ai][bj][m][n], 0, 0, 0); __builtin_amdgcn_s_setprio(0); } while (0)
; #define PG8_WAIT_V(n) asm volatile("s_waitcnt vmcnt(" #n ")" ::: "memory")
; template <class Epi, class Sched, bool ALIGN_EPI = false, bool SP2 = false>
; __device__ __forceinline__ void gemm_phase(PG8_LAS unsigned char* lds, const Gemm g, const Sched& S, const Epi& E) {
;     ...
;             PG8_LDB(B0, 0, 0); PG8_LDB(B1, 0, 1); PG8_SCHED; PG8_LDA(At, 0, 0); PG8_STAGE(PG8_SA(1, 1), a1 + hstep, voffA);
;             PG8_WAIT_V(8); PG8_WAIT_L(0); PG8_BAR; PG8_MMA(0, 0, At, B0); PG8_MMA(0, 1, At, B1); PG8_BAR; PG8_SCHED;
;             PG8_LDA(At, 0, 1); PG8_STAGE(PG8_SB(0, 0), b2, voffB); PG8_STAGE(PG8_SB(0, 1), b2 + hstep, voffB); PG8_STAGE(PG8_SA(0, 0), a2, voffA);
;             PG8_WAIT_V(8); PG8_WAIT_L(0); PG8_BAR; PG8_MMA(1, 0, At, B0); PG8_MMA(1, 1, At, B1); PG8_BAR; PG8_SCHED;
;             PG8_LDB(B0, 1, 0); PG8_LDB(B1, 1, 1); PG8_SCHED; PG8_LDA(At, 1, 0); PG8_STAGE(PG8_SA(0, 1), a2 + hstep, voffA);
;             PG8_WAIT_V(8); PG8_WAIT_L(0); PG8_BAR; PG8_MMA(0, 0, At, B0); PG8_MMA(0, 1, At, B1); PG8_BAR; PG8_SCHED;
;             PG8_LDA(At, 1, 1); PG8_STAGE(PG8_SB(1, 0), b3, voffB); PG8_STAGE(PG8_SB(1, 1), b3 + hstep, voffB); PG8_STAGE(PG8_SA(1, 0), a3, voffA);
;             PG8_WAIT_V(8); PG8_WAIT_L(0); PG8_BAR; PG8_MMA(1, 0, At, B0); PG8_MMA(1, 1, At, B1); PG8_BAR; PG8_SCHED;
	s_setprio 1
	s_waitcnt lgkmcnt(0)
	v_mfma_f32_16x16x32_bf16 v[62:65], v[98:101], v[162:165], v[62:65]
	v_mfma_f32_16x16x32_bf16 v[58:61], v[122:125], v[162:165], v[58:61]
	v_mfma_f32_16x16x32_bf16 v[46:49], v[98:101], v[170:173], v[46:49]
	v_mfma_f32_16x16x32_bf16 v[42:45], v[122:125], v[170:173], v[42:45]
	v_mfma_f32_16x16x32_bf16 v[30:33], v[98:101], v[178:181], v[30:33]
	v_mfma_f32_16x16x32_bf16 v[26:29], v[122:125], v[178:181], v[26:29]
	v_mfma_f32_16x16x32_bf16 v[14:17], v[98:101], v[186:189], v[14:17]
	v_mfma_f32_16x16x32_bf16 v[10:13], v[122:125], v[186:189], v[10:13]
	v_mfma_f32_16x16x32_bf16 v[62:65], v[110:113], v[166:169], v[62:65]
	v_mfma_f32_16x16x32_bf16 v[58:61], v[134:137], v[166:169], v[58:61]
	v_mfma_f32_16x16x32_bf16 v[46:49], v[110:113], v[174:177], v[46:49]
	v_mfma_f32_16x16x32_bf16 v[42:45], v[134:137], v[174:177], v[42:45]
	v_mfma_f32_16x16x32_bf16 v[30:33], v[110:113], v[182:185], v[30:33]
	v_mfma_f32_16x16x32_bf16 v[26:29], v[134:137], v[182:185], v[26:29]
	v_mfma_f32_16x16x32_bf16 v[14:17], v[110:113], v[204:207], v[14:17]
	v_mfma_f32_16x16x32_bf16 v[10:13], v[134:137], v[204:207], v[10:13]
	s_setprio 0
	s_setprio 1
	v_mfma_f32_16x16x32_bf16 v[54:57], v[138:141], v[162:165], v[54:57]
	v_mfma_f32_16x16x32_bf16 v[50:53], v[146:149], v[162:165], v[50:53]
	v_mfma_f32_16x16x32_bf16 v[38:41], v[138:141], v[170:173], v[38:41]
	v_mfma_f32_16x16x32_bf16 v[34:37], v[146:149], v[170:173], v[34:37]
	v_mfma_f32_16x16x32_bf16 v[22:25], v[138:141], v[178:181], v[22:25]
	v_mfma_f32_16x16x32_bf16 v[18:21], v[146:149], v[178:181], v[18:21]
	v_mfma_f32_16x16x32_bf16 v[6:9], v[138:141], v[186:189], v[6:9]
	v_mfma_f32_16x16x32_bf16 v[2:5], v[146:149], v[186:189], v[2:5]
	v_mfma_f32_16x16x32_bf16 v[54:57], v[142:145], v[166:169], v[54:57]
	v_mfma_f32_16x16x32_bf16 v[50:53], v[150:153], v[166:169], v[50:53]
	v_mfma_f32_16x16x32_bf16 v[38:41], v[142:145], v[174:177], v[38:41]
	v_mfma_f32_16x16x32_bf16 v[34:37], v[150:153], v[174:177], v[34:37]
	v_mfma_f32_16x16x32_bf16 v[22:25], v[142:145], v[182:185], v[22:25]
	v_mfma_f32_16x16x32_bf16 v[18:21], v[150:153], v[182:185], v[18:21]
	v_mfma_f32_16x16x32_bf16 v[6:9], v[142:145], v[204:207], v[6:9]
	s_setprio 3
	s_barrier
	v_mfma_f32_16x16x32_bf16 v[2:5], v[150:153], v[204:207], v[2:5]
	s_setprio 0
	s_add_i32 s61, 0, 0x18000
	s_add_i32 s62, 0, 0x1c000
	v_add_u32_e32 v134, s61, v237
	v_add_u32_e32 v150, s62, v237
	ds_read_b128 v[98:101], v134
	ds_read_b128 v[110:113], v134 offset:1024
	ds_read_b128 v[122:125], v134 offset:2048
	ds_read_b128 v[134:137], v134 offset:3072
	ds_read_b128 v[138:141], v150
	ds_read_b128 v[142:145], v150 offset:1024
	ds_read_b128 v[146:149], v150 offset:2048
	ds_read_b128 v[150:153], v150 offset:3072
	s_add_u32 s18, s38, 0xb0000
	s_addc_u32 s19, s39, 0
	s_mov_b32 m0, s43
	v_lshl_add_u64 v[216:217], s[18:19], 0, v[190:191]
	ds_read_b128 v[162:165], v241 offset:32768
	ds_read_b128 v[166:169], v241 offset:33792
	ds_read_b128 v[170:173], v241 offset:34816
	ds_read_b128 v[174:177], v241 offset:35840
	ds_read_b128 v[178:181], v241 offset:36864
	ds_read_b128 v[182:185], v241 offset:37888
	ds_read_b128 v[186:189], v241 offset:38912
	ds_read_b128 v[204:207], v241 offset:39936
	global_load_lds_dwordx4 v[216:217], off
	v_lshl_add_u64 v[216:217], s[18:19], 0, v[194:195]
	s_mov_b32 m0, s44
	s_nop 0
	global_load_lds_dwordx4 v[216:217], off
	s_waitcnt vmcnt(8)
	s_waitcnt lgkmcnt(0)
	s_barrier
	s_setprio 1
	s_waitcnt lgkmcnt(0)
	v_mfma_f32_16x16x32_bf16 v[158:161], v[98:101], v[162:165], v[158:161]
	v_mfma_f32_16x16x32_bf16 v[154:157], v[122:125], v[162:165], v[154:157]
	v_mfma_f32_16x16x32_bf16 v[118:121], v[98:101], v[170:173], v[118:121]
	v_mfma_f32_16x16x32_bf16 v[114:117], v[122:125], v[170:173], v[114:117]
	v_mfma_f32_16x16x32_bf16 v[94:97], v[98:101], v[178:181], v[94:97]
	v_mfma_f32_16x16x32_bf16 v[90:93], v[122:125], v[178:181], v[90:93]
	v_mfma_f32_16x16x32_bf16 v[78:81], v[98:101], v[186:189], v[78:81]
	v_mfma_f32_16x16x32_bf16 v[74:77], v[122:125], v[186:189], v[74:77]
	v_mfma_f32_16x16x32_bf16 v[158:161], v[110:113], v[166:169], v[158:161]
	v_mfma_f32_16x16x32_bf16 v[154:157], v[134:137], v[166:169], v[154:157]
	v_mfma_f32_16x16x32_bf16 v[118:121], v[110:113], v[174:177], v[118:121]
	v_mfma_f32_16x16x32_bf16 v[114:117], v[134:137], v[174:177], v[114:117]
	v_mfma_f32_16x16x32_bf16 v[94:97], v[110:113], v[182:185], v[94:97]
	v_mfma_f32_16x16x32_bf16 v[90:93], v[134:137], v[182:185], v[90:93]
	v_mfma_f32_16x16x32_bf16 v[78:81], v[110:113], v[204:207], v[78:81]
	v_mfma_f32_16x16x32_bf16 v[74:77], v[134:137], v[204:207], v[74:77]
	s_setprio 0
	s_setprio 1
	v_mfma_f32_16x16x32_bf16 v[130:133], v[138:141], v[162:165], v[130:133]
	v_mfma_f32_16x16x32_bf16 v[126:129], v[146:149], v[162:165], v[126:129]
	v_mfma_f32_16x16x32_bf16 v[106:109], v[138:141], v[170:173], v[106:109]
	v_mfma_f32_16x16x32_bf16 v[102:105], v[146:149], v[170:173], v[102:105]
	v_mfma_f32_16x16x32_bf16 v[86:89], v[138:141], v[178:181], v[86:89]
	v_mfma_f32_16x16x32_bf16 v[82:85], v[146:149], v[178:181], v[82:85]
	v_mfma_f32_16x16x32_bf16 v[70:73], v[138:141], v[186:189], v[70:73]
	v_mfma_f32_16x16x32_bf16 v[66:69], v[146:149], v[186:189], v[66:69]
	v_mfma_f32_16x16x32_bf16 v[130:133], v[142:145], v[166:169], v[130:133]
	v_mfma_f32_16x16x32_bf16 v[126:129], v[150:153], v[166:169], v[126:129]
	v_mfma_f32_16x16x32_bf16 v[106:109], v[142:145], v[174:177], v[106:109]
	v_mfma_f32_16x16x32_bf16 v[102:105], v[150:153], v[174:177], v[102:105]
	v_mfma_f32_16x16x32_bf16 v[86:89], v[142:145], v[182:185], v[86:89]
	v_mfma_f32_16x16x32_bf16 v[82:85], v[150:153], v[182:185], v[82:85]
	v_mfma_f32_16x16x32_bf16 v[70:73], v[142:145], v[204:207], v[70:73]
	s_setprio 3
	s_barrier
; #define PG8_STAGE(bufoff, gbase, voff) do { _Pragma("unroll") for (int _i = 0; _i < 2; ++_i) \
;         __builtin_amdgcn_global_load_lds((const unsigned*)((const char*)(gbase) + (voff)[_i]), (PG8_LAS unsigned*)(lds + (bufoff) + ldsw + _i * 8192), 16, 0, 0); } while (0)
; #define PG8_LDA(dst, b, h) do { _Pragma("unroll") for (int m = 0; m < 4; ++m) _Pragma("unroll") for (int k = 0; k < 2; ++k) dst[m][k] = *(const PG8_LAS bf16x8*)(lds + PG8_SA(b, h) + aoff + m * 2048 + k * 1024); } while (0)
; #define PG8_LDB(dst, b, h) do { _Pragma("unroll") for (int n = 0; n < 2; ++n) _Pragma("unroll") for (int k = 0; k < 2; ++k) dst[n][k] = *(const PG8_LAS bf16x8*)(lds + PG8_SB(b, h) + boff + n * 2048 + k * 1024); } while (0)
; #define PG8_WAIT_V(n) asm volatile("s_waitcnt vmcnt(" #n ")" ::: "memory")
; #define PG8_WAIT_L(n) asm volatile("s_waitcnt lgkmcnt(" #n ")" ::: "memory")
;     __device__ __forceinline__ void operator()(const f32x4 (&acc)[2][2][4][2], const Unit& u, int wr, int wc, int fr, int fq) const {
;     ...
;                 for (int bj = 0; bj < 2; ++bj) bva[ai][m][bj] = *(const u32x4*)(Xb + (size_t)(row0 + ai * HALF + m * 16) * DM + col0 + bj * HALF);
; template <class Epi, class Sched, bool ALIGN_EPI = false, bool SP2 = false>
; __device__ __forceinline__ void gemm_phase(PG8_LAS unsigned char* lds, const Gemm g, const Sched& S, const Epi& E) {
;     ...
;             PG8_LDB(B0, 0, 0); PG8_LDB(B1, 0, 1); PG8_SCHED; PG8_LDA(At, 0, 0); PG8_STAGE(PG8_SA(1, 1), a1 + hstep, voffA);
;             PG8_WAIT_V(8); PG8_WAIT_L(0); PG8_BAR; PG8_MMA(0, 0, At, B0); PG8_MMA(0, 1, At, B1); PG8_BAR; PG8_SCHED;
;             PG8_LDA(At, 0, 1); PG8_STAGE(PG8_SB(0, 0), b2, voffB); PG8_STAGE(PG8_SB(0, 1), b2 + hstep, voffB); PG8_STAGE(PG8_SA(0, 0), a2, voffA);
;             PG8_WAIT_V(8); PG8_WAIT_L(0); PG8_BAR; PG8_MMA(1, 0, At, B0); PG8_MMA(1, 1, At, B1); PG8_BAR; PG8_SCHED;
;             PG8_LDB(B0, 1, 0); PG8_LDB(B1, 1, 1); PG8_SCHED; PG8_LDA(At, 1, 0); PG8_STAGE(PG8_SA(0, 1), a2 + hstep, voffA);
;             PG8_WAIT_V(8); PG8_WAIT_L(0); PG8_BAR; PG8_MMA(0, 0, At, B0); PG8_MMA(0, 1, At, B1); PG8_BAR; PG8_SCHED;
;             PG8_LDA(At, 1, 1); PG8_STAGE(PG8_SB(1, 0), b3, voffB); PG8_STAGE(PG8_SB(1, 1), b3 + hstep, voffB); PG8_STAGE(PG8_SA(1, 0), a3, voffA);
;             PG8_WAIT_V(8); PG8_WAIT_L(0); PG8_BAR; PG8_MMA(1, 0, At, B0); PG8_MMA(1, 1, At, B1); PG8_BAR; PG8_SCHED;
	v_mfma_f32_16x16x32_bf16 v[66:69], v[150:153], v[204:207], v[66:69]
	s_setprio 0
	s_add_i32 s18, s61, s40
	v_lshl_add_u64 v[208:209], v[208:209], 0, s[16:17]
	s_mov_b32 m0, s18
	ds_read_b128 v[162:165], v241 offset:49152
	ds_read_b128 v[166:169], v241 offset:50176
	ds_read_b128 v[170:173], v241 offset:51200
	ds_read_b128 v[174:177], v241 offset:52224
	ds_read_b128 v[178:181], v241 offset:53248
	ds_read_b128 v[182:185], v241 offset:54272
	ds_read_b128 v[186:189], v241 offset:55296
	ds_read_b128 v[204:207], v241 offset:56320
	global_load_lds_dwordx4 v[208:209], off
	s_add_i32 m0, s18, 0x2000
	s_add_u32 s18, s36, 0xb0080
	v_lshl_add_u64 v[208:209], v[210:211], 0, s[16:17]
	s_addc_u32 s19, s37, 0
	s_add_i32 s36, s62, s40
	global_load_lds_dwordx4 v[208:209], off
	v_lshl_add_u64 v[208:209], s[18:19], 0, v[192:193]
	s_mov_b32 m0, s36
	s_nop 0
	global_load_lds_dwordx4 v[208:209], off
	v_lshl_add_u64 v[208:209], s[18:19], 0, v[196:197]
	s_add_i32 m0, s36, 0x2000
	s_nop 0
	global_load_lds_dwordx4 v[208:209], off
	v_lshl_add_u64 v[208:209], v[212:213], 0, s[16:17]
	s_mov_b32 m0, s46
	s_nop 0
	global_load_lds_dwordx4 v[208:209], off
	v_lshl_add_u64 v[208:209], v[214:215], 0, s[16:17]
	s_mov_b32 m0, s47
	s_nop 0
	global_load_lds_dwordx4 v[208:209], off
	s_waitcnt vmcnt(8)
	s_waitcnt lgkmcnt(0)
	s_barrier
	s_setprio 1
	s_waitcnt lgkmcnt(0)
	v_mfma_f32_16x16x32_bf16 v[62:65], v[98:101], v[162:165], v[62:65]
	v_mfma_f32_16x16x32_bf16 v[58:61], v[122:125], v[162:165], v[58:61]
	v_mfma_f32_16x16x32_bf16 v[46:49], v[98:101], v[170:173], v[46:49]
	v_mfma_f32_16x16x32_bf16 v[42:45], v[122:125], v[170:173], v[42:45]
	v_mfma_f32_16x16x32_bf16 v[30:33], v[98:101], v[178:181], v[30:33]
	v_mfma_f32_16x16x32_bf16 v[26:29], v[122:125], v[178:181], v[26:29]
	v_mfma_f32_16x16x32_bf16 v[14:17], v[98:101], v[186:189], v[14:17]
	v_mfma_f32_16x16x32_bf16 v[10:13], v[122:125], v[186:189], v[10:13]
	v_mfma_f32_16x16x32_bf16 v[62:65], v[110:113], v[166:169], v[62:65]
	v_mfma_f32_16x16x32_bf16 v[58:61], v[134:137], v[166:169], v[58:61]
	v_mfma_f32_16x16x32_bf16 v[46:49], v[110:113], v[174:177], v[46:49]
	v_mfma_f32_16x16x32_bf16 v[42:45], v[134:137], v[174:177], v[42:45]
	v_mfma_f32_16x16x32_bf16 v[30:33], v[110:113], v[182:185], v[30:33]
	v_mfma_f32_16x16x32_bf16 v[26:29], v[134:137], v[182:185], v[26:29]
	v_mfma_f32_16x16x32_bf16 v[14:17], v[110:113], v[204:207], v[14:17]
	v_mfma_f32_16x16x32_bf16 v[10:13], v[134:137], v[204:207], v[10:13]
	s_setprio 0
	s_setprio 1
	v_mfma_f32_16x16x32_bf16 v[54:57], v[138:141], v[162:165], v[54:57]
	v_mfma_f32_16x16x32_bf16 v[50:53], v[146:149], v[162:165], v[50:53]
	v_mfma_f32_16x16x32_bf16 v[38:41], v[138:141], v[170:173], v[38:41]
	v_mfma_f32_16x16x32_bf16 v[34:37], v[146:149], v[170:173], v[34:37]
	v_mfma_f32_16x16x32_bf16 v[22:25], v[138:141], v[178:181], v[22:25]
	v_mfma_f32_16x16x32_bf16 v[18:21], v[146:149], v[178:181], v[18:21]
	v_mfma_f32_16x16x32_bf16 v[6:9], v[138:141], v[186:189], v[6:9]
	v_mfma_f32_16x16x32_bf16 v[2:5], v[146:149], v[186:189], v[2:5]
	v_mfma_f32_16x16x32_bf16 v[54:57], v[142:145], v[166:169], v[54:57]
	v_mfma_f32_16x16x32_bf16 v[50:53], v[150:153], v[166:169], v[50:53]
	v_mfma_f32_16x16x32_bf16 v[38:41], v[142:145], v[174:177], v[38:41]
	v_mfma_f32_16x16x32_bf16 v[34:37], v[150:153], v[174:177], v[34:37]
	v_mfma_f32_16x16x32_bf16 v[22:25], v[142:145], v[182:185], v[22:25]
	v_mfma_f32_16x16x32_bf16 v[18:21], v[150:153], v[182:185], v[18:21]
	v_mfma_f32_16x16x32_bf16 v[6:9], v[142:145], v[204:207], v[6:9]
	s_setprio 3
	s_barrier
	v_mfma_f32_16x16x32_bf16 v[2:5], v[150:153], v[204:207], v[2:5]
	s_setprio 0
	s_add_i32 s60, s60, 2
	s_add_u32 s34, s34, 0x100
	s_addc_u32 s35, s35, 0
	s_add_u32 s58, s58, 0x100
	s_addc_u32 s59, s59, 0
	s_cmp_gt_u32 s60, 41
	s_cbranch_scc1 .Lrp_gen_p5
	s_cmp_lg_u32 s60, 40
	s_cbranch_scc1 .LBB0_892
	s_cmpk_lg_i32 s33, 0x100
	s_cbranch_scc1 .LBB0_892
	ds_read_b128 v[98:101], v239
	ds_read_b128 v[110:113], v239 offset:1024
	ds_read_b128 v[122:125], v239 offset:2048
	ds_read_b128 v[134:137], v239 offset:3072
	ds_read_b128 v[138:141], v240
	ds_read_b128 v[142:145], v240 offset:1024
	ds_read_b128 v[146:149], v240 offset:2048
	ds_read_b128 v[150:153], v240 offset:3072
	s_add_u32 s18, s34, 0xfff50080
	s_addc_u32 s19, s35, -1
	s_cmp_eq_u32 s60, 40
	s_cselect_b32 s39, s1, s19
	s_cselect_b32 s38, s0, s18
	s_cselect_b32 s37, s31, s59
	s_cselect_b32 s36, s30, s58
	v_lshl_add_u64 v[208:209], s[34:35], 0, v[198:199]
	s_add_i32 m0, s41, 0xc000
	ds_read_b128 v[162:165], v241
	ds_read_b128 v[166:169], v241 offset:1024
	ds_read_b128 v[170:173], v241 offset:2048
	ds_read_b128 v[174:177], v241 offset:3072
	ds_read_b128 v[178:181], v241 offset:4096
	ds_read_b128 v[182:185], v241 offset:5120
	ds_read_b128 v[186:189], v241 offset:6144
	ds_read_b128 v[204:207], v241 offset:7168
	global_load_lds_dwordx4 v[208:209], off
	v_lshl_add_u64 v[208:209], s[34:35], 0, v[200:201]
	s_add_i32 m0, s41, 0xe000
	s_nop 0
	global_load_lds_dwordx4 v[208:209], off
	v_lshl_or_b32 v255, s12, 8, v238
	v_lshl_add_u32 v235, s57, 8, v1
	v_lshlrev_b32_e32 v255, 1, v255
	v_lshl_add_u32 v255, v235, 11, v255
	s_mov_b64 s[84:85], s[20:21]
	global_load_dwordx4 v[242:245], v255, s[84:85]
	global_load_dwordx4 v[208:211], v255, s[84:85] offset:256
	s_add_u32 s84, s20, 0x8000
	s_addc_u32 s85, s21, 0
	global_load_dwordx4 v[212:215], v255, s[84:85]
	global_load_dwordx4 v[216:219], v255, s[84:85] offset:256
	s_add_u32 s84, s20, 0x10000
	s_addc_u32 s85, s21, 0
	global_load_dwordx4 v[220:223], v255, s[84:85]
	global_load_dwordx4 v[224:227], v255, s[84:85] offset:256
	s_add_u32 s84, s20, 0x18000
	s_addc_u32 s85, s21, 0
	global_load_dwordx4 v[228:231], v255, s[84:85]
	global_load_dwordx4 v[232:235], v255, s[84:85] offset:256
	s_add_u32 s84, s20, 0x40000
	s_addc_u32 s85, s21, 0
	global_load_dwordx4 v[246:249], v255, s[84:85]
	global_load_dwordx4 v[250:253], v255, s[84:85] offset:256
	s_waitcnt vmcnt(18)
	s_waitcnt lgkmcnt(0)
	s_barrier
; #define PG8_STAGE(bufoff, gbase, voff) do { _Pragma("unroll") for (int _i = 0; _i < 2; ++_i) \
;         __builtin_amdgcn_global_load_lds((const unsigned*)((const char*)(gbase) + (voff)[_i]), (PG8_LAS unsigned*)(lds + (bufoff) + ldsw + _i * 8192), 16, 0, 0); } while (0)
; #define PG8_LDA(dst, b, h) do { _Pragma("unroll") for (int m = 0; m < 4; ++m) _Pragma("unroll") for (int k = 0; k < 2; ++k) dst[m][k] = *(const PG8_LAS bf16x8*)(lds + PG8_SA(b, h) + aoff + m * 2048 + k * 1024); } while (0)
; #define PG8_LDB(dst, b, h) do { _Pragma("unroll") for (int n = 0; n < 2; ++n) _Pragma("unroll") for (int k = 0; k < 2; ++k) dst[n][k] = *(const PG8_LAS bf16x8*)(lds + PG8_SB(b, h) + boff + n * 2048 + k * 1024); } while (0)
; #define PG8_MMA(ai, bj, At, Bt) do { __builtin_amdgcn_s_setprio(1); _Pragma("unroll") for (int m = 0; m < 4; ++m) _Pragma("unroll") for (int n = 0; n < 2; ++n) _Pragma("unroll") for (int k = 0; k < 2; ++k) \
;         acc[ai][bj][m][n] = __builtin_amdgcn_mfma_f32_16x16x32_bf16(Bt[n][k], At[m][k], acc[ai][bj][m][n], 0, 0, 0); __builtin_amdgcn_s_setprio(0); } while (0)
; #define PG8_WAIT_V(n) asm volatile("s_waitcnt vmcnt(" #n ")" ::: "memory")
; template <class Epi, class Sched, bool ALIGN_EPI = false, bool SP2 = false>
; __device__ __forceinline__ void gemm_phase(PG8_LAS unsigned char* lds, const Gemm g, const Sched& S, const Epi& E) {
;     ...
;             PG8_LDB(B0, 0, 0); PG8_LDB(B1, 0, 1); PG8_SCHED; PG8_LDA(At, 0, 0); PG8_STAGE(PG8_SA(1, 1), a1 + hstep, voffA);
;             PG8_WAIT_V(8); PG8_WAIT_L(0); PG8_BAR; PG8_MMA(0, 0, At, B0); PG8_MMA(0, 1, At, B1); PG8_BAR; PG8_SCHED;
;             PG8_LDA(At, 0, 1); PG8_STAGE(PG8_SB(0, 0), b2, voffB); PG8_STAGE(PG8_SB(0, 1), b2 + hstep, voffB); PG8_STAGE(PG8_SA(0, 0), a2, voffA);
;             PG8_WAIT_V(8); PG8_WAIT_L(0); PG8_BAR; PG8_MMA(1, 0, At, B0); PG8_MMA(1, 1, At, B1); PG8_BAR; PG8_SCHED;
;             PG8_LDB(B0, 1, 0); PG8_LDB(B1, 1, 1); PG8_SCHED; PG8_LDA(At, 1, 0); PG8_STAGE(PG8_SA(0, 1), a2 + hstep, voffA);
;             PG8_WAIT_V(8); PG8_WAIT_L(0); PG8_BAR; PG8_MMA(0, 0, At, B0); PG8_MMA(0, 1, At, B1); PG8_BAR; PG8_SCHED;
;             PG8_LDA(At, 1, 1); PG8_STAGE(PG8_SB(1, 0), b3, voffB); PG8_STAGE(PG8_SB(1, 1), b3 + hstep, voffB); PG8_STAGE(PG8_SA(1, 0), a3, voffA);
;             PG8_WAIT_V(8); PG8_WAIT_L(0); PG8_BAR; PG8_MMA(1, 0, At, B0); PG8_MMA(1, 1, At, B1); PG8_BAR; PG8_SCHED;
	s_setprio 1
	s_waitcnt lgkmcnt(0)
	v_mfma_f32_16x16x32_bf16 v[158:161], v[98:101], v[162:165], v[158:161]
	v_mfma_f32_16x16x32_bf16 v[154:157], v[122:125], v[162:165], v[154:157]
	v_mfma_f32_16x16x32_bf16 v[118:121], v[98:101], v[170:173], v[118:121]
	v_mfma_f32_16x16x32_bf16 v[114:117], v[122:125], v[170:173], v[114:117]
	v_mfma_f32_16x16x32_bf16 v[94:97], v[98:101], v[178:181], v[94:97]
	v_mfma_f32_16x16x32_bf16 v[90:93], v[122:125], v[178:181], v[90:93]
	v_mfma_f32_16x16x32_bf16 v[78:81], v[98:101], v[186:189], v[78:81]
	v_mfma_f32_16x16x32_bf16 v[74:77], v[122:125], v[186:189], v[74:77]
	v_mfma_f32_16x16x32_bf16 v[158:161], v[110:113], v[166:169], v[158:161]
	v_mfma_f32_16x16x32_bf16 v[154:157], v[134:137], v[166:169], v[154:157]
	v_mfma_f32_16x16x32_bf16 v[118:121], v[110:113], v[174:177], v[118:121]
	v_mfma_f32_16x16x32_bf16 v[114:117], v[134:137], v[174:177], v[114:117]
	v_mfma_f32_16x16x32_bf16 v[94:97], v[110:113], v[182:185], v[94:97]
	v_mfma_f32_16x16x32_bf16 v[90:93], v[134:137], v[182:185], v[90:93]
	v_mfma_f32_16x16x32_bf16 v[78:81], v[110:113], v[204:207], v[78:81]
	v_mfma_f32_16x16x32_bf16 v[74:77], v[134:137], v[204:207], v[74:77]
	s_setprio 0
	s_setprio 1
	v_mfma_f32_16x16x32_bf16 v[130:133], v[138:141], v[162:165], v[130:133]
	v_mfma_f32_16x16x32_bf16 v[126:129], v[146:149], v[162:165], v[126:129]
	v_mfma_f32_16x16x32_bf16 v[106:109], v[138:141], v[170:173], v[106:109]
	v_mfma_f32_16x16x32_bf16 v[102:105], v[146:149], v[170:173], v[102:105]
	v_mfma_f32_16x16x32_bf16 v[86:89], v[138:141], v[178:181], v[86:89]
	v_mfma_f32_16x16x32_bf16 v[82:85], v[146:149], v[178:181], v[82:85]
	v_mfma_f32_16x16x32_bf16 v[70:73], v[138:141], v[186:189], v[70:73]
	v_mfma_f32_16x16x32_bf16 v[66:69], v[146:149], v[186:189], v[66:69]
	v_mfma_f32_16x16x32_bf16 v[130:133], v[142:145], v[166:169], v[130:133]
	v_mfma_f32_16x16x32_bf16 v[126:129], v[150:153], v[166:169], v[126:129]
	v_mfma_f32_16x16x32_bf16 v[106:109], v[142:145], v[174:177], v[106:109]
	v_mfma_f32_16x16x32_bf16 v[102:105], v[150:153], v[174:177], v[102:105]
	v_mfma_f32_16x16x32_bf16 v[86:89], v[142:145], v[182:185], v[86:89]
	v_mfma_f32_16x16x32_bf16 v[82:85], v[150:153], v[182:185], v[82:85]
	v_mfma_f32_16x16x32_bf16 v[70:73], v[142:145], v[204:207], v[70:73]
	s_setprio 3
	s_barrier
	v_mfma_f32_16x16x32_bf16 v[66:69], v[150:153], v[204:207], v[66:69]
	s_setprio 0
	s_add_i32 s18, s52, s40
	s_mov_b32 m0, s18
	ds_read_b128 v[162:165], v241 offset:16384
	ds_read_b128 v[166:169], v241 offset:17408
	ds_read_b128 v[170:173], v241 offset:18432
	ds_read_b128 v[174:177], v241 offset:19456
	ds_read_b128 v[178:181], v241 offset:20480
	ds_read_b128 v[182:185], v241 offset:21504
	ds_read_b128 v[186:189], v241 offset:22528
	ds_read_b128 v[204:207], v241 offset:23552
	s_add_i32 m0, s18, 0x2000
	s_add_u32 s18, s36, 0xb0000
	s_addc_u32 s19, s37, 0
	s_add_i32 s61, s53, s40
	s_mov_b32 m0, s61
	s_add_i32 m0, s61, 0x2000
	s_nop 0
	s_mov_b32 m0, s41
	s_nop 0
	s_mov_b32 m0, s42
	s_nop 0
	s_waitcnt vmcnt(12)
	s_waitcnt lgkmcnt(0)
	s_barrier
	s_setprio 1
	s_waitcnt lgkmcnt(0)
	v_mfma_f32_16x16x32_bf16 v[62:65], v[98:101], v[162:165], v[62:65]
	v_mfma_f32_16x16x32_bf16 v[58:61], v[122:125], v[162:165], v[58:61]
	v_mfma_f32_16x16x32_bf16 v[46:49], v[98:101], v[170:173], v[46:49]
	v_mfma_f32_16x16x32_bf16 v[42:45], v[122:125], v[170:173], v[42:45]
	v_mfma_f32_16x16x32_bf16 v[30:33], v[98:101], v[178:181], v[30:33]
	v_mfma_f32_16x16x32_bf16 v[26:29], v[122:125], v[178:181], v[26:29]
	v_mfma_f32_16x16x32_bf16 v[14:17], v[98:101], v[186:189], v[14:17]
	v_mfma_f32_16x16x32_bf16 v[10:13], v[122:125], v[186:189], v[10:13]
	v_mfma_f32_16x16x32_bf16 v[62:65], v[110:113], v[166:169], v[62:65]
	v_mfma_f32_16x16x32_bf16 v[58:61], v[134:137], v[166:169], v[58:61]
	v_mfma_f32_16x16x32_bf16 v[46:49], v[110:113], v[174:177], v[46:49]
	v_mfma_f32_16x16x32_bf16 v[42:45], v[134:137], v[174:177], v[42:45]
	v_mfma_f32_16x16x32_bf16 v[30:33], v[110:113], v[182:185], v[30:33]
	v_mfma_f32_16x16x32_bf16 v[26:29], v[134:137], v[182:185], v[26:29]
	v_mfma_f32_16x16x32_bf16 v[14:17], v[110:113], v[204:207], v[14:17]
	v_mfma_f32_16x16x32_bf16 v[10:13], v[134:137], v[204:207], v[10:13]
	s_setprio 0
	s_setprio 1
	v_mfma_f32_16x16x32_bf16 v[54:57], v[138:141], v[162:165], v[54:57]
	v_mfma_f32_16x16x32_bf16 v[50:53], v[146:149], v[162:165], v[50:53]
	v_mfma_f32_16x16x32_bf16 v[38:41], v[138:141], v[170:173], v[38:41]
	v_mfma_f32_16x16x32_bf16 v[34:37], v[146:149], v[170:173], v[34:37]
	v_mfma_f32_16x16x32_bf16 v[22:25], v[138:141], v[178:181], v[22:25]
	v_mfma_f32_16x16x32_bf16 v[18:21], v[146:149], v[178:181], v[18:21]
	v_mfma_f32_16x16x32_bf16 v[6:9], v[138:141], v[186:189], v[6:9]
	v_mfma_f32_16x16x32_bf16 v[2:5], v[146:149], v[186:189], v[2:5]
	v_mfma_f32_16x16x32_bf16 v[54:57], v[142:145], v[166:169], v[54:57]
	v_mfma_f32_16x16x32_bf16 v[50:53], v[150:153], v[166:169], v[50:53]
	v_mfma_f32_16x16x32_bf16 v[38:41], v[142:145], v[174:177], v[38:41]
	v_mfma_f32_16x16x32_bf16 v[34:37], v[150:153], v[174:177], v[34:37]
	v_mfma_f32_16x16x32_bf16 v[22:25], v[142:145], v[182:185], v[22:25]
	v_mfma_f32_16x16x32_bf16 v[18:21], v[150:153], v[182:185], v[18:21]
	v_mfma_f32_16x16x32_bf16 v[6:9], v[142:145], v[204:207], v[6:9]
	s_setprio 3
	s_barrier
; #define PG8_STAGE(bufoff, gbase, voff) do { _Pragma("unroll") for (int _i = 0; _i < 2; ++_i) \
;         __builtin_amdgcn_global_load_lds((const unsigned*)((const char*)(gbase) + (voff)[_i]), (PG8_LAS unsigned*)(lds + (bufoff) + ldsw + _i * 8192), 16, 0, 0); } while (0)
; #define PG8_LDA(dst, b, h) do { _Pragma("unroll") for (int m = 0; m < 4; ++m) _Pragma("unroll") for (int k = 0; k < 2; ++k) dst[m][k] = *(const PG8_LAS bf16x8*)(lds + PG8_SA(b, h) + aoff + m * 2048 + k * 1024); } while (0)
; #define PG8_LDB(dst, b, h) do { _Pragma("unroll") for (int n = 0; n < 2; ++n) _Pragma("unroll") for (int k = 0; k < 2; ++k) dst[n][k] = *(const PG8_LAS bf16x8*)(lds + PG8_SB(b, h) + boff + n * 2048 + k * 1024); } while (0)
; #define PG8_MMA(ai, bj, At, Bt) do { __builtin_amdgcn_s_setprio(1); _Pragma("unroll") for (int m = 0; m < 4; ++m) _Pragma("unroll") for (int n = 0; n < 2; ++n) _Pragma("unroll") for (int k = 0; k < 2; ++k) \
;         acc[ai][bj][m][n] = __builtin_amdgcn_mfma_f32_16x16x32_bf16(Bt[n][k], At[m][k], acc[ai][bj][m][n], 0, 0, 0); __builtin_amdgcn_s_setprio(0); } while (0)
; #define PG8_WAIT_V(n) asm volatile("s_waitcnt vmcnt(" #n ")" ::: "memory")
; template <class Epi, class Sched, bool ALIGN_EPI = false, bool SP2 = false>
; __device__ __forceinline__ void gemm_phase(PG8_LAS unsigned char* lds, const Gemm g, const Sched& S, const Epi& E) {
;     ...
;             PG8_LDB(B0, 0, 0); PG8_LDB(B1, 0, 1); PG8_SCHED; PG8_LDA(At, 0, 0); PG8_STAGE(PG8_SA(1, 1), a1 + hstep, voffA);
;             PG8_WAIT_V(8); PG8_WAIT_L(0); PG8_BAR; PG8_MMA(0, 0, At, B0); PG8_MMA(0, 1, At, B1); PG8_BAR; PG8_SCHED;
;             PG8_LDA(At, 0, 1); PG8_STAGE(PG8_SB(0, 0), b2, voffB); PG8_STAGE(PG8_SB(0, 1), b2 + hstep, voffB); PG8_STAGE(PG8_SA(0, 0), a2, voffA);
;             PG8_WAIT_V(8); PG8_WAIT_L(0); PG8_BAR; PG8_MMA(1, 0, At, B0); PG8_MMA(1, 1, At, B1); PG8_BAR; PG8_SCHED;
;             PG8_LDB(B0, 1, 0); PG8_LDB(B1, 1, 1); PG8_SCHED; PG8_LDA(At, 1, 0); PG8_STAGE(PG8_SA(0, 1), a2 + hstep, voffA);
;             PG8_WAIT_V(8); PG8_WAIT_L(0); PG8_BAR; PG8_MMA(0, 0, At, B0); PG8_MMA(0, 1, At, B1); PG8_BAR; PG8_SCHED;
;             PG8_LDA(At, 1, 1); PG8_STAGE(PG8_SB(1, 0), b3, voffB); PG8_STAGE(PG8_SB(1, 1), b3 + hstep, voffB); PG8_STAGE(PG8_SA(1, 0), a3, voffA);
;             PG8_WAIT_V(8); PG8_WAIT_L(0); PG8_BAR; PG8_MMA(1, 0, At, B0); PG8_MMA(1, 1, At, B1); PG8_BAR; PG8_SCHED;
	v_mfma_f32_16x16x32_bf16 v[2:5], v[150:153], v[204:207], v[2:5]
	s_setprio 0
	s_add_i32 s61, 0, 0x18000
	s_add_i32 s62, 0, 0x1c000
	v_add_u32_e32 v134, s61, v237
	v_add_u32_e32 v150, s62, v237
	ds_read_b128 v[98:101], v134
	ds_read_b128 v[110:113], v134 offset:1024
	ds_read_b128 v[122:125], v134 offset:2048
	ds_read_b128 v[134:137], v134 offset:3072
	ds_read_b128 v[138:141], v150
	ds_read_b128 v[142:145], v150 offset:1024
	ds_read_b128 v[146:149], v150 offset:2048
	ds_read_b128 v[150:153], v150 offset:3072
	s_add_u32 s18, s38, 0xb0000
	s_addc_u32 s19, s39, 0
	s_mov_b32 m0, s43
	ds_read_b128 v[162:165], v241 offset:32768
	ds_read_b128 v[166:169], v241 offset:33792
	ds_read_b128 v[170:173], v241 offset:34816
	ds_read_b128 v[174:177], v241 offset:35840
	ds_read_b128 v[178:181], v241 offset:36864
	ds_read_b128 v[182:185], v241 offset:37888
	ds_read_b128 v[186:189], v241 offset:38912
	ds_read_b128 v[204:207], v241 offset:39936
	s_mov_b32 m0, s44
	s_nop 0
	s_waitcnt vmcnt(10)
	s_waitcnt lgkmcnt(0)
	s_barrier
	s_setprio 1
	s_waitcnt lgkmcnt(0)
	v_mfma_f32_16x16x32_bf16 v[158:161], v[98:101], v[162:165], v[158:161]
	v_mfma_f32_16x16x32_bf16 v[154:157], v[122:125], v[162:165], v[154:157]
	v_mfma_f32_16x16x32_bf16 v[118:121], v[98:101], v[170:173], v[118:121]
	v_mfma_f32_16x16x32_bf16 v[114:117], v[122:125], v[170:173], v[114:117]
	v_mfma_f32_16x16x32_bf16 v[94:97], v[98:101], v[178:181], v[94:97]
	v_mfma_f32_16x16x32_bf16 v[90:93], v[122:125], v[178:181], v[90:93]
	v_mfma_f32_16x16x32_bf16 v[78:81], v[98:101], v[186:189], v[78:81]
	v_mfma_f32_16x16x32_bf16 v[74:77], v[122:125], v[186:189], v[74:77]
	v_mfma_f32_16x16x32_bf16 v[158:161], v[110:113], v[166:169], v[158:161]
	v_mfma_f32_16x16x32_bf16 v[154:157], v[134:137], v[166:169], v[154:157]
	v_mfma_f32_16x16x32_bf16 v[118:121], v[110:113], v[174:177], v[118:121]
	v_mfma_f32_16x16x32_bf16 v[114:117], v[134:137], v[174:177], v[114:117]
	v_mfma_f32_16x16x32_bf16 v[94:97], v[110:113], v[182:185], v[94:97]
	v_mfma_f32_16x16x32_bf16 v[90:93], v[134:137], v[182:185], v[90:93]
	v_mfma_f32_16x16x32_bf16 v[78:81], v[110:113], v[204:207], v[78:81]
	v_mfma_f32_16x16x32_bf16 v[74:77], v[134:137], v[204:207], v[74:77]
	s_setprio 0
	s_setprio 1
	v_mfma_f32_16x16x32_bf16 v[130:133], v[138:141], v[162:165], v[130:133]
	v_mfma_f32_16x16x32_bf16 v[126:129], v[146:149], v[162:165], v[126:129]
	v_mfma_f32_16x16x32_bf16 v[106:109], v[138:141], v[170:173], v[106:109]
	v_mfma_f32_16x16x32_bf16 v[102:105], v[146:149], v[170:173], v[102:105]
	v_mfma_f32_16x16x32_bf16 v[86:89], v[138:141], v[178:181], v[86:89]
	v_mfma_f32_16x16x32_bf16 v[82:85], v[146:149], v[178:181], v[82:85]
	v_mfma_f32_16x16x32_bf16 v[70:73], v[138:141], v[186:189], v[70:73]
	v_mfma_f32_16x16x32_bf16 v[66:69], v[146:149], v[186:189], v[66:69]
	v_mfma_f32_16x16x32_bf16 v[130:133], v[142:145], v[166:169], v[130:133]
	v_mfma_f32_16x16x32_bf16 v[126:129], v[150:153], v[166:169], v[126:129]
	v_mfma_f32_16x16x32_bf16 v[106:109], v[142:145], v[174:177], v[106:109]
	v_mfma_f32_16x16x32_bf16 v[102:105], v[150:153], v[174:177], v[102:105]
	v_mfma_f32_16x16x32_bf16 v[86:89], v[142:145], v[182:185], v[86:89]
	v_mfma_f32_16x16x32_bf16 v[82:85], v[150:153], v[182:185], v[82:85]
	v_mfma_f32_16x16x32_bf16 v[70:73], v[142:145], v[204:207], v[70:73]
	s_setprio 3
	s_barrier
	v_mfma_f32_16x16x32_bf16 v[66:69], v[150:153], v[204:207], v[66:69]
	s_setprio 0
	s_add_i32 s18, s61, s40
	s_mov_b32 m0, s18
	ds_read_b128 v[162:165], v241 offset:49152
	ds_read_b128 v[166:169], v241 offset:50176
	ds_read_b128 v[170:173], v241 offset:51200
	ds_read_b128 v[174:177], v241 offset:52224
	ds_read_b128 v[178:181], v241 offset:53248
	ds_read_b128 v[182:185], v241 offset:54272
	ds_read_b128 v[186:189], v241 offset:55296
	ds_read_b128 v[204:207], v241 offset:56320
	s_add_i32 m0, s18, 0x2000
	s_add_u32 s18, s36, 0xb0080
	s_addc_u32 s19, s37, 0
	s_add_i32 s36, s62, s40
	s_mov_b32 m0, s36
	s_nop 0
	s_add_i32 m0, s36, 0x2000
	s_nop 0
	s_mov_b32 m0, s46
	s_nop 0
	s_mov_b32 m0, s47
	s_nop 0
	s_waitcnt vmcnt(10)
	s_waitcnt lgkmcnt(0)
	s_barrier
	s_setprio 1
	s_waitcnt lgkmcnt(0)
	v_mfma_f32_16x16x32_bf16 v[62:65], v[98:101], v[162:165], v[62:65]
	v_mfma_f32_16x16x32_bf16 v[58:61], v[122:125], v[162:165], v[58:61]
	v_mfma_f32_16x16x32_bf16 v[46:49], v[98:101], v[170:173], v[46:49]
	v_mfma_f32_16x16x32_bf16 v[42:45], v[122:125], v[170:173], v[42:45]
	v_mfma_f32_16x16x32_bf16 v[30:33], v[98:101], v[178:181], v[30:33]
	v_mfma_f32_16x16x32_bf16 v[26:29], v[122:125], v[178:181], v[26:29]
	v_mfma_f32_16x16x32_bf16 v[14:17], v[98:101], v[186:189], v[14:17]
	v_mfma_f32_16x16x32_bf16 v[10:13], v[122:125], v[186:189], v[10:13]
	v_mfma_f32_16x16x32_bf16 v[62:65], v[110:113], v[166:169], v[62:65]
	v_mfma_f32_16x16x32_bf16 v[58:61], v[134:137], v[166:169], v[58:61]
	v_mfma_f32_16x16x32_bf16 v[46:49], v[110:113], v[174:177], v[46:49]
	v_mfma_f32_16x16x32_bf16 v[42:45], v[134:137], v[174:177], v[42:45]
	v_mfma_f32_16x16x32_bf16 v[30:33], v[110:113], v[182:185], v[30:33]
	v_mfma_f32_16x16x32_bf16 v[26:29], v[134:137], v[182:185], v[26:29]
	v_mfma_f32_16x16x32_bf16 v[14:17], v[110:113], v[204:207], v[14:17]
	v_mfma_f32_16x16x32_bf16 v[10:13], v[134:137], v[204:207], v[10:13]
	s_setprio 0
	s_setprio 1
	v_mfma_f32_16x16x32_bf16 v[54:57], v[138:141], v[162:165], v[54:57]
	v_mfma_f32_16x16x32_bf16 v[50:53], v[146:149], v[162:165], v[50:53]
	v_mfma_f32_16x16x32_bf16 v[38:41], v[138:141], v[170:173], v[38:41]
	v_mfma_f32_16x16x32_bf16 v[34:37], v[146:149], v[170:173], v[34:37]
	v_mfma_f32_16x16x32_bf16 v[22:25], v[138:141], v[178:181], v[22:25]
	v_mfma_f32_16x16x32_bf16 v[18:21], v[146:149], v[178:181], v[18:21]
	v_mfma_f32_16x16x32_bf16 v[6:9], v[138:141], v[186:189], v[6:9]
	v_mfma_f32_16x16x32_bf16 v[2:5], v[146:149], v[186:189], v[2:5]
	v_mfma_f32_16x16x32_bf16 v[54:57], v[142:145], v[166:169], v[54:57]
	v_mfma_f32_16x16x32_bf16 v[50:53], v[150:153], v[166:169], v[50:53]
	v_mfma_f32_16x16x32_bf16 v[38:41], v[142:145], v[174:177], v[38:41]
	v_mfma_f32_16x16x32_bf16 v[34:37], v[150:153], v[174:177], v[34:37]
	v_mfma_f32_16x16x32_bf16 v[22:25], v[142:145], v[182:185], v[22:25]
	v_mfma_f32_16x16x32_bf16 v[18:21], v[150:153], v[182:185], v[18:21]
	v_mfma_f32_16x16x32_bf16 v[6:9], v[142:145], v[204:207], v[6:9]
	s_setprio 3
	s_barrier
	v_mfma_f32_16x16x32_bf16 v[2:5], v[150:153], v[204:207], v[2:5]
	s_setprio 0
	s_add_i32 s60, s60, 2
	s_add_u32 s34, s34, 0x100
	s_addc_u32 s35, s35, 0
	s_add_u32 s58, s58, 0x100
	s_addc_u32 s59, s59, 0
	s_branch .Lrp_done_p5

; #define PG8_STAGE(bufoff, gbase, voff) do { _Pragma("unroll") for (int _i = 0; _i < 2; ++_i) \
;         __builtin_amdgcn_global_load_lds((const unsigned*)((const char*)(gbase) + (voff)[_i]), (PG8_LAS unsigned*)(lds + (bufoff) + ldsw + _i * 8192), 16, 0, 0); } while (0)
; #define PG8_LDA(dst, b, h) do { _Pragma("unroll") for (int m = 0; m < 4; ++m) _Pragma("unroll") for (int k = 0; k < 2; ++k) dst[m][k] = *(const PG8_LAS bf16x8*)(lds + PG8_SA(b, h) + aoff + m * 2048 + k * 1024); } while (0)
; #define PG8_LDB(dst, b, h) do { _Pragma("unroll") for (int n = 0; n < 2; ++n) _Pragma("unroll") for (int k = 0; k < 2; ++k) dst[n][k] = *(const PG8_LAS bf16x8*)(lds + PG8_SB(b, h) + boff + n * 2048 + k * 1024); } while (0)
; #define PG8_MMA(ai, bj, At, Bt) do { __builtin_amdgcn_s_setprio(1); _Pragma("unroll") for (int m = 0; m < 4; ++m) _Pragma("unroll") for (int n = 0; n < 2; ++n) _Pragma("unroll") for (int k = 0; k < 2; ++k) \
;         acc[ai][bj][m][n] = __builtin_amdgcn_mfma_f32_16x16x32_bf16(Bt[n][k], At[m][k], acc[ai][bj][m][n], 0, 0, 0); __builtin_amdgcn_s_setprio(0); } while (0)
; #define PG8_WAIT_V(n) asm volatile("s_waitcnt vmcnt(" #n ")" ::: "memory")
; template <class Epi, class Sched, bool ALIGN_EPI = false, bool SP2 = false>
; __device__ __forceinline__ void gemm_phase(PG8_LAS unsigned char* lds, const Gemm g, const Sched& S, const Epi& E) {
;     ...
;             PG8_LDB(B0, 0, 0); PG8_LDB(B1, 0, 1); PG8_SCHED; PG8_LDA(At, 0, 0); PG8_STAGE(PG8_SA(1, 1), a1 + hstep, voffA);
;             PG8_WAIT_V(8); PG8_WAIT_L(0); PG8_BAR; PG8_MMA(0, 0, At, B0); PG8_MMA(0, 1, At, B1); PG8_BAR; PG8_SCHED;
;             PG8_LDA(At, 0, 1); PG8_STAGE(PG8_SB(0, 0), b2, voffB); PG8_STAGE(PG8_SB(0, 1), b2 + hstep, voffB); PG8_STAGE(PG8_SA(0, 0), a2, voffA);
;             PG8_WAIT_V(8); PG8_WAIT_L(0); PG8_BAR; PG8_MMA(1, 0, At, B0); PG8_MMA(1, 1, At, B1); PG8_BAR; PG8_SCHED;
;             PG8_LDB(B0, 1, 0); PG8_LDB(B1, 1, 1); PG8_SCHED; PG8_LDA(At, 1, 0); PG8_STAGE(PG8_SA(0, 1), a2 + hstep, voffA);
;             PG8_WAIT_V(8); PG8_WAIT_L(0); PG8_BAR; PG8_MMA(0, 0, At, B0); PG8_MMA(0, 1, At, B1); PG8_BAR; PG8_SCHED;
;             PG8_LDA(At, 1, 1); PG8_STAGE(PG8_SB(1, 0), b3, voffB); PG8_STAGE(PG8_SB(1, 1), b3 + hstep, voffB); PG8_STAGE(PG8_SA(1, 0), a3, voffA);
;             PG8_WAIT_V(8); PG8_WAIT_L(0); PG8_BAR; PG8_MMA(1, 0, At, B0); PG8_MMA(1, 1, At, B1); PG8_BAR; PG8_SCHED;
.LBB0_1033:
	ds_read_b128 v[128:131], v202
	ds_read_b128 v[132:135], v202 offset:1024
	ds_read_b128 v[136:139], v202 offset:2048
	ds_read_b128 v[140:143], v202 offset:3072
	ds_read_b128 v[144:147], v203
	ds_read_b128 v[148:151], v203 offset:1024
	ds_read_b128 v[152:155], v203 offset:2048
	ds_read_b128 v[156:159], v203 offset:3072
	s_add_u32 s6, s4, 0xfffc0080
	s_addc_u32 s7, s5, -1
	s_cmp_eq_u32 s62, 12
	s_cselect_b32 s41, s3, s7
	s_cselect_b32 s40, s35, s6
	s_cselect_b32 s7, s31, s61
	s_cselect_b32 s6, s59, s60
	v_lshl_add_u64 v[218:219], s[4:5], 0, v[170:171]
	s_add_i32 m0, s44, 0xc000
	ds_read_b128 v[178:181], v204
	ds_read_b128 v[182:185], v204 offset:1024
	ds_read_b128 v[186:189], v204 offset:2048
	ds_read_b128 v[190:193], v204 offset:3072
	ds_read_b128 v[194:197], v204 offset:4096
	ds_read_b128 v[206:209], v204 offset:5120
	ds_read_b128 v[210:213], v204 offset:6144
	ds_read_b128 v[214:217], v204 offset:7168
	global_load_lds_dwordx4 v[218:219], off
	v_lshl_add_u64 v[218:219], s[4:5], 0, v[172:173]
	s_add_i32 m0, s44, 0xe000
	s_nop 0
	global_load_lds_dwordx4 v[218:219], off
	s_waitcnt vmcnt(8)
	s_waitcnt lgkmcnt(0)
	s_barrier
	s_setprio 1
	s_waitcnt lgkmcnt(0)
	v_mfma_f32_16x16x32_bf16 v[124:127], v[128:131], v[178:181], v[124:127]
	v_mfma_f32_16x16x32_bf16 v[120:123], v[136:139], v[178:181], v[120:123]
	v_mfma_f32_16x16x32_bf16 v[108:111], v[128:131], v[186:189], v[108:111]
	v_mfma_f32_16x16x32_bf16 v[104:107], v[136:139], v[186:189], v[104:107]
	v_mfma_f32_16x16x32_bf16 v[92:95], v[128:131], v[194:197], v[92:95]
	v_mfma_f32_16x16x32_bf16 v[88:91], v[136:139], v[194:197], v[88:91]
	v_mfma_f32_16x16x32_bf16 v[76:79], v[128:131], v[210:213], v[76:79]
	v_mfma_f32_16x16x32_bf16 v[72:75], v[136:139], v[210:213], v[72:75]
	v_mfma_f32_16x16x32_bf16 v[124:127], v[132:135], v[182:185], v[124:127]
	v_mfma_f32_16x16x32_bf16 v[120:123], v[140:143], v[182:185], v[120:123]
	v_mfma_f32_16x16x32_bf16 v[108:111], v[132:135], v[190:193], v[108:111]
	v_mfma_f32_16x16x32_bf16 v[104:107], v[140:143], v[190:193], v[104:107]
	v_mfma_f32_16x16x32_bf16 v[92:95], v[132:135], v[206:209], v[92:95]
	v_mfma_f32_16x16x32_bf16 v[88:91], v[140:143], v[206:209], v[88:91]
	v_mfma_f32_16x16x32_bf16 v[76:79], v[132:135], v[214:217], v[76:79]
	v_mfma_f32_16x16x32_bf16 v[72:75], v[140:143], v[214:217], v[72:75]
	s_setprio 0
	s_setprio 1
	v_mfma_f32_16x16x32_bf16 v[116:119], v[144:147], v[178:181], v[116:119]
	v_mfma_f32_16x16x32_bf16 v[112:115], v[152:155], v[178:181], v[112:115]
	v_mfma_f32_16x16x32_bf16 v[100:103], v[144:147], v[186:189], v[100:103]
	v_mfma_f32_16x16x32_bf16 v[96:99], v[152:155], v[186:189], v[96:99]
	v_mfma_f32_16x16x32_bf16 v[84:87], v[144:147], v[194:197], v[84:87]
	v_mfma_f32_16x16x32_bf16 v[80:83], v[152:155], v[194:197], v[80:83]
	v_mfma_f32_16x16x32_bf16 v[68:71], v[144:147], v[210:213], v[68:71]
	v_mfma_f32_16x16x32_bf16 v[64:67], v[152:155], v[210:213], v[64:67]
	v_mfma_f32_16x16x32_bf16 v[116:119], v[148:151], v[182:185], v[116:119]
	v_mfma_f32_16x16x32_bf16 v[112:115], v[156:159], v[182:185], v[112:115]
	v_mfma_f32_16x16x32_bf16 v[100:103], v[148:151], v[190:193], v[100:103]
	v_mfma_f32_16x16x32_bf16 v[96:99], v[156:159], v[190:193], v[96:99]
	v_mfma_f32_16x16x32_bf16 v[84:87], v[148:151], v[206:209], v[84:87]
	v_mfma_f32_16x16x32_bf16 v[80:83], v[156:159], v[206:209], v[80:83]
	v_mfma_f32_16x16x32_bf16 v[68:71], v[148:151], v[214:217], v[68:71]
	s_setprio 3
	s_barrier
	v_mfma_f32_16x16x32_bf16 v[64:67], v[156:159], v[214:217], v[64:67]
	s_setprio 0
	s_add_i32 s63, s55, s42
	v_lshl_add_u64 v[218:219], s[6:7], 0, v[162:163]
	s_mov_b32 m0, s63
	ds_read_b128 v[178:181], v204 offset:16384
	ds_read_b128 v[182:185], v204 offset:17408
	ds_read_b128 v[186:189], v204 offset:18432
	ds_read_b128 v[190:193], v204 offset:19456
	ds_read_b128 v[194:197], v204 offset:20480
	ds_read_b128 v[206:209], v204 offset:21504
	ds_read_b128 v[210:213], v204 offset:22528
	ds_read_b128 v[214:217], v204 offset:23552
	global_load_lds_dwordx4 v[218:219], off
	s_add_i32 m0, s63, 0x2000
	s_add_u32 s64, s6, 0x40000
	v_lshl_add_u64 v[220:221], s[6:7], 0, v[166:167]
	s_addc_u32 s65, s7, 0
	s_add_i32 s63, s56, s42
	global_load_lds_dwordx4 v[220:221], off
	v_lshl_add_u64 v[222:223], s[64:65], 0, v[162:163]
	s_mov_b32 m0, s63
	v_lshl_add_u64 v[224:225], s[40:41], 0, v[164:165]
	global_load_lds_dwordx4 v[222:223], off
	v_lshl_add_u64 v[222:223], s[64:65], 0, v[166:167]
	s_add_i32 m0, s63, 0x2000
	s_nop 0
	global_load_lds_dwordx4 v[222:223], off
	v_lshl_add_u64 v[222:223], s[40:41], 0, v[160:161]
	s_mov_b32 m0, s44
	s_nop 0
	global_load_lds_dwordx4 v[222:223], off
	s_mov_b32 m0, s45
	s_nop 0
	global_load_lds_dwordx4 v[224:225], off
	s_waitcnt vmcnt(8)
	s_waitcnt lgkmcnt(0)
	s_barrier
; #define PG8_STAGE(bufoff, gbase, voff) do { _Pragma("unroll") for (int _i = 0; _i < 2; ++_i) \
;         __builtin_amdgcn_global_load_lds((const unsigned*)((const char*)(gbase) + (voff)[_i]), (PG8_LAS unsigned*)(lds + (bufoff) + ldsw + _i * 8192), 16, 0, 0); } while (0)
; #define PG8_LDA(dst, b, h) do { _Pragma("unroll") for (int m = 0; m < 4; ++m) _Pragma("unroll") for (int k = 0; k < 2; ++k) dst[m][k] = *(const PG8_LAS bf16x8*)(lds + PG8_SA(b, h) + aoff + m * 2048 + k * 1024); } while (0)
; #define PG8_LDB(dst, b, h) do { _Pragma("unroll") for (int n = 0; n < 2; ++n) _Pragma("unroll") for (int k = 0; k < 2; ++k) dst[n][k] = *(const PG8_LAS bf16x8*)(lds + PG8_SB(b, h) + boff + n * 2048 + k * 1024); } while (0)
; #define PG8_MMA(ai, bj, At, Bt) do { __builtin_amdgcn_s_setprio(1); _Pragma("unroll") for (int m = 0; m < 4; ++m) _Pragma("unroll") for (int n = 0; n < 2; ++n) _Pragma("unroll") for (int k = 0; k < 2; ++k) \
;         acc[ai][bj][m][n] = __builtin_amdgcn_mfma_f32_16x16x32_bf16(Bt[n][k], At[m][k], acc[ai][bj][m][n], 0, 0, 0); __builtin_amdgcn_s_setprio(0); } while (0)
; #define PG8_WAIT_V(n) asm volatile("s_waitcnt vmcnt(" #n ")" ::: "memory")
; template <class Epi, class Sched, bool ALIGN_EPI = false, bool SP2 = false>
; __device__ __forceinline__ void gemm_phase(PG8_LAS unsigned char* lds, const Gemm g, const Sched& S, const Epi& E) {
;     ...
;             PG8_LDB(B0, 0, 0); PG8_LDB(B1, 0, 1); PG8_SCHED; PG8_LDA(At, 0, 0); PG8_STAGE(PG8_SA(1, 1), a1 + hstep, voffA);
;             PG8_WAIT_V(8); PG8_WAIT_L(0); PG8_BAR; PG8_MMA(0, 0, At, B0); PG8_MMA(0, 1, At, B1); PG8_BAR; PG8_SCHED;
;             PG8_LDA(At, 0, 1); PG8_STAGE(PG8_SB(0, 0), b2, voffB); PG8_STAGE(PG8_SB(0, 1), b2 + hstep, voffB); PG8_STAGE(PG8_SA(0, 0), a2, voffA);
;             PG8_WAIT_V(8); PG8_WAIT_L(0); PG8_BAR; PG8_MMA(1, 0, At, B0); PG8_MMA(1, 1, At, B1); PG8_BAR; PG8_SCHED;
;             PG8_LDB(B0, 1, 0); PG8_LDB(B1, 1, 1); PG8_SCHED; PG8_LDA(At, 1, 0); PG8_STAGE(PG8_SA(0, 1), a2 + hstep, voffA);
;             PG8_WAIT_V(8); PG8_WAIT_L(0); PG8_BAR; PG8_MMA(0, 0, At, B0); PG8_MMA(0, 1, At, B1); PG8_BAR; PG8_SCHED;
;             PG8_LDA(At, 1, 1); PG8_STAGE(PG8_SB(1, 0), b3, voffB); PG8_STAGE(PG8_SB(1, 1), b3 + hstep, voffB); PG8_STAGE(PG8_SA(1, 0), a3, voffA);
;             PG8_WAIT_V(8); PG8_WAIT_L(0); PG8_BAR; PG8_MMA(1, 0, At, B0); PG8_MMA(1, 1, At, B1); PG8_BAR; PG8_SCHED;
	s_setprio 1
	s_waitcnt lgkmcnt(0)
	v_mfma_f32_16x16x32_bf16 v[60:63], v[128:131], v[178:181], v[60:63]
	v_mfma_f32_16x16x32_bf16 v[56:59], v[136:139], v[178:181], v[56:59]
	v_mfma_f32_16x16x32_bf16 v[44:47], v[128:131], v[186:189], v[44:47]
	v_mfma_f32_16x16x32_bf16 v[40:43], v[136:139], v[186:189], v[40:43]
	v_mfma_f32_16x16x32_bf16 v[28:31], v[128:131], v[194:197], v[28:31]
	v_mfma_f32_16x16x32_bf16 v[24:27], v[136:139], v[194:197], v[24:27]
	v_mfma_f32_16x16x32_bf16 v[12:15], v[128:131], v[210:213], v[12:15]
	v_mfma_f32_16x16x32_bf16 v[8:11], v[136:139], v[210:213], v[8:11]
	v_mfma_f32_16x16x32_bf16 v[60:63], v[132:135], v[182:185], v[60:63]
	v_mfma_f32_16x16x32_bf16 v[56:59], v[140:143], v[182:185], v[56:59]
	v_mfma_f32_16x16x32_bf16 v[44:47], v[132:135], v[190:193], v[44:47]
	v_mfma_f32_16x16x32_bf16 v[40:43], v[140:143], v[190:193], v[40:43]
	v_mfma_f32_16x16x32_bf16 v[28:31], v[132:135], v[206:209], v[28:31]
	v_mfma_f32_16x16x32_bf16 v[24:27], v[140:143], v[206:209], v[24:27]
	v_mfma_f32_16x16x32_bf16 v[12:15], v[132:135], v[214:217], v[12:15]
	v_mfma_f32_16x16x32_bf16 v[8:11], v[140:143], v[214:217], v[8:11]
	s_setprio 0
	s_setprio 1
	v_mfma_f32_16x16x32_bf16 v[52:55], v[144:147], v[178:181], v[52:55]
	v_mfma_f32_16x16x32_bf16 v[48:51], v[152:155], v[178:181], v[48:51]
	v_mfma_f32_16x16x32_bf16 v[36:39], v[144:147], v[186:189], v[36:39]
	v_mfma_f32_16x16x32_bf16 v[32:35], v[152:155], v[186:189], v[32:35]
	v_mfma_f32_16x16x32_bf16 v[20:23], v[144:147], v[194:197], v[20:23]
	v_mfma_f32_16x16x32_bf16 v[16:19], v[152:155], v[194:197], v[16:19]
	v_mfma_f32_16x16x32_bf16 v[4:7], v[144:147], v[210:213], v[4:7]
	v_mfma_f32_16x16x32_bf16 v[0:3], v[152:155], v[210:213], v[0:3]
	v_mfma_f32_16x16x32_bf16 v[52:55], v[148:151], v[182:185], v[52:55]
	v_mfma_f32_16x16x32_bf16 v[48:51], v[156:159], v[182:185], v[48:51]
	v_mfma_f32_16x16x32_bf16 v[36:39], v[148:151], v[190:193], v[36:39]
	v_mfma_f32_16x16x32_bf16 v[32:35], v[156:159], v[190:193], v[32:35]
	v_mfma_f32_16x16x32_bf16 v[20:23], v[148:151], v[206:209], v[20:23]
	v_mfma_f32_16x16x32_bf16 v[16:19], v[156:159], v[206:209], v[16:19]
	v_mfma_f32_16x16x32_bf16 v[4:7], v[148:151], v[214:217], v[4:7]
	s_setprio 3
	s_barrier
	v_mfma_f32_16x16x32_bf16 v[0:3], v[156:159], v[214:217], v[0:3]
	s_setprio 0
	s_add_i32 s63, 0, 0x18000
	s_add_i32 s64, 0, 0x1c000
	v_add_u32_e32 v140, s63, v199
	v_add_u32_e32 v156, s64, v199
	ds_read_b128 v[128:131], v140
	ds_read_b128 v[132:135], v140 offset:1024
	ds_read_b128 v[136:139], v140 offset:2048
	ds_read_b128 v[140:143], v140 offset:3072
	ds_read_b128 v[144:147], v156
	ds_read_b128 v[148:151], v156 offset:1024
	ds_read_b128 v[152:155], v156 offset:2048
	ds_read_b128 v[156:159], v156 offset:3072
	s_add_u32 s40, s40, 0x40000
	s_addc_u32 s41, s41, 0
	s_mov_b32 m0, s46
	v_lshl_add_u64 v[226:227], s[40:41], 0, v[160:161]
	ds_read_b128 v[178:181], v204 offset:32768
	ds_read_b128 v[182:185], v204 offset:33792
	ds_read_b128 v[186:189], v204 offset:34816
	ds_read_b128 v[190:193], v204 offset:35840
	ds_read_b128 v[194:197], v204 offset:36864
	ds_read_b128 v[206:209], v204 offset:37888
	ds_read_b128 v[210:213], v204 offset:38912
	ds_read_b128 v[214:217], v204 offset:39936
	global_load_lds_dwordx4 v[226:227], off
	v_lshl_add_u64 v[226:227], s[40:41], 0, v[164:165]
	s_mov_b32 m0, s47
	s_nop 0
	global_load_lds_dwordx4 v[226:227], off
	s_waitcnt vmcnt(8)
	s_waitcnt lgkmcnt(0)
	s_barrier
	s_setprio 1
	s_waitcnt lgkmcnt(0)
	v_mfma_f32_16x16x32_bf16 v[124:127], v[128:131], v[178:181], v[124:127]
	v_mfma_f32_16x16x32_bf16 v[120:123], v[136:139], v[178:181], v[120:123]
	v_mfma_f32_16x16x32_bf16 v[108:111], v[128:131], v[186:189], v[108:111]
	v_mfma_f32_16x16x32_bf16 v[104:107], v[136:139], v[186:189], v[104:107]
	v_mfma_f32_16x16x32_bf16 v[92:95], v[128:131], v[194:197], v[92:95]
	v_mfma_f32_16x16x32_bf16 v[88:91], v[136:139], v[194:197], v[88:91]
	v_mfma_f32_16x16x32_bf16 v[76:79], v[128:131], v[210:213], v[76:79]
	v_mfma_f32_16x16x32_bf16 v[72:75], v[136:139], v[210:213], v[72:75]
	v_mfma_f32_16x16x32_bf16 v[124:127], v[132:135], v[182:185], v[124:127]
	v_mfma_f32_16x16x32_bf16 v[120:123], v[140:143], v[182:185], v[120:123]
	v_mfma_f32_16x16x32_bf16 v[108:111], v[132:135], v[190:193], v[108:111]
	v_mfma_f32_16x16x32_bf16 v[104:107], v[140:143], v[190:193], v[104:107]
	v_mfma_f32_16x16x32_bf16 v[92:95], v[132:135], v[206:209], v[92:95]
	v_mfma_f32_16x16x32_bf16 v[88:91], v[140:143], v[206:209], v[88:91]
	v_mfma_f32_16x16x32_bf16 v[76:79], v[132:135], v[214:217], v[76:79]
	v_mfma_f32_16x16x32_bf16 v[72:75], v[140:143], v[214:217], v[72:75]
	s_setprio 0
	s_setprio 1
	v_mfma_f32_16x16x32_bf16 v[116:119], v[144:147], v[178:181], v[116:119]
	v_mfma_f32_16x16x32_bf16 v[112:115], v[152:155], v[178:181], v[112:115]
	v_mfma_f32_16x16x32_bf16 v[100:103], v[144:147], v[186:189], v[100:103]
	v_mfma_f32_16x16x32_bf16 v[96:99], v[152:155], v[186:189], v[96:99]
	v_mfma_f32_16x16x32_bf16 v[84:87], v[144:147], v[194:197], v[84:87]
	v_mfma_f32_16x16x32_bf16 v[80:83], v[152:155], v[194:197], v[80:83]
	v_mfma_f32_16x16x32_bf16 v[68:71], v[144:147], v[210:213], v[68:71]
	v_mfma_f32_16x16x32_bf16 v[64:67], v[152:155], v[210:213], v[64:67]
	v_mfma_f32_16x16x32_bf16 v[116:119], v[148:151], v[182:185], v[116:119]
	v_mfma_f32_16x16x32_bf16 v[112:115], v[156:159], v[182:185], v[112:115]
	v_mfma_f32_16x16x32_bf16 v[100:103], v[148:151], v[190:193], v[100:103]
	v_mfma_f32_16x16x32_bf16 v[96:99], v[156:159], v[190:193], v[96:99]
	v_mfma_f32_16x16x32_bf16 v[84:87], v[148:151], v[206:209], v[84:87]
	v_mfma_f32_16x16x32_bf16 v[80:83], v[156:159], v[206:209], v[80:83]
	v_mfma_f32_16x16x32_bf16 v[68:71], v[148:151], v[214:217], v[68:71]
	s_setprio 3
	s_barrier
; #define PG8_STAGE(bufoff, gbase, voff) do { _Pragma("unroll") for (int _i = 0; _i < 2; ++_i) \
;         __builtin_amdgcn_global_load_lds((const unsigned*)((const char*)(gbase) + (voff)[_i]), (PG8_LAS unsigned*)(lds + (bufoff) + ldsw + _i * 8192), 16, 0, 0); } while (0)
; #define PG8_LDA(dst, b, h) do { _Pragma("unroll") for (int m = 0; m < 4; ++m) _Pragma("unroll") for (int k = 0; k < 2; ++k) dst[m][k] = *(const PG8_LAS bf16x8*)(lds + PG8_SA(b, h) + aoff + m * 2048 + k * 1024); } while (0)
; #define PG8_LDB(dst, b, h) do { _Pragma("unroll") for (int n = 0; n < 2; ++n) _Pragma("unroll") for (int k = 0; k < 2; ++k) dst[n][k] = *(const PG8_LAS bf16x8*)(lds + PG8_SB(b, h) + boff + n * 2048 + k * 1024); } while (0)
; #define PG8_MMA(ai, bj, At, Bt) do { __builtin_amdgcn_s_setprio(1); _Pragma("unroll") for (int m = 0; m < 4; ++m) _Pragma("unroll") for (int n = 0; n < 2; ++n) _Pragma("unroll") for (int k = 0; k < 2; ++k) \
;         acc[ai][bj][m][n] = __builtin_amdgcn_mfma_f32_16x16x32_bf16(Bt[n][k], At[m][k], acc[ai][bj][m][n], 0, 0, 0); __builtin_amdgcn_s_setprio(0); } while (0)
; template <class Epi, class Sched, bool ALIGN_EPI = false, bool SP2 = false>
; __device__ __forceinline__ void gemm_phase(PG8_LAS unsigned char* lds, const Gemm g, const Sched& S, const Epi& E) {
;     ...
;             PG8_LDB(B0, 0, 0); PG8_LDB(B1, 0, 1); PG8_SCHED; PG8_LDA(At, 0, 0); PG8_STAGE(PG8_SA(1, 1), a1 + hstep, voffA);
;             PG8_WAIT_V(8); PG8_WAIT_L(0); PG8_BAR; PG8_MMA(0, 0, At, B0); PG8_MMA(0, 1, At, B1); PG8_BAR; PG8_SCHED;
;             PG8_LDA(At, 0, 1); PG8_STAGE(PG8_SB(0, 0), b2, voffB); PG8_STAGE(PG8_SB(0, 1), b2 + hstep, voffB); PG8_STAGE(PG8_SA(0, 0), a2, voffA);
;             PG8_WAIT_V(8); PG8_WAIT_L(0); PG8_BAR; PG8_MMA(1, 0, At, B0); PG8_MMA(1, 1, At, B1); PG8_BAR; PG8_SCHED;
;             PG8_LDB(B0, 1, 0); PG8_LDB(B1, 1, 1); PG8_SCHED; PG8_LDA(At, 1, 0); PG8_STAGE(PG8_SA(0, 1), a2 + hstep, voffA);
;             PG8_WAIT_V(8); PG8_WAIT_L(0); PG8_BAR; PG8_MMA(0, 0, At, B0); PG8_MMA(0, 1, At, B1); PG8_BAR; PG8_SCHED;
;             PG8_LDA(At, 1, 1); PG8_STAGE(PG8_SB(1, 0), b3, voffB); PG8_STAGE(PG8_SB(1, 1), b3 + hstep, voffB); PG8_STAGE(PG8_SA(1, 0), a3, voffA);
;             PG8_WAIT_V(8); PG8_WAIT_L(0); PG8_BAR; PG8_MMA(1, 0, At, B0); PG8_MMA(1, 1, At, B1); PG8_BAR; PG8_SCHED;
;     ...
;         if constexpr (ALIGN_EPI) { if (wr == 0) PG8_BAR; }
	v_mfma_f32_16x16x32_bf16 v[64:67], v[156:159], v[214:217], v[64:67]
	s_setprio 0
	s_add_i32 s40, s63, s42
	v_lshl_add_u64 v[218:219], v[218:219], 0, s[12:13]
	s_mov_b32 m0, s40
	ds_read_b128 v[178:181], v204 offset:49152
	ds_read_b128 v[182:185], v204 offset:50176
	ds_read_b128 v[186:189], v204 offset:51200
	ds_read_b128 v[190:193], v204 offset:52224
	ds_read_b128 v[194:197], v204 offset:53248
	ds_read_b128 v[206:209], v204 offset:54272
	ds_read_b128 v[210:213], v204 offset:55296
	ds_read_b128 v[214:217], v204 offset:56320
	global_load_lds_dwordx4 v[218:219], off
	s_add_i32 m0, s40, 0x2000
	s_add_u32 s6, s6, 0x40080
	v_lshl_add_u64 v[218:219], v[220:221], 0, s[12:13]
	s_addc_u32 s7, s7, 0
	s_add_i32 s40, s64, s42
	global_load_lds_dwordx4 v[218:219], off
	v_lshl_add_u64 v[218:219], s[6:7], 0, v[162:163]
	s_mov_b32 m0, s40
	s_nop 0
	global_load_lds_dwordx4 v[218:219], off
	v_lshl_add_u64 v[218:219], s[6:7], 0, v[166:167]
	s_add_i32 m0, s40, 0x2000
	s_nop 0
	global_load_lds_dwordx4 v[218:219], off
	v_lshl_add_u64 v[218:219], v[222:223], 0, s[12:13]
	s_mov_b32 m0, s52
	s_nop 0
	global_load_lds_dwordx4 v[218:219], off
	v_lshl_add_u64 v[218:219], v[224:225], 0, s[12:13]
	s_mov_b32 m0, s53
	s_nop 0
	global_load_lds_dwordx4 v[218:219], off
	s_waitcnt vmcnt(8)
	s_waitcnt lgkmcnt(0)
	s_barrier
	s_setprio 1
	s_waitcnt lgkmcnt(0)
	v_mfma_f32_16x16x32_bf16 v[60:63], v[128:131], v[178:181], v[60:63]
	v_mfma_f32_16x16x32_bf16 v[56:59], v[136:139], v[178:181], v[56:59]
	v_mfma_f32_16x16x32_bf16 v[44:47], v[128:131], v[186:189], v[44:47]
	v_mfma_f32_16x16x32_bf16 v[40:43], v[136:139], v[186:189], v[40:43]
	v_mfma_f32_16x16x32_bf16 v[28:31], v[128:131], v[194:197], v[28:31]
	v_mfma_f32_16x16x32_bf16 v[24:27], v[136:139], v[194:197], v[24:27]
	v_mfma_f32_16x16x32_bf16 v[12:15], v[128:131], v[210:213], v[12:15]
	v_mfma_f32_16x16x32_bf16 v[8:11], v[136:139], v[210:213], v[8:11]
	v_mfma_f32_16x16x32_bf16 v[60:63], v[132:135], v[182:185], v[60:63]
	v_mfma_f32_16x16x32_bf16 v[56:59], v[140:143], v[182:185], v[56:59]
	v_mfma_f32_16x16x32_bf16 v[44:47], v[132:135], v[190:193], v[44:47]
	v_mfma_f32_16x16x32_bf16 v[40:43], v[140:143], v[190:193], v[40:43]
	v_mfma_f32_16x16x32_bf16 v[28:31], v[132:135], v[206:209], v[28:31]
	v_mfma_f32_16x16x32_bf16 v[24:27], v[140:143], v[206:209], v[24:27]
	v_mfma_f32_16x16x32_bf16 v[12:15], v[132:135], v[214:217], v[12:15]
	v_mfma_f32_16x16x32_bf16 v[8:11], v[140:143], v[214:217], v[8:11]
	s_setprio 0
	s_setprio 1
	v_mfma_f32_16x16x32_bf16 v[52:55], v[144:147], v[178:181], v[52:55]
	v_mfma_f32_16x16x32_bf16 v[48:51], v[152:155], v[178:181], v[48:51]
	v_mfma_f32_16x16x32_bf16 v[36:39], v[144:147], v[186:189], v[36:39]
	v_mfma_f32_16x16x32_bf16 v[32:35], v[152:155], v[186:189], v[32:35]
	v_mfma_f32_16x16x32_bf16 v[20:23], v[144:147], v[194:197], v[20:23]
	v_mfma_f32_16x16x32_bf16 v[16:19], v[152:155], v[194:197], v[16:19]
	v_mfma_f32_16x16x32_bf16 v[4:7], v[144:147], v[210:213], v[4:7]
	v_mfma_f32_16x16x32_bf16 v[0:3], v[152:155], v[210:213], v[0:3]
	v_mfma_f32_16x16x32_bf16 v[52:55], v[148:151], v[182:185], v[52:55]
	v_mfma_f32_16x16x32_bf16 v[48:51], v[156:159], v[182:185], v[48:51]
	v_mfma_f32_16x16x32_bf16 v[36:39], v[148:151], v[190:193], v[36:39]
	v_mfma_f32_16x16x32_bf16 v[32:35], v[156:159], v[190:193], v[32:35]
	v_mfma_f32_16x16x32_bf16 v[20:23], v[148:151], v[206:209], v[20:23]
	v_mfma_f32_16x16x32_bf16 v[16:19], v[156:159], v[206:209], v[16:19]
	v_mfma_f32_16x16x32_bf16 v[4:7], v[148:151], v[214:217], v[4:7]
	s_setprio 3
	s_barrier
	v_mfma_f32_16x16x32_bf16 v[0:3], v[156:159], v[214:217], v[0:3]
	s_setprio 0
	s_add_i32 s62, s62, 2
	s_add_u32 s4, s4, 0x100
	s_addc_u32 s5, s5, 0
	s_add_u32 s60, s60, 0x100
	s_addc_u32 s61, s61, 0
	s_cmp_gt_u32 s62, 13
	s_cbranch_scc0 .LBB0_1033
	s_and_b64 vcc, exec, s[14:15]
	s_cbranch_vccz .LBB0_1036
	s_barrier
